# GEMM K-loops: removed the 16 per-segment s_setprio flips per iteration (all waves stay prio 0); keeps mid_opt LDS bank-conflict fix
# speedup vs baseline: 1.0047x; 1.0047x over previous
.LBB0_176:
	s_ashr_i32 s19, s18, 31
	s_lshl_b64 s[20:21], s[18:19], 21
	s_add_u32 s20, s54, s20
	s_addc_u32 s21, s55, s21
	s_and_b64 s[22:23], s[0:1], exec
	s_cselect_b32 s19, s21, s27
	s_cselect_b32 s58, s20, s26
	s_ashr_i32 s17, s16, 31
	s_lshl_b64 s[22:23], s[16:17], 21
	s_add_u32 s22, s35, s22
	s_addc_u32 s23, s39, s23
	s_and_b64 s[30:31], s[0:1], exec
	s_cselect_b32 s17, s23, s29
	s_cselect_b32 s59, s22, s28
	s_add_u32 s26, s26, 0x100080
	s_addc_u32 s27, s27, 0
	s_add_u32 s62, s28, 0x100
	v_mov_b32_e32 v2, 0
	s_addc_u32 s63, s29, 0
	s_mov_b32 s80, -2
	v_mov_b32_e32 v3, v2
	v_mov_b32_e32 v4, v2
	v_mov_b32_e32 v5, v2
	v_mov_b32_e32 v6, v2
	v_mov_b32_e32 v7, v2
	v_mov_b32_e32 v8, v2
	v_mov_b32_e32 v9, v2
	v_mov_b32_e32 v10, v2
	v_mov_b32_e32 v11, v2
	v_mov_b32_e32 v12, v2
	v_mov_b32_e32 v13, v2
	v_mov_b32_e32 v18, v2
	v_mov_b32_e32 v19, v2
	v_mov_b32_e32 v20, v2
	v_mov_b32_e32 v21, v2
	v_mov_b32_e32 v26, v2
	v_mov_b32_e32 v27, v2
	v_mov_b32_e32 v28, v2
	v_mov_b32_e32 v29, v2
	v_mov_b32_e32 v34, v2
	v_mov_b32_e32 v35, v2
	v_mov_b32_e32 v36, v2
	v_mov_b32_e32 v37, v2
	v_mov_b32_e32 v42, v2
	v_mov_b32_e32 v43, v2
	v_mov_b32_e32 v44, v2
	v_mov_b32_e32 v45, v2
	v_mov_b32_e32 v50, v2
	v_mov_b32_e32 v51, v2
	v_mov_b32_e32 v52, v2
	v_mov_b32_e32 v53, v2
	v_mov_b32_e32 v14, v2
	v_mov_b32_e32 v15, v2
	v_mov_b32_e32 v16, v2
	v_mov_b32_e32 v17, v2
	v_mov_b32_e32 v22, v2
	v_mov_b32_e32 v23, v2
	v_mov_b32_e32 v24, v2
	v_mov_b32_e32 v25, v2
	v_mov_b32_e32 v30, v2
	v_mov_b32_e32 v31, v2
	v_mov_b32_e32 v32, v2
	v_mov_b32_e32 v33, v2
	v_mov_b32_e32 v38, v2
	v_mov_b32_e32 v39, v2
	v_mov_b32_e32 v40, v2
	v_mov_b32_e32 v41, v2
	v_mov_b32_e32 v46, v2
	v_mov_b32_e32 v47, v2
	v_mov_b32_e32 v48, v2
	v_mov_b32_e32 v49, v2
	v_mov_b32_e32 v54, v2
	v_mov_b32_e32 v55, v2
	v_mov_b32_e32 v56, v2
	v_mov_b32_e32 v57, v2
	v_mov_b32_e32 v58, v2
	v_mov_b32_e32 v59, v2
	v_mov_b32_e32 v60, v2
	v_mov_b32_e32 v61, v2
	v_mov_b32_e32 v62, v2
	v_mov_b32_e32 v63, v2
	v_mov_b32_e32 v64, v2
	v_mov_b32_e32 v65, v2
	v_mov_b32_e32 v66, v2
	v_mov_b32_e32 v67, v2
	v_mov_b32_e32 v68, v2
	v_mov_b32_e32 v69, v2
	v_mov_b32_e32 v70, v2
	v_mov_b32_e32 v71, v2
	v_mov_b32_e32 v72, v2
	v_mov_b32_e32 v73, v2
	v_mov_b32_e32 v74, v2
	v_mov_b32_e32 v75, v2
	v_mov_b32_e32 v76, v2
	v_mov_b32_e32 v77, v2
	v_mov_b32_e32 v82, v2
	v_mov_b32_e32 v83, v2
	v_mov_b32_e32 v84, v2
	v_mov_b32_e32 v85, v2
	v_mov_b32_e32 v90, v2
	v_mov_b32_e32 v91, v2
	v_mov_b32_e32 v92, v2
	v_mov_b32_e32 v93, v2
	v_mov_b32_e32 v98, v2
	v_mov_b32_e32 v99, v2
	v_mov_b32_e32 v100, v2
	v_mov_b32_e32 v101, v2
	v_mov_b32_e32 v106, v2
	v_mov_b32_e32 v107, v2
	v_mov_b32_e32 v108, v2
	v_mov_b32_e32 v109, v2
	v_mov_b32_e32 v114, v2
	v_mov_b32_e32 v115, v2
	v_mov_b32_e32 v116, v2
	v_mov_b32_e32 v117, v2
	v_mov_b32_e32 v78, v2
	v_mov_b32_e32 v79, v2
	v_mov_b32_e32 v80, v2
	v_mov_b32_e32 v81, v2
	v_mov_b32_e32 v86, v2
	v_mov_b32_e32 v87, v2
	v_mov_b32_e32 v88, v2
	v_mov_b32_e32 v89, v2
	v_mov_b32_e32 v94, v2
	v_mov_b32_e32 v95, v2
	v_mov_b32_e32 v96, v2
	v_mov_b32_e32 v97, v2
	v_mov_b32_e32 v102, v2
	v_mov_b32_e32 v103, v2
	v_mov_b32_e32 v104, v2
	v_mov_b32_e32 v105, v2
	v_mov_b32_e32 v110, v2
	v_mov_b32_e32 v111, v2
	v_mov_b32_e32 v112, v2
	v_mov_b32_e32 v113, v2
	v_mov_b32_e32 v118, v2
	v_mov_b32_e32 v119, v2
	v_mov_b32_e32 v120, v2
	v_mov_b32_e32 v121, v2
	v_mov_b32_e32 v122, v2
	v_mov_b32_e32 v123, v2
	v_mov_b32_e32 v124, v2
	v_mov_b32_e32 v125, v2
	v_mov_b32_e32 v126, v2
	v_mov_b32_e32 v127, v2
	v_mov_b32_e32 v128, v2
	v_mov_b32_e32 v129, v2
	s_setprio 0
.LBB0_177:
	ds_read_b128 v[164:167], v153
	ds_read_b128 v[168:171], v153 offset:1024
	ds_read_b128 v[172:175], v153 offset:2048
	ds_read_b128 v[176:179], v153 offset:3072
	ds_read_b128 v[184:187], v160
	ds_read_b128 v[188:191], v160 offset:1024
	ds_read_b128 v[192:195], v160 offset:2048
	ds_read_b128 v[196:199], v160 offset:3072
	s_add_u32 s28, s26, 0xfff00080
	s_addc_u32 s29, s27, -1
	s_cmp_eq_u32 s80, 60
	s_cselect_b32 s31, s19, s29
	s_cselect_b32 s30, s58, s28
	s_cselect_b32 s29, s17, s63
	s_cselect_b32 s28, s59, s62
	v_lshl_add_u64 v[148:149], s[26:27], 0, v[140:141]
	s_add_i32 m0, s25, 0xc000
	ds_read_b128 v[200:203], v161
	ds_read_b128 v[204:207], v161 offset:1024
	ds_read_b128 v[208:211], v161 offset:2048
	ds_read_b128 v[212:215], v161 offset:3072
	ds_read_b128 v[216:219], v161 offset:4096
	ds_read_b128 v[220:223], v161 offset:5120
	ds_read_b128 v[224:227], v161 offset:6144
	ds_read_b128 v[228:231], v161 offset:7168
	global_load_lds_dwordx4 v[148:149], off
	v_lshl_add_u64 v[148:149], s[26:27], 0, v[142:143]
	s_add_i32 m0, s25, 0xe000
	s_nop 0
	global_load_lds_dwordx4 v[148:149], off
	s_waitcnt vmcnt(8)
	s_waitcnt lgkmcnt(0)
	s_barrier
	s_waitcnt lgkmcnt(0)
	v_mfma_f32_16x16x32_bf16 v[126:129], v[164:167], v[200:203], v[126:129]
	v_mfma_f32_16x16x32_bf16 v[122:125], v[172:175], v[200:203], v[122:125]
	v_mfma_f32_16x16x32_bf16 v[118:121], v[164:167], v[208:211], v[118:121]
	v_mfma_f32_16x16x32_bf16 v[110:113], v[172:175], v[208:211], v[110:113]
	v_mfma_f32_16x16x32_bf16 v[102:105], v[164:167], v[216:219], v[102:105]
	v_mfma_f32_16x16x32_bf16 v[94:97], v[172:175], v[216:219], v[94:97]
	v_mfma_f32_16x16x32_bf16 v[86:89], v[164:167], v[224:227], v[86:89]
	v_mfma_f32_16x16x32_bf16 v[78:81], v[172:175], v[224:227], v[78:81]
	v_mfma_f32_16x16x32_bf16 v[126:129], v[168:171], v[204:207], v[126:129]
	v_mfma_f32_16x16x32_bf16 v[122:125], v[176:179], v[204:207], v[122:125]
	v_mfma_f32_16x16x32_bf16 v[118:121], v[168:171], v[212:215], v[118:121]
	v_mfma_f32_16x16x32_bf16 v[110:113], v[176:179], v[212:215], v[110:113]
	v_mfma_f32_16x16x32_bf16 v[102:105], v[168:171], v[220:223], v[102:105]
	v_mfma_f32_16x16x32_bf16 v[94:97], v[176:179], v[220:223], v[94:97]
	v_mfma_f32_16x16x32_bf16 v[86:89], v[168:171], v[228:231], v[86:89]
	v_mfma_f32_16x16x32_bf16 v[78:81], v[176:179], v[228:231], v[78:81]
	v_mfma_f32_16x16x32_bf16 v[114:117], v[184:187], v[200:203], v[114:117]
	v_mfma_f32_16x16x32_bf16 v[106:109], v[192:195], v[200:203], v[106:109]
	v_mfma_f32_16x16x32_bf16 v[98:101], v[184:187], v[208:211], v[98:101]
	v_mfma_f32_16x16x32_bf16 v[90:93], v[192:195], v[208:211], v[90:93]
	v_mfma_f32_16x16x32_bf16 v[82:85], v[184:187], v[216:219], v[82:85]
	v_mfma_f32_16x16x32_bf16 v[74:77], v[192:195], v[216:219], v[74:77]
	v_mfma_f32_16x16x32_bf16 v[70:73], v[184:187], v[224:227], v[70:73]
	v_mfma_f32_16x16x32_bf16 v[66:69], v[192:195], v[224:227], v[66:69]
	v_mfma_f32_16x16x32_bf16 v[114:117], v[188:191], v[204:207], v[114:117]
	v_mfma_f32_16x16x32_bf16 v[106:109], v[196:199], v[204:207], v[106:109]
	v_mfma_f32_16x16x32_bf16 v[98:101], v[188:191], v[212:215], v[98:101]
	v_mfma_f32_16x16x32_bf16 v[90:93], v[196:199], v[212:215], v[90:93]
	v_mfma_f32_16x16x32_bf16 v[82:85], v[188:191], v[220:223], v[82:85]
	v_mfma_f32_16x16x32_bf16 v[74:77], v[196:199], v[220:223], v[74:77]
	v_mfma_f32_16x16x32_bf16 v[70:73], v[188:191], v[228:231], v[70:73]
	v_mfma_f32_16x16x32_bf16 v[66:69], v[196:199], v[228:231], v[66:69]
	s_barrier
	s_add_i32 s81, s51, s34
	v_lshl_add_u64 v[148:149], s[28:29], 0, v[132:133]
	s_mov_b32 m0, s81
	ds_read_b128 v[200:203], v161 offset:16384
	ds_read_b128 v[204:207], v161 offset:17408
	ds_read_b128 v[208:211], v161 offset:18432
	ds_read_b128 v[212:215], v161 offset:19456
	ds_read_b128 v[216:219], v161 offset:20480
	ds_read_b128 v[220:223], v161 offset:21504
	ds_read_b128 v[224:227], v161 offset:22528
	ds_read_b128 v[228:231], v161 offset:23552
	global_load_lds_dwordx4 v[148:149], off
	s_add_i32 m0, s81, 0x2000
	s_add_u32 s82, s28, 0x100000
	v_lshl_add_u64 v[180:181], s[28:29], 0, v[136:137]
	s_addc_u32 s83, s29, 0
	s_add_i32 s81, s52, s34
	global_load_lds_dwordx4 v[180:181], off
	v_lshl_add_u64 v[232:233], s[82:83], 0, v[132:133]
	s_mov_b32 m0, s81
	v_lshl_add_u64 v[234:235], s[30:31], 0, v[134:135]
	global_load_lds_dwordx4 v[232:233], off
	v_lshl_add_u64 v[232:233], s[82:83], 0, v[136:137]
	s_add_i32 m0, s81, 0x2000
	s_nop 0
	global_load_lds_dwordx4 v[232:233], off
	v_lshl_add_u64 v[232:233], s[30:31], 0, v[130:131]
	s_mov_b32 m0, s25
	s_nop 0
	global_load_lds_dwordx4 v[232:233], off
	s_mov_b32 m0, s43
	s_nop 0
	global_load_lds_dwordx4 v[234:235], off
	s_waitcnt vmcnt(8)
	s_waitcnt lgkmcnt(0)
	s_barrier
	s_waitcnt lgkmcnt(0)
	v_mfma_f32_16x16x32_bf16 v[62:65], v[164:167], v[200:203], v[62:65]
	v_mfma_f32_16x16x32_bf16 v[58:61], v[172:175], v[200:203], v[58:61]
	v_mfma_f32_16x16x32_bf16 v[54:57], v[164:167], v[208:211], v[54:57]
	v_mfma_f32_16x16x32_bf16 v[46:49], v[172:175], v[208:211], v[46:49]
	v_mfma_f32_16x16x32_bf16 v[38:41], v[164:167], v[216:219], v[38:41]
	v_mfma_f32_16x16x32_bf16 v[30:33], v[172:175], v[216:219], v[30:33]
	v_mfma_f32_16x16x32_bf16 v[22:25], v[164:167], v[224:227], v[22:25]
	v_mfma_f32_16x16x32_bf16 v[14:17], v[172:175], v[224:227], v[14:17]
	v_mfma_f32_16x16x32_bf16 v[62:65], v[168:171], v[204:207], v[62:65]
	v_mfma_f32_16x16x32_bf16 v[58:61], v[176:179], v[204:207], v[58:61]
	v_mfma_f32_16x16x32_bf16 v[54:57], v[168:171], v[212:215], v[54:57]
	v_mfma_f32_16x16x32_bf16 v[46:49], v[176:179], v[212:215], v[46:49]
	v_mfma_f32_16x16x32_bf16 v[38:41], v[168:171], v[220:223], v[38:41]
	v_mfma_f32_16x16x32_bf16 v[30:33], v[176:179], v[220:223], v[30:33]
	v_mfma_f32_16x16x32_bf16 v[22:25], v[168:171], v[228:231], v[22:25]
	v_mfma_f32_16x16x32_bf16 v[14:17], v[176:179], v[228:231], v[14:17]
	v_mfma_f32_16x16x32_bf16 v[50:53], v[184:187], v[200:203], v[50:53]
	v_mfma_f32_16x16x32_bf16 v[42:45], v[192:195], v[200:203], v[42:45]
	v_mfma_f32_16x16x32_bf16 v[34:37], v[184:187], v[208:211], v[34:37]
	v_mfma_f32_16x16x32_bf16 v[26:29], v[192:195], v[208:211], v[26:29]
	v_mfma_f32_16x16x32_bf16 v[18:21], v[184:187], v[216:219], v[18:21]
	v_mfma_f32_16x16x32_bf16 v[10:13], v[192:195], v[216:219], v[10:13]
	v_mfma_f32_16x16x32_bf16 v[6:9], v[184:187], v[224:227], v[6:9]
	v_mfma_f32_16x16x32_bf16 v[2:5], v[192:195], v[224:227], v[2:5]
	v_mfma_f32_16x16x32_bf16 v[50:53], v[188:191], v[204:207], v[50:53]
	v_mfma_f32_16x16x32_bf16 v[42:45], v[196:199], v[204:207], v[42:45]
	v_mfma_f32_16x16x32_bf16 v[34:37], v[188:191], v[212:215], v[34:37]
	v_mfma_f32_16x16x32_bf16 v[26:29], v[196:199], v[212:215], v[26:29]
	v_mfma_f32_16x16x32_bf16 v[18:21], v[188:191], v[220:223], v[18:21]
	v_mfma_f32_16x16x32_bf16 v[10:13], v[196:199], v[220:223], v[10:13]
	v_mfma_f32_16x16x32_bf16 v[6:9], v[188:191], v[228:231], v[6:9]
	v_mfma_f32_16x16x32_bf16 v[2:5], v[196:199], v[228:231], v[2:5]
	s_barrier
	s_add_i32 s81, 0, 0x18000
	v_add_u32_e32 v162, s81, v151
	s_add_i32 s82, 0, 0x1c000
	ds_read_b128 v[164:167], v162
	ds_read_b128 v[168:171], v162 offset:1024
	ds_read_b128 v[172:175], v162 offset:2048
	ds_read_b128 v[176:179], v162 offset:3072
	v_add_u32_e32 v162, s82, v151
	ds_read_b128 v[184:187], v162
	ds_read_b128 v[188:191], v162 offset:1024
	ds_read_b128 v[192:195], v162 offset:2048
	ds_read_b128 v[196:199], v162 offset:3072
	s_add_u32 s30, s30, 0x100000
	s_addc_u32 s31, s31, 0
	s_mov_b32 m0, s44
	v_lshl_add_u64 v[236:237], s[30:31], 0, v[130:131]
	ds_read_b128 v[200:203], v161 offset:32768
	ds_read_b128 v[204:207], v161 offset:33792
	ds_read_b128 v[208:211], v161 offset:34816
	ds_read_b128 v[212:215], v161 offset:35840
	ds_read_b128 v[216:219], v161 offset:36864
	ds_read_b128 v[220:223], v161 offset:37888
	ds_read_b128 v[224:227], v161 offset:38912
	ds_read_b128 v[228:231], v161 offset:39936
	global_load_lds_dwordx4 v[236:237], off
	v_lshl_add_u64 v[236:237], s[30:31], 0, v[134:135]
	s_mov_b32 m0, s45
	s_nop 0
	global_load_lds_dwordx4 v[236:237], off
	s_waitcnt vmcnt(8)
	s_waitcnt lgkmcnt(0)
	s_barrier
	s_waitcnt lgkmcnt(0)
	v_mfma_f32_16x16x32_bf16 v[126:129], v[164:167], v[200:203], v[126:129]
	v_mfma_f32_16x16x32_bf16 v[122:125], v[172:175], v[200:203], v[122:125]
	v_mfma_f32_16x16x32_bf16 v[118:121], v[164:167], v[208:211], v[118:121]
	v_mfma_f32_16x16x32_bf16 v[110:113], v[172:175], v[208:211], v[110:113]
	v_mfma_f32_16x16x32_bf16 v[102:105], v[164:167], v[216:219], v[102:105]
	v_mfma_f32_16x16x32_bf16 v[94:97], v[172:175], v[216:219], v[94:97]
	v_mfma_f32_16x16x32_bf16 v[86:89], v[164:167], v[224:227], v[86:89]
	v_mfma_f32_16x16x32_bf16 v[78:81], v[172:175], v[224:227], v[78:81]
	v_mfma_f32_16x16x32_bf16 v[126:129], v[168:171], v[204:207], v[126:129]
	v_mfma_f32_16x16x32_bf16 v[122:125], v[176:179], v[204:207], v[122:125]
	v_mfma_f32_16x16x32_bf16 v[118:121], v[168:171], v[212:215], v[118:121]
	v_mfma_f32_16x16x32_bf16 v[110:113], v[176:179], v[212:215], v[110:113]
	v_mfma_f32_16x16x32_bf16 v[102:105], v[168:171], v[220:223], v[102:105]
	v_mfma_f32_16x16x32_bf16 v[94:97], v[176:179], v[220:223], v[94:97]
	v_mfma_f32_16x16x32_bf16 v[86:89], v[168:171], v[228:231], v[86:89]
	v_mfma_f32_16x16x32_bf16 v[78:81], v[176:179], v[228:231], v[78:81]
	v_mfma_f32_16x16x32_bf16 v[114:117], v[184:187], v[200:203], v[114:117]
	v_mfma_f32_16x16x32_bf16 v[106:109], v[192:195], v[200:203], v[106:109]
	v_mfma_f32_16x16x32_bf16 v[98:101], v[184:187], v[208:211], v[98:101]
	v_mfma_f32_16x16x32_bf16 v[90:93], v[192:195], v[208:211], v[90:93]
	v_mfma_f32_16x16x32_bf16 v[82:85], v[184:187], v[216:219], v[82:85]
	v_mfma_f32_16x16x32_bf16 v[74:77], v[192:195], v[216:219], v[74:77]
	v_mfma_f32_16x16x32_bf16 v[70:73], v[184:187], v[224:227], v[70:73]
	v_mfma_f32_16x16x32_bf16 v[66:69], v[192:195], v[224:227], v[66:69]
	v_mfma_f32_16x16x32_bf16 v[114:117], v[188:191], v[204:207], v[114:117]
	v_mfma_f32_16x16x32_bf16 v[106:109], v[196:199], v[204:207], v[106:109]
	v_mfma_f32_16x16x32_bf16 v[98:101], v[188:191], v[212:215], v[98:101]
	v_mfma_f32_16x16x32_bf16 v[90:93], v[196:199], v[212:215], v[90:93]
	v_mfma_f32_16x16x32_bf16 v[82:85], v[188:191], v[220:223], v[82:85]
	v_mfma_f32_16x16x32_bf16 v[74:77], v[196:199], v[220:223], v[74:77]
	v_mfma_f32_16x16x32_bf16 v[70:73], v[188:191], v[228:231], v[70:73]
	v_mfma_f32_16x16x32_bf16 v[66:69], v[196:199], v[228:231], v[66:69]
	s_barrier
	s_add_i32 s30, s81, s34
	v_lshl_add_u64 v[148:149], v[148:149], 0, s[12:13]
	s_mov_b32 m0, s30
	ds_read_b128 v[200:203], v161 offset:49152
	ds_read_b128 v[204:207], v161 offset:50176
	ds_read_b128 v[208:211], v161 offset:51200
	ds_read_b128 v[212:215], v161 offset:52224
	ds_read_b128 v[216:219], v161 offset:53248
	ds_read_b128 v[220:223], v161 offset:54272
	ds_read_b128 v[224:227], v161 offset:55296
	ds_read_b128 v[228:231], v161 offset:56320
	global_load_lds_dwordx4 v[148:149], off
	s_add_i32 m0, s30, 0x2000
	s_add_u32 s28, s28, 0x100080
	v_lshl_add_u64 v[148:149], v[180:181], 0, s[12:13]
	s_addc_u32 s29, s29, 0
	s_add_i32 s30, s82, s34
	global_load_lds_dwordx4 v[148:149], off
	v_lshl_add_u64 v[148:149], s[28:29], 0, v[132:133]
	s_mov_b32 m0, s30
	s_nop 0
	global_load_lds_dwordx4 v[148:149], off
	v_lshl_add_u64 v[148:149], s[28:29], 0, v[136:137]
	s_add_i32 m0, s30, 0x2000
	s_nop 0
	global_load_lds_dwordx4 v[148:149], off
	v_lshl_add_u64 v[148:149], v[232:233], 0, s[12:13]
	s_mov_b32 m0, s46
	s_nop 0
	global_load_lds_dwordx4 v[148:149], off
	v_lshl_add_u64 v[148:149], v[234:235], 0, s[12:13]
	s_mov_b32 m0, s47
	s_nop 0
	global_load_lds_dwordx4 v[148:149], off
	s_waitcnt vmcnt(8)
	s_waitcnt lgkmcnt(0)
	s_barrier
	s_waitcnt lgkmcnt(0)
	v_mfma_f32_16x16x32_bf16 v[62:65], v[164:167], v[200:203], v[62:65]
	v_mfma_f32_16x16x32_bf16 v[58:61], v[172:175], v[200:203], v[58:61]
	v_mfma_f32_16x16x32_bf16 v[54:57], v[164:167], v[208:211], v[54:57]
	v_mfma_f32_16x16x32_bf16 v[46:49], v[172:175], v[208:211], v[46:49]
	v_mfma_f32_16x16x32_bf16 v[38:41], v[164:167], v[216:219], v[38:41]
	v_mfma_f32_16x16x32_bf16 v[30:33], v[172:175], v[216:219], v[30:33]
	v_mfma_f32_16x16x32_bf16 v[22:25], v[164:167], v[224:227], v[22:25]
	v_mfma_f32_16x16x32_bf16 v[14:17], v[172:175], v[224:227], v[14:17]
	v_mfma_f32_16x16x32_bf16 v[62:65], v[168:171], v[204:207], v[62:65]
	v_mfma_f32_16x16x32_bf16 v[58:61], v[176:179], v[204:207], v[58:61]
	v_mfma_f32_16x16x32_bf16 v[54:57], v[168:171], v[212:215], v[54:57]
	v_mfma_f32_16x16x32_bf16 v[46:49], v[176:179], v[212:215], v[46:49]
	v_mfma_f32_16x16x32_bf16 v[38:41], v[168:171], v[220:223], v[38:41]
	v_mfma_f32_16x16x32_bf16 v[30:33], v[176:179], v[220:223], v[30:33]
	v_mfma_f32_16x16x32_bf16 v[22:25], v[168:171], v[228:231], v[22:25]
	v_mfma_f32_16x16x32_bf16 v[14:17], v[176:179], v[228:231], v[14:17]
	v_mfma_f32_16x16x32_bf16 v[50:53], v[184:187], v[200:203], v[50:53]
	v_mfma_f32_16x16x32_bf16 v[42:45], v[192:195], v[200:203], v[42:45]
	v_mfma_f32_16x16x32_bf16 v[34:37], v[184:187], v[208:211], v[34:37]
	v_mfma_f32_16x16x32_bf16 v[26:29], v[192:195], v[208:211], v[26:29]
	v_mfma_f32_16x16x32_bf16 v[18:21], v[184:187], v[216:219], v[18:21]
	v_mfma_f32_16x16x32_bf16 v[10:13], v[192:195], v[216:219], v[10:13]
	v_mfma_f32_16x16x32_bf16 v[6:9], v[184:187], v[224:227], v[6:9]
	v_mfma_f32_16x16x32_bf16 v[2:5], v[192:195], v[224:227], v[2:5]
	v_mfma_f32_16x16x32_bf16 v[50:53], v[188:191], v[204:207], v[50:53]
	v_mfma_f32_16x16x32_bf16 v[42:45], v[196:199], v[204:207], v[42:45]
	v_mfma_f32_16x16x32_bf16 v[34:37], v[188:191], v[212:215], v[34:37]
	v_mfma_f32_16x16x32_bf16 v[26:29], v[196:199], v[212:215], v[26:29]
	v_mfma_f32_16x16x32_bf16 v[18:21], v[188:191], v[220:223], v[18:21]
	v_mfma_f32_16x16x32_bf16 v[10:13], v[196:199], v[220:223], v[10:13]
	v_mfma_f32_16x16x32_bf16 v[6:9], v[188:191], v[228:231], v[6:9]
	v_mfma_f32_16x16x32_bf16 v[2:5], v[196:199], v[228:231], v[2:5]
	s_barrier
	s_add_i32 s80, s80, 2
	s_add_u32 s26, s26, 0x100
	s_addc_u32 s27, s27, 0
	s_add_u32 s62, s62, 0x100
	s_addc_u32 s63, s63, 0
	s_cmp_gt_u32 s80, 61
	s_cbranch_scc0 .LBB0_177
	s_and_b64 vcc, exec, s[14:15]
	s_cbranch_vccz .LBB0_180
	s_barrier

.LBB0_196:
	s_ashr_i32 s21, s20, 31
	s_lshl_b64 s[22:23], s[20:21], 21
	s_add_u32 s22, s54, s22
	s_addc_u32 s23, s55, s23
	s_and_b64 s[24:25], s[0:1], exec
	s_cselect_b32 s21, s23, s29
	s_cselect_b32 s63, s22, s28
	s_ashr_i32 s19, s18, 31
	s_lshl_b64 s[24:25], s[18:19], 21
	s_add_u32 s24, s44, s24
	s_addc_u32 s25, s45, s25
	s_and_b64 s[34:35], s[0:1], exec
	s_cselect_b32 s19, s25, s31
	s_cselect_b32 s80, s24, s30
	s_add_u32 s28, s28, 0x100080
	s_addc_u32 s29, s29, 0
	s_add_u32 s81, s30, 0x100
	v_mov_b32_e32 v2, 0
	s_addc_u32 s82, s31, 0
	s_mov_b32 s83, -2
	v_mov_b32_e32 v3, v2
	v_mov_b32_e32 v4, v2
	v_mov_b32_e32 v5, v2
	v_mov_b32_e32 v6, v2
	v_mov_b32_e32 v7, v2
	v_mov_b32_e32 v8, v2
	v_mov_b32_e32 v9, v2
	v_mov_b32_e32 v18, v2
	v_mov_b32_e32 v19, v2
	v_mov_b32_e32 v20, v2
	v_mov_b32_e32 v21, v2
	v_mov_b32_e32 v22, v2
	v_mov_b32_e32 v23, v2
	v_mov_b32_e32 v24, v2
	v_mov_b32_e32 v25, v2
	v_mov_b32_e32 v34, v2
	v_mov_b32_e32 v35, v2
	v_mov_b32_e32 v36, v2
	v_mov_b32_e32 v37, v2
	v_mov_b32_e32 v38, v2
	v_mov_b32_e32 v39, v2
	v_mov_b32_e32 v40, v2
	v_mov_b32_e32 v41, v2
	v_mov_b32_e32 v50, v2
	v_mov_b32_e32 v51, v2
	v_mov_b32_e32 v52, v2
	v_mov_b32_e32 v53, v2
	v_mov_b32_e32 v54, v2
	v_mov_b32_e32 v55, v2
	v_mov_b32_e32 v56, v2
	v_mov_b32_e32 v57, v2
	v_mov_b32_e32 v10, v2
	v_mov_b32_e32 v11, v2
	v_mov_b32_e32 v12, v2
	v_mov_b32_e32 v13, v2
	v_mov_b32_e32 v14, v2
	v_mov_b32_e32 v15, v2
	v_mov_b32_e32 v16, v2
	v_mov_b32_e32 v17, v2
	v_mov_b32_e32 v26, v2
	v_mov_b32_e32 v27, v2
	v_mov_b32_e32 v28, v2
	v_mov_b32_e32 v29, v2
	v_mov_b32_e32 v30, v2
	v_mov_b32_e32 v31, v2
	v_mov_b32_e32 v32, v2
	v_mov_b32_e32 v33, v2
	v_mov_b32_e32 v42, v2
	v_mov_b32_e32 v43, v2
	v_mov_b32_e32 v44, v2
	v_mov_b32_e32 v45, v2
	v_mov_b32_e32 v46, v2
	v_mov_b32_e32 v47, v2
	v_mov_b32_e32 v48, v2
	v_mov_b32_e32 v49, v2
	v_mov_b32_e32 v58, v2
	v_mov_b32_e32 v59, v2
	v_mov_b32_e32 v60, v2
	v_mov_b32_e32 v61, v2
	v_mov_b32_e32 v62, v2
	v_mov_b32_e32 v63, v2
	v_mov_b32_e32 v64, v2
	v_mov_b32_e32 v65, v2
	v_mov_b32_e32 v66, v2
	v_mov_b32_e32 v67, v2
	v_mov_b32_e32 v68, v2
	v_mov_b32_e32 v69, v2
	v_mov_b32_e32 v70, v2
	v_mov_b32_e32 v71, v2
	v_mov_b32_e32 v72, v2
	v_mov_b32_e32 v73, v2
	v_mov_b32_e32 v82, v2
	v_mov_b32_e32 v83, v2
	v_mov_b32_e32 v84, v2
	v_mov_b32_e32 v85, v2
	v_mov_b32_e32 v86, v2
	v_mov_b32_e32 v87, v2
	v_mov_b32_e32 v88, v2
	v_mov_b32_e32 v89, v2
	v_mov_b32_e32 v98, v2
	v_mov_b32_e32 v99, v2
	v_mov_b32_e32 v100, v2
	v_mov_b32_e32 v101, v2
	v_mov_b32_e32 v102, v2
	v_mov_b32_e32 v103, v2
	v_mov_b32_e32 v104, v2
	v_mov_b32_e32 v105, v2
	v_mov_b32_e32 v114, v2
	v_mov_b32_e32 v115, v2
	v_mov_b32_e32 v116, v2
	v_mov_b32_e32 v117, v2
	v_mov_b32_e32 v118, v2
	v_mov_b32_e32 v119, v2
	v_mov_b32_e32 v120, v2
	v_mov_b32_e32 v121, v2
	v_mov_b32_e32 v74, v2
	v_mov_b32_e32 v75, v2
	v_mov_b32_e32 v76, v2
	v_mov_b32_e32 v77, v2
	v_mov_b32_e32 v78, v2
	v_mov_b32_e32 v79, v2
	v_mov_b32_e32 v80, v2
	v_mov_b32_e32 v81, v2
	v_mov_b32_e32 v90, v2
	v_mov_b32_e32 v91, v2
	v_mov_b32_e32 v92, v2
	v_mov_b32_e32 v93, v2
	v_mov_b32_e32 v94, v2
	v_mov_b32_e32 v95, v2
	v_mov_b32_e32 v96, v2
	v_mov_b32_e32 v97, v2
	v_mov_b32_e32 v106, v2
	v_mov_b32_e32 v107, v2
	v_mov_b32_e32 v108, v2
	v_mov_b32_e32 v109, v2
	v_mov_b32_e32 v110, v2
	v_mov_b32_e32 v111, v2
	v_mov_b32_e32 v112, v2
	v_mov_b32_e32 v113, v2
	v_mov_b32_e32 v122, v2
	v_mov_b32_e32 v123, v2
	v_mov_b32_e32 v124, v2
	v_mov_b32_e32 v125, v2
	v_mov_b32_e32 v126, v2
	v_mov_b32_e32 v127, v2
	v_mov_b32_e32 v128, v2
	v_mov_b32_e32 v129, v2
	s_setprio 0
.LBB0_197:
	ds_read_b128 v[164:167], v153
	ds_read_b128 v[168:171], v153 offset:1024
	ds_read_b128 v[172:175], v153 offset:2048
	ds_read_b128 v[176:179], v153 offset:3072
	ds_read_b128 v[184:187], v160
	ds_read_b128 v[188:191], v160 offset:1024
	ds_read_b128 v[192:195], v160 offset:2048
	ds_read_b128 v[196:199], v160 offset:3072
	s_add_u32 s30, s28, 0xfff00080
	s_addc_u32 s31, s29, -1
	s_cmp_eq_u32 s83, 60
	s_cselect_b32 s35, s21, s31
	s_cselect_b32 s34, s63, s30
	s_cselect_b32 s31, s19, s82
	s_cselect_b32 s30, s80, s81
	v_lshl_add_u64 v[148:149], s[28:29], 0, v[140:141]
	s_add_i32 m0, s27, 0xc000
	ds_read_b128 v[200:203], v161
	ds_read_b128 v[204:207], v161 offset:1024
	ds_read_b128 v[208:211], v161 offset:2048
	ds_read_b128 v[212:215], v161 offset:3072
	ds_read_b128 v[216:219], v161 offset:4096
	ds_read_b128 v[220:223], v161 offset:5120
	ds_read_b128 v[224:227], v161 offset:6144
	ds_read_b128 v[228:231], v161 offset:7168
	global_load_lds_dwordx4 v[148:149], off
	v_lshl_add_u64 v[148:149], s[28:29], 0, v[142:143]
	s_add_i32 m0, s27, 0xe000
	s_nop 0
	global_load_lds_dwordx4 v[148:149], off
	s_waitcnt vmcnt(8)
	s_waitcnt lgkmcnt(0)
	s_barrier
	s_waitcnt lgkmcnt(0)
	v_mfma_f32_16x16x32_bf16 v[126:129], v[164:167], v[200:203], v[126:129]
	v_mfma_f32_16x16x32_bf16 v[122:125], v[172:175], v[200:203], v[122:125]
	v_mfma_f32_16x16x32_bf16 v[110:113], v[164:167], v[208:211], v[110:113]
	v_mfma_f32_16x16x32_bf16 v[106:109], v[172:175], v[208:211], v[106:109]
	v_mfma_f32_16x16x32_bf16 v[94:97], v[164:167], v[216:219], v[94:97]
	v_mfma_f32_16x16x32_bf16 v[90:93], v[172:175], v[216:219], v[90:93]
	v_mfma_f32_16x16x32_bf16 v[78:81], v[164:167], v[224:227], v[78:81]
	v_mfma_f32_16x16x32_bf16 v[74:77], v[172:175], v[224:227], v[74:77]
	v_mfma_f32_16x16x32_bf16 v[126:129], v[168:171], v[204:207], v[126:129]
	v_mfma_f32_16x16x32_bf16 v[122:125], v[176:179], v[204:207], v[122:125]
	v_mfma_f32_16x16x32_bf16 v[110:113], v[168:171], v[212:215], v[110:113]
	v_mfma_f32_16x16x32_bf16 v[106:109], v[176:179], v[212:215], v[106:109]
	v_mfma_f32_16x16x32_bf16 v[94:97], v[168:171], v[220:223], v[94:97]
	v_mfma_f32_16x16x32_bf16 v[90:93], v[176:179], v[220:223], v[90:93]
	v_mfma_f32_16x16x32_bf16 v[78:81], v[168:171], v[228:231], v[78:81]
	v_mfma_f32_16x16x32_bf16 v[74:77], v[176:179], v[228:231], v[74:77]
	v_mfma_f32_16x16x32_bf16 v[118:121], v[184:187], v[200:203], v[118:121]
	v_mfma_f32_16x16x32_bf16 v[114:117], v[192:195], v[200:203], v[114:117]
	v_mfma_f32_16x16x32_bf16 v[102:105], v[184:187], v[208:211], v[102:105]
	v_mfma_f32_16x16x32_bf16 v[98:101], v[192:195], v[208:211], v[98:101]
	v_mfma_f32_16x16x32_bf16 v[86:89], v[184:187], v[216:219], v[86:89]
	v_mfma_f32_16x16x32_bf16 v[82:85], v[192:195], v[216:219], v[82:85]
	v_mfma_f32_16x16x32_bf16 v[70:73], v[184:187], v[224:227], v[70:73]
	v_mfma_f32_16x16x32_bf16 v[66:69], v[192:195], v[224:227], v[66:69]
	v_mfma_f32_16x16x32_bf16 v[118:121], v[188:191], v[204:207], v[118:121]
	v_mfma_f32_16x16x32_bf16 v[114:117], v[196:199], v[204:207], v[114:117]
	v_mfma_f32_16x16x32_bf16 v[102:105], v[188:191], v[212:215], v[102:105]
	v_mfma_f32_16x16x32_bf16 v[98:101], v[196:199], v[212:215], v[98:101]
	v_mfma_f32_16x16x32_bf16 v[86:89], v[188:191], v[220:223], v[86:89]
	v_mfma_f32_16x16x32_bf16 v[82:85], v[196:199], v[220:223], v[82:85]
	v_mfma_f32_16x16x32_bf16 v[70:73], v[188:191], v[228:231], v[70:73]
	v_mfma_f32_16x16x32_bf16 v[66:69], v[196:199], v[228:231], v[66:69]
	s_barrier
	s_add_i32 s84, s58, s43
	v_lshl_add_u64 v[148:149], s[30:31], 0, v[132:133]
	s_mov_b32 m0, s84
	ds_read_b128 v[200:203], v161 offset:16384
	ds_read_b128 v[204:207], v161 offset:17408
	ds_read_b128 v[208:211], v161 offset:18432
	ds_read_b128 v[212:215], v161 offset:19456
	ds_read_b128 v[216:219], v161 offset:20480
	ds_read_b128 v[220:223], v161 offset:21504
	ds_read_b128 v[224:227], v161 offset:22528
	ds_read_b128 v[228:231], v161 offset:23552
	global_load_lds_dwordx4 v[148:149], off
	s_add_i32 m0, s84, 0x2000
	s_add_u32 s84, s30, 0x100000
	v_lshl_add_u64 v[180:181], s[30:31], 0, v[136:137]
	s_addc_u32 s85, s31, 0
	s_add_i32 s86, s59, s43
	global_load_lds_dwordx4 v[180:181], off
	v_lshl_add_u64 v[232:233], s[84:85], 0, v[132:133]
	s_mov_b32 m0, s86
	v_lshl_add_u64 v[234:235], s[34:35], 0, v[134:135]
	global_load_lds_dwordx4 v[232:233], off
	v_lshl_add_u64 v[232:233], s[84:85], 0, v[136:137]
	s_add_i32 m0, s86, 0x2000
	s_nop 0
	global_load_lds_dwordx4 v[232:233], off
	v_lshl_add_u64 v[232:233], s[34:35], 0, v[130:131]
	s_mov_b32 m0, s27
	s_nop 0
	global_load_lds_dwordx4 v[232:233], off
	s_mov_b32 m0, s46
	s_nop 0
	global_load_lds_dwordx4 v[234:235], off
	s_waitcnt vmcnt(8)
	s_waitcnt lgkmcnt(0)
	s_barrier
	s_waitcnt lgkmcnt(0)
	v_mfma_f32_16x16x32_bf16 v[62:65], v[164:167], v[200:203], v[62:65]
	v_mfma_f32_16x16x32_bf16 v[58:61], v[172:175], v[200:203], v[58:61]
	v_mfma_f32_16x16x32_bf16 v[46:49], v[164:167], v[208:211], v[46:49]
	v_mfma_f32_16x16x32_bf16 v[42:45], v[172:175], v[208:211], v[42:45]
	v_mfma_f32_16x16x32_bf16 v[30:33], v[164:167], v[216:219], v[30:33]
	v_mfma_f32_16x16x32_bf16 v[26:29], v[172:175], v[216:219], v[26:29]
	v_mfma_f32_16x16x32_bf16 v[14:17], v[164:167], v[224:227], v[14:17]
	v_mfma_f32_16x16x32_bf16 v[10:13], v[172:175], v[224:227], v[10:13]
	v_mfma_f32_16x16x32_bf16 v[62:65], v[168:171], v[204:207], v[62:65]
	v_mfma_f32_16x16x32_bf16 v[58:61], v[176:179], v[204:207], v[58:61]
	v_mfma_f32_16x16x32_bf16 v[46:49], v[168:171], v[212:215], v[46:49]
	v_mfma_f32_16x16x32_bf16 v[42:45], v[176:179], v[212:215], v[42:45]
	v_mfma_f32_16x16x32_bf16 v[30:33], v[168:171], v[220:223], v[30:33]
	v_mfma_f32_16x16x32_bf16 v[26:29], v[176:179], v[220:223], v[26:29]
	v_mfma_f32_16x16x32_bf16 v[14:17], v[168:171], v[228:231], v[14:17]
	v_mfma_f32_16x16x32_bf16 v[10:13], v[176:179], v[228:231], v[10:13]
	v_mfma_f32_16x16x32_bf16 v[54:57], v[184:187], v[200:203], v[54:57]
	v_mfma_f32_16x16x32_bf16 v[50:53], v[192:195], v[200:203], v[50:53]
	v_mfma_f32_16x16x32_bf16 v[38:41], v[184:187], v[208:211], v[38:41]
	v_mfma_f32_16x16x32_bf16 v[34:37], v[192:195], v[208:211], v[34:37]
	v_mfma_f32_16x16x32_bf16 v[22:25], v[184:187], v[216:219], v[22:25]
	v_mfma_f32_16x16x32_bf16 v[18:21], v[192:195], v[216:219], v[18:21]
	v_mfma_f32_16x16x32_bf16 v[6:9], v[184:187], v[224:227], v[6:9]
	v_mfma_f32_16x16x32_bf16 v[2:5], v[192:195], v[224:227], v[2:5]
	v_mfma_f32_16x16x32_bf16 v[54:57], v[188:191], v[204:207], v[54:57]
	v_mfma_f32_16x16x32_bf16 v[50:53], v[196:199], v[204:207], v[50:53]
	v_mfma_f32_16x16x32_bf16 v[38:41], v[188:191], v[212:215], v[38:41]
	v_mfma_f32_16x16x32_bf16 v[34:37], v[196:199], v[212:215], v[34:37]
	v_mfma_f32_16x16x32_bf16 v[22:25], v[188:191], v[220:223], v[22:25]
	v_mfma_f32_16x16x32_bf16 v[18:21], v[196:199], v[220:223], v[18:21]
	v_mfma_f32_16x16x32_bf16 v[6:9], v[188:191], v[228:231], v[6:9]
	v_mfma_f32_16x16x32_bf16 v[2:5], v[196:199], v[228:231], v[2:5]
	s_barrier
	s_add_i32 s84, 0, 0x18000
	v_add_u32_e32 v162, s84, v151
	s_add_i32 s85, 0, 0x1c000
	ds_read_b128 v[164:167], v162
	ds_read_b128 v[168:171], v162 offset:1024
	ds_read_b128 v[172:175], v162 offset:2048
	ds_read_b128 v[176:179], v162 offset:3072
	v_add_u32_e32 v162, s85, v151
	ds_read_b128 v[184:187], v162
	ds_read_b128 v[188:191], v162 offset:1024
	ds_read_b128 v[192:195], v162 offset:2048
	ds_read_b128 v[196:199], v162 offset:3072
	s_add_u32 s34, s34, 0x100000
	s_addc_u32 s35, s35, 0
	s_mov_b32 m0, s47
	v_lshl_add_u64 v[236:237], s[34:35], 0, v[130:131]
	ds_read_b128 v[200:203], v161 offset:32768
	ds_read_b128 v[204:207], v161 offset:33792
	ds_read_b128 v[208:211], v161 offset:34816
	ds_read_b128 v[212:215], v161 offset:35840
	ds_read_b128 v[216:219], v161 offset:36864
	ds_read_b128 v[220:223], v161 offset:37888
	ds_read_b128 v[224:227], v161 offset:38912
	ds_read_b128 v[228:231], v161 offset:39936
	global_load_lds_dwordx4 v[236:237], off
	v_lshl_add_u64 v[236:237], s[34:35], 0, v[134:135]
	s_mov_b32 m0, s50
	s_nop 0
	global_load_lds_dwordx4 v[236:237], off
	s_waitcnt vmcnt(8)
	s_waitcnt lgkmcnt(0)
	s_barrier
	s_waitcnt lgkmcnt(0)
	v_mfma_f32_16x16x32_bf16 v[126:129], v[164:167], v[200:203], v[126:129]
	v_mfma_f32_16x16x32_bf16 v[122:125], v[172:175], v[200:203], v[122:125]
	v_mfma_f32_16x16x32_bf16 v[110:113], v[164:167], v[208:211], v[110:113]
	v_mfma_f32_16x16x32_bf16 v[106:109], v[172:175], v[208:211], v[106:109]
	v_mfma_f32_16x16x32_bf16 v[94:97], v[164:167], v[216:219], v[94:97]
	v_mfma_f32_16x16x32_bf16 v[90:93], v[172:175], v[216:219], v[90:93]
	v_mfma_f32_16x16x32_bf16 v[78:81], v[164:167], v[224:227], v[78:81]
	v_mfma_f32_16x16x32_bf16 v[74:77], v[172:175], v[224:227], v[74:77]
	v_mfma_f32_16x16x32_bf16 v[126:129], v[168:171], v[204:207], v[126:129]
	v_mfma_f32_16x16x32_bf16 v[122:125], v[176:179], v[204:207], v[122:125]
	v_mfma_f32_16x16x32_bf16 v[110:113], v[168:171], v[212:215], v[110:113]
	v_mfma_f32_16x16x32_bf16 v[106:109], v[176:179], v[212:215], v[106:109]
	v_mfma_f32_16x16x32_bf16 v[94:97], v[168:171], v[220:223], v[94:97]
	v_mfma_f32_16x16x32_bf16 v[90:93], v[176:179], v[220:223], v[90:93]
	v_mfma_f32_16x16x32_bf16 v[78:81], v[168:171], v[228:231], v[78:81]
	v_mfma_f32_16x16x32_bf16 v[74:77], v[176:179], v[228:231], v[74:77]
	v_mfma_f32_16x16x32_bf16 v[118:121], v[184:187], v[200:203], v[118:121]
	v_mfma_f32_16x16x32_bf16 v[114:117], v[192:195], v[200:203], v[114:117]
	v_mfma_f32_16x16x32_bf16 v[102:105], v[184:187], v[208:211], v[102:105]
	v_mfma_f32_16x16x32_bf16 v[98:101], v[192:195], v[208:211], v[98:101]
	v_mfma_f32_16x16x32_bf16 v[86:89], v[184:187], v[216:219], v[86:89]
	v_mfma_f32_16x16x32_bf16 v[82:85], v[192:195], v[216:219], v[82:85]
	v_mfma_f32_16x16x32_bf16 v[70:73], v[184:187], v[224:227], v[70:73]
	v_mfma_f32_16x16x32_bf16 v[66:69], v[192:195], v[224:227], v[66:69]
	v_mfma_f32_16x16x32_bf16 v[118:121], v[188:191], v[204:207], v[118:121]
	v_mfma_f32_16x16x32_bf16 v[114:117], v[196:199], v[204:207], v[114:117]
	v_mfma_f32_16x16x32_bf16 v[102:105], v[188:191], v[212:215], v[102:105]
	v_mfma_f32_16x16x32_bf16 v[98:101], v[196:199], v[212:215], v[98:101]
	v_mfma_f32_16x16x32_bf16 v[86:89], v[188:191], v[220:223], v[86:89]
	v_mfma_f32_16x16x32_bf16 v[82:85], v[196:199], v[220:223], v[82:85]
	v_mfma_f32_16x16x32_bf16 v[70:73], v[188:191], v[228:231], v[70:73]
	v_mfma_f32_16x16x32_bf16 v[66:69], v[196:199], v[228:231], v[66:69]
	s_barrier
	s_add_i32 s34, s84, s43
	v_lshl_add_u64 v[148:149], v[148:149], 0, s[14:15]
	s_mov_b32 m0, s34
	ds_read_b128 v[200:203], v161 offset:49152
	ds_read_b128 v[204:207], v161 offset:50176
	ds_read_b128 v[208:211], v161 offset:51200
	ds_read_b128 v[212:215], v161 offset:52224
	ds_read_b128 v[216:219], v161 offset:53248
	ds_read_b128 v[220:223], v161 offset:54272
	ds_read_b128 v[224:227], v161 offset:55296
	ds_read_b128 v[228:231], v161 offset:56320
	global_load_lds_dwordx4 v[148:149], off
	s_add_i32 m0, s34, 0x2000
	s_add_u32 s30, s30, 0x100080
	v_lshl_add_u64 v[148:149], v[180:181], 0, s[14:15]
	s_addc_u32 s31, s31, 0
	s_add_i32 s34, s85, s43
	global_load_lds_dwordx4 v[148:149], off
	v_lshl_add_u64 v[148:149], s[30:31], 0, v[132:133]
	s_mov_b32 m0, s34
	s_nop 0
	global_load_lds_dwordx4 v[148:149], off
	v_lshl_add_u64 v[148:149], s[30:31], 0, v[136:137]
	s_add_i32 m0, s34, 0x2000
	s_nop 0
	global_load_lds_dwordx4 v[148:149], off
	v_lshl_add_u64 v[148:149], v[232:233], 0, s[14:15]
	s_mov_b32 m0, s52
	s_nop 0
	global_load_lds_dwordx4 v[148:149], off
	v_lshl_add_u64 v[148:149], v[234:235], 0, s[14:15]
	s_mov_b32 m0, s53
	s_nop 0
	global_load_lds_dwordx4 v[148:149], off
	s_waitcnt vmcnt(8)
	s_waitcnt lgkmcnt(0)
	s_barrier
	s_waitcnt lgkmcnt(0)
	v_mfma_f32_16x16x32_bf16 v[62:65], v[164:167], v[200:203], v[62:65]
	v_mfma_f32_16x16x32_bf16 v[58:61], v[172:175], v[200:203], v[58:61]
	v_mfma_f32_16x16x32_bf16 v[46:49], v[164:167], v[208:211], v[46:49]
	v_mfma_f32_16x16x32_bf16 v[42:45], v[172:175], v[208:211], v[42:45]
	v_mfma_f32_16x16x32_bf16 v[30:33], v[164:167], v[216:219], v[30:33]
	v_mfma_f32_16x16x32_bf16 v[26:29], v[172:175], v[216:219], v[26:29]
	v_mfma_f32_16x16x32_bf16 v[14:17], v[164:167], v[224:227], v[14:17]
	v_mfma_f32_16x16x32_bf16 v[10:13], v[172:175], v[224:227], v[10:13]
	v_mfma_f32_16x16x32_bf16 v[62:65], v[168:171], v[204:207], v[62:65]
	v_mfma_f32_16x16x32_bf16 v[58:61], v[176:179], v[204:207], v[58:61]
	v_mfma_f32_16x16x32_bf16 v[46:49], v[168:171], v[212:215], v[46:49]
	v_mfma_f32_16x16x32_bf16 v[42:45], v[176:179], v[212:215], v[42:45]
	v_mfma_f32_16x16x32_bf16 v[30:33], v[168:171], v[220:223], v[30:33]
	v_mfma_f32_16x16x32_bf16 v[26:29], v[176:179], v[220:223], v[26:29]
	v_mfma_f32_16x16x32_bf16 v[14:17], v[168:171], v[228:231], v[14:17]
	v_mfma_f32_16x16x32_bf16 v[10:13], v[176:179], v[228:231], v[10:13]
	v_mfma_f32_16x16x32_bf16 v[54:57], v[184:187], v[200:203], v[54:57]
	v_mfma_f32_16x16x32_bf16 v[50:53], v[192:195], v[200:203], v[50:53]
	v_mfma_f32_16x16x32_bf16 v[38:41], v[184:187], v[208:211], v[38:41]
	v_mfma_f32_16x16x32_bf16 v[34:37], v[192:195], v[208:211], v[34:37]
	v_mfma_f32_16x16x32_bf16 v[22:25], v[184:187], v[216:219], v[22:25]
	v_mfma_f32_16x16x32_bf16 v[18:21], v[192:195], v[216:219], v[18:21]
	v_mfma_f32_16x16x32_bf16 v[6:9], v[184:187], v[224:227], v[6:9]
	v_mfma_f32_16x16x32_bf16 v[2:5], v[192:195], v[224:227], v[2:5]
	v_mfma_f32_16x16x32_bf16 v[54:57], v[188:191], v[204:207], v[54:57]
	v_mfma_f32_16x16x32_bf16 v[50:53], v[196:199], v[204:207], v[50:53]
	v_mfma_f32_16x16x32_bf16 v[38:41], v[188:191], v[212:215], v[38:41]
	v_mfma_f32_16x16x32_bf16 v[34:37], v[196:199], v[212:215], v[34:37]
	v_mfma_f32_16x16x32_bf16 v[22:25], v[188:191], v[220:223], v[22:25]
	v_mfma_f32_16x16x32_bf16 v[18:21], v[196:199], v[220:223], v[18:21]
	v_mfma_f32_16x16x32_bf16 v[6:9], v[188:191], v[228:231], v[6:9]
	v_mfma_f32_16x16x32_bf16 v[2:5], v[196:199], v[228:231], v[2:5]
	s_barrier
	s_add_i32 s83, s83, 2
	s_add_u32 s28, s28, 0x100
	s_addc_u32 s29, s29, 0
	s_add_u32 s81, s81, 0x100
	s_addc_u32 s82, s82, 0
	s_cmp_gt_u32 s83, 61
	s_cbranch_scc0 .LBB0_197
	s_and_b64 vcc, exec, s[16:17]
	s_cbranch_vccz .LBB0_200
	s_barrier

.LBB0_216:
	s_ashr_i32 s21, s20, 31
	s_lshl_b64 s[22:23], s[20:21], 21
	s_add_u32 s22, s54, s22
	s_addc_u32 s23, s55, s23
	s_and_b64 s[24:25], s[0:1], exec
	s_cselect_b32 s21, s23, s29
	s_cselect_b32 s63, s22, s28
	s_ashr_i32 s19, s18, 31
	s_lshl_b64 s[24:25], s[18:19], 21
	s_add_u32 s24, s44, s24
	s_addc_u32 s25, s45, s25
	s_and_b64 s[34:35], s[0:1], exec
	s_cselect_b32 s19, s25, s31
	s_cselect_b32 s80, s24, s30
	s_add_u32 s28, s28, 0x100080
	s_addc_u32 s29, s29, 0
	s_add_u32 s81, s30, 0x100
	v_mov_b32_e32 v2, 0
	s_addc_u32 s82, s31, 0
	s_mov_b32 s83, -2
	v_mov_b32_e32 v3, v2
	v_mov_b32_e32 v4, v2
	v_mov_b32_e32 v5, v2
	v_mov_b32_e32 v6, v2
	v_mov_b32_e32 v7, v2
	v_mov_b32_e32 v8, v2
	v_mov_b32_e32 v9, v2
	v_mov_b32_e32 v10, v2
	v_mov_b32_e32 v11, v2
	v_mov_b32_e32 v12, v2
	v_mov_b32_e32 v13, v2
	v_mov_b32_e32 v18, v2
	v_mov_b32_e32 v19, v2
	v_mov_b32_e32 v20, v2
	v_mov_b32_e32 v21, v2
	v_mov_b32_e32 v26, v2
	v_mov_b32_e32 v27, v2
	v_mov_b32_e32 v28, v2
	v_mov_b32_e32 v29, v2
	v_mov_b32_e32 v34, v2
	v_mov_b32_e32 v35, v2
	v_mov_b32_e32 v36, v2
	v_mov_b32_e32 v37, v2
	v_mov_b32_e32 v42, v2
	v_mov_b32_e32 v43, v2
	v_mov_b32_e32 v44, v2
	v_mov_b32_e32 v45, v2
	v_mov_b32_e32 v50, v2
	v_mov_b32_e32 v51, v2
	v_mov_b32_e32 v52, v2
	v_mov_b32_e32 v53, v2
	v_mov_b32_e32 v14, v2
	v_mov_b32_e32 v15, v2
	v_mov_b32_e32 v16, v2
	v_mov_b32_e32 v17, v2
	v_mov_b32_e32 v22, v2
	v_mov_b32_e32 v23, v2
	v_mov_b32_e32 v24, v2
	v_mov_b32_e32 v25, v2
	v_mov_b32_e32 v30, v2
	v_mov_b32_e32 v31, v2
	v_mov_b32_e32 v32, v2
	v_mov_b32_e32 v33, v2
	v_mov_b32_e32 v38, v2
	v_mov_b32_e32 v39, v2
	v_mov_b32_e32 v40, v2
	v_mov_b32_e32 v41, v2
	v_mov_b32_e32 v46, v2
	v_mov_b32_e32 v47, v2
	v_mov_b32_e32 v48, v2
	v_mov_b32_e32 v49, v2
	v_mov_b32_e32 v54, v2
	v_mov_b32_e32 v55, v2
	v_mov_b32_e32 v56, v2
	v_mov_b32_e32 v57, v2
	v_mov_b32_e32 v58, v2
	v_mov_b32_e32 v59, v2
	v_mov_b32_e32 v60, v2
	v_mov_b32_e32 v61, v2
	v_mov_b32_e32 v62, v2
	v_mov_b32_e32 v63, v2
	v_mov_b32_e32 v64, v2
	v_mov_b32_e32 v65, v2
	v_mov_b32_e32 v66, v2
	v_mov_b32_e32 v67, v2
	v_mov_b32_e32 v68, v2
	v_mov_b32_e32 v69, v2
	v_mov_b32_e32 v70, v2
	v_mov_b32_e32 v71, v2
	v_mov_b32_e32 v72, v2
	v_mov_b32_e32 v73, v2
	v_mov_b32_e32 v74, v2
	v_mov_b32_e32 v75, v2
	v_mov_b32_e32 v76, v2
	v_mov_b32_e32 v77, v2
	v_mov_b32_e32 v82, v2
	v_mov_b32_e32 v83, v2
	v_mov_b32_e32 v84, v2
	v_mov_b32_e32 v85, v2
	v_mov_b32_e32 v90, v2
	v_mov_b32_e32 v91, v2
	v_mov_b32_e32 v92, v2
	v_mov_b32_e32 v93, v2
	v_mov_b32_e32 v98, v2
	v_mov_b32_e32 v99, v2
	v_mov_b32_e32 v100, v2
	v_mov_b32_e32 v101, v2
	v_mov_b32_e32 v106, v2
	v_mov_b32_e32 v107, v2
	v_mov_b32_e32 v108, v2
	v_mov_b32_e32 v109, v2
	v_mov_b32_e32 v114, v2
	v_mov_b32_e32 v115, v2
	v_mov_b32_e32 v116, v2
	v_mov_b32_e32 v117, v2
	v_mov_b32_e32 v78, v2
	v_mov_b32_e32 v79, v2
	v_mov_b32_e32 v80, v2
	v_mov_b32_e32 v81, v2
	v_mov_b32_e32 v86, v2
	v_mov_b32_e32 v87, v2
	v_mov_b32_e32 v88, v2
	v_mov_b32_e32 v89, v2
	v_mov_b32_e32 v94, v2
	v_mov_b32_e32 v95, v2
	v_mov_b32_e32 v96, v2
	v_mov_b32_e32 v97, v2
	v_mov_b32_e32 v102, v2
	v_mov_b32_e32 v103, v2
	v_mov_b32_e32 v104, v2
	v_mov_b32_e32 v105, v2
	v_mov_b32_e32 v110, v2
	v_mov_b32_e32 v111, v2
	v_mov_b32_e32 v112, v2
	v_mov_b32_e32 v113, v2
	v_mov_b32_e32 v118, v2
	v_mov_b32_e32 v119, v2
	v_mov_b32_e32 v120, v2
	v_mov_b32_e32 v121, v2
	v_mov_b32_e32 v122, v2
	v_mov_b32_e32 v123, v2
	v_mov_b32_e32 v124, v2
	v_mov_b32_e32 v125, v2
	v_mov_b32_e32 v126, v2
	v_mov_b32_e32 v127, v2
	v_mov_b32_e32 v128, v2
	v_mov_b32_e32 v129, v2
	s_setprio 0
.LBB0_217:
	ds_read_b128 v[164:167], v153
	ds_read_b128 v[168:171], v153 offset:1024
	ds_read_b128 v[172:175], v153 offset:2048
	ds_read_b128 v[176:179], v153 offset:3072
	ds_read_b128 v[184:187], v160
	ds_read_b128 v[188:191], v160 offset:1024
	ds_read_b128 v[192:195], v160 offset:2048
	ds_read_b128 v[196:199], v160 offset:3072
	s_add_u32 s30, s28, 0xfff00080
	s_addc_u32 s31, s29, -1
	s_cmp_eq_u32 s83, 60
	s_cselect_b32 s35, s21, s31
	s_cselect_b32 s34, s63, s30
	s_cselect_b32 s31, s19, s82
	s_cselect_b32 s30, s80, s81
	v_lshl_add_u64 v[148:149], s[28:29], 0, v[140:141]
	s_add_i32 m0, s27, 0xc000
	ds_read_b128 v[200:203], v161
	ds_read_b128 v[204:207], v161 offset:1024
	ds_read_b128 v[208:211], v161 offset:2048
	ds_read_b128 v[212:215], v161 offset:3072
	ds_read_b128 v[216:219], v161 offset:4096
	ds_read_b128 v[220:223], v161 offset:5120
	ds_read_b128 v[224:227], v161 offset:6144
	ds_read_b128 v[228:231], v161 offset:7168
	global_load_lds_dwordx4 v[148:149], off
	v_lshl_add_u64 v[148:149], s[28:29], 0, v[142:143]
	s_add_i32 m0, s27, 0xe000
	s_nop 0
	global_load_lds_dwordx4 v[148:149], off
	s_waitcnt vmcnt(8)
	s_waitcnt lgkmcnt(0)
	s_barrier
	s_waitcnt lgkmcnt(0)
	v_mfma_f32_16x16x32_bf16 v[126:129], v[164:167], v[200:203], v[126:129]
	v_mfma_f32_16x16x32_bf16 v[122:125], v[172:175], v[200:203], v[122:125]
	v_mfma_f32_16x16x32_bf16 v[118:121], v[164:167], v[208:211], v[118:121]
	v_mfma_f32_16x16x32_bf16 v[110:113], v[172:175], v[208:211], v[110:113]
	v_mfma_f32_16x16x32_bf16 v[102:105], v[164:167], v[216:219], v[102:105]
	v_mfma_f32_16x16x32_bf16 v[94:97], v[172:175], v[216:219], v[94:97]
	v_mfma_f32_16x16x32_bf16 v[86:89], v[164:167], v[224:227], v[86:89]
	v_mfma_f32_16x16x32_bf16 v[78:81], v[172:175], v[224:227], v[78:81]
	v_mfma_f32_16x16x32_bf16 v[126:129], v[168:171], v[204:207], v[126:129]
	v_mfma_f32_16x16x32_bf16 v[122:125], v[176:179], v[204:207], v[122:125]
	v_mfma_f32_16x16x32_bf16 v[118:121], v[168:171], v[212:215], v[118:121]
	v_mfma_f32_16x16x32_bf16 v[110:113], v[176:179], v[212:215], v[110:113]
	v_mfma_f32_16x16x32_bf16 v[102:105], v[168:171], v[220:223], v[102:105]
	v_mfma_f32_16x16x32_bf16 v[94:97], v[176:179], v[220:223], v[94:97]
	v_mfma_f32_16x16x32_bf16 v[86:89], v[168:171], v[228:231], v[86:89]
	v_mfma_f32_16x16x32_bf16 v[78:81], v[176:179], v[228:231], v[78:81]
	v_mfma_f32_16x16x32_bf16 v[114:117], v[184:187], v[200:203], v[114:117]
	v_mfma_f32_16x16x32_bf16 v[106:109], v[192:195], v[200:203], v[106:109]
	v_mfma_f32_16x16x32_bf16 v[98:101], v[184:187], v[208:211], v[98:101]
	v_mfma_f32_16x16x32_bf16 v[90:93], v[192:195], v[208:211], v[90:93]
	v_mfma_f32_16x16x32_bf16 v[82:85], v[184:187], v[216:219], v[82:85]
	v_mfma_f32_16x16x32_bf16 v[74:77], v[192:195], v[216:219], v[74:77]
	v_mfma_f32_16x16x32_bf16 v[70:73], v[184:187], v[224:227], v[70:73]
	v_mfma_f32_16x16x32_bf16 v[66:69], v[192:195], v[224:227], v[66:69]
	v_mfma_f32_16x16x32_bf16 v[114:117], v[188:191], v[204:207], v[114:117]
	v_mfma_f32_16x16x32_bf16 v[106:109], v[196:199], v[204:207], v[106:109]
	v_mfma_f32_16x16x32_bf16 v[98:101], v[188:191], v[212:215], v[98:101]
	v_mfma_f32_16x16x32_bf16 v[90:93], v[196:199], v[212:215], v[90:93]
	v_mfma_f32_16x16x32_bf16 v[82:85], v[188:191], v[220:223], v[82:85]
	v_mfma_f32_16x16x32_bf16 v[74:77], v[196:199], v[220:223], v[74:77]
	v_mfma_f32_16x16x32_bf16 v[70:73], v[188:191], v[228:231], v[70:73]
	v_mfma_f32_16x16x32_bf16 v[66:69], v[196:199], v[228:231], v[66:69]
	s_barrier
	s_add_i32 s84, s58, s43
	v_lshl_add_u64 v[148:149], s[30:31], 0, v[132:133]
	s_mov_b32 m0, s84
	ds_read_b128 v[200:203], v161 offset:16384
	ds_read_b128 v[204:207], v161 offset:17408
	ds_read_b128 v[208:211], v161 offset:18432
	ds_read_b128 v[212:215], v161 offset:19456
	ds_read_b128 v[216:219], v161 offset:20480
	ds_read_b128 v[220:223], v161 offset:21504
	ds_read_b128 v[224:227], v161 offset:22528
	ds_read_b128 v[228:231], v161 offset:23552
	global_load_lds_dwordx4 v[148:149], off
	s_add_i32 m0, s84, 0x2000
	s_add_u32 s84, s30, 0x100000
	v_lshl_add_u64 v[180:181], s[30:31], 0, v[136:137]
	s_addc_u32 s85, s31, 0
	s_add_i32 s86, s59, s43
	global_load_lds_dwordx4 v[180:181], off
	v_lshl_add_u64 v[232:233], s[84:85], 0, v[132:133]
	s_mov_b32 m0, s86
	v_lshl_add_u64 v[234:235], s[34:35], 0, v[134:135]
	global_load_lds_dwordx4 v[232:233], off
	v_lshl_add_u64 v[232:233], s[84:85], 0, v[136:137]
	s_add_i32 m0, s86, 0x2000
	s_nop 0
	global_load_lds_dwordx4 v[232:233], off
	v_lshl_add_u64 v[232:233], s[34:35], 0, v[130:131]
	s_mov_b32 m0, s27
	s_nop 0
	global_load_lds_dwordx4 v[232:233], off
	s_mov_b32 m0, s46
	s_nop 0
	global_load_lds_dwordx4 v[234:235], off
	s_waitcnt vmcnt(8)
	s_waitcnt lgkmcnt(0)
	s_barrier
	s_waitcnt lgkmcnt(0)
	v_mfma_f32_16x16x32_bf16 v[62:65], v[164:167], v[200:203], v[62:65]
	v_mfma_f32_16x16x32_bf16 v[58:61], v[172:175], v[200:203], v[58:61]
	v_mfma_f32_16x16x32_bf16 v[54:57], v[164:167], v[208:211], v[54:57]
	v_mfma_f32_16x16x32_bf16 v[46:49], v[172:175], v[208:211], v[46:49]
	v_mfma_f32_16x16x32_bf16 v[38:41], v[164:167], v[216:219], v[38:41]
	v_mfma_f32_16x16x32_bf16 v[30:33], v[172:175], v[216:219], v[30:33]
	v_mfma_f32_16x16x32_bf16 v[22:25], v[164:167], v[224:227], v[22:25]
	v_mfma_f32_16x16x32_bf16 v[14:17], v[172:175], v[224:227], v[14:17]
	v_mfma_f32_16x16x32_bf16 v[62:65], v[168:171], v[204:207], v[62:65]
	v_mfma_f32_16x16x32_bf16 v[58:61], v[176:179], v[204:207], v[58:61]
	v_mfma_f32_16x16x32_bf16 v[54:57], v[168:171], v[212:215], v[54:57]
	v_mfma_f32_16x16x32_bf16 v[46:49], v[176:179], v[212:215], v[46:49]
	v_mfma_f32_16x16x32_bf16 v[38:41], v[168:171], v[220:223], v[38:41]
	v_mfma_f32_16x16x32_bf16 v[30:33], v[176:179], v[220:223], v[30:33]
	v_mfma_f32_16x16x32_bf16 v[22:25], v[168:171], v[228:231], v[22:25]
	v_mfma_f32_16x16x32_bf16 v[14:17], v[176:179], v[228:231], v[14:17]
	v_mfma_f32_16x16x32_bf16 v[50:53], v[184:187], v[200:203], v[50:53]
	v_mfma_f32_16x16x32_bf16 v[42:45], v[192:195], v[200:203], v[42:45]
	v_mfma_f32_16x16x32_bf16 v[34:37], v[184:187], v[208:211], v[34:37]
	v_mfma_f32_16x16x32_bf16 v[26:29], v[192:195], v[208:211], v[26:29]
	v_mfma_f32_16x16x32_bf16 v[18:21], v[184:187], v[216:219], v[18:21]
	v_mfma_f32_16x16x32_bf16 v[10:13], v[192:195], v[216:219], v[10:13]
	v_mfma_f32_16x16x32_bf16 v[6:9], v[184:187], v[224:227], v[6:9]
	v_mfma_f32_16x16x32_bf16 v[2:5], v[192:195], v[224:227], v[2:5]
	v_mfma_f32_16x16x32_bf16 v[50:53], v[188:191], v[204:207], v[50:53]
	v_mfma_f32_16x16x32_bf16 v[42:45], v[196:199], v[204:207], v[42:45]
	v_mfma_f32_16x16x32_bf16 v[34:37], v[188:191], v[212:215], v[34:37]
	v_mfma_f32_16x16x32_bf16 v[26:29], v[196:199], v[212:215], v[26:29]
	v_mfma_f32_16x16x32_bf16 v[18:21], v[188:191], v[220:223], v[18:21]
	v_mfma_f32_16x16x32_bf16 v[10:13], v[196:199], v[220:223], v[10:13]
	v_mfma_f32_16x16x32_bf16 v[6:9], v[188:191], v[228:231], v[6:9]
	v_mfma_f32_16x16x32_bf16 v[2:5], v[196:199], v[228:231], v[2:5]
	s_barrier
	s_add_i32 s84, 0, 0x18000
	v_add_u32_e32 v162, s84, v151
	s_add_i32 s85, 0, 0x1c000
	ds_read_b128 v[164:167], v162
	ds_read_b128 v[168:171], v162 offset:1024
	ds_read_b128 v[172:175], v162 offset:2048
	ds_read_b128 v[176:179], v162 offset:3072
	v_add_u32_e32 v162, s85, v151
	ds_read_b128 v[184:187], v162
	ds_read_b128 v[188:191], v162 offset:1024
	ds_read_b128 v[192:195], v162 offset:2048
	ds_read_b128 v[196:199], v162 offset:3072
	s_add_u32 s34, s34, 0x100000
	s_addc_u32 s35, s35, 0
	s_mov_b32 m0, s47
	v_lshl_add_u64 v[236:237], s[34:35], 0, v[130:131]
	ds_read_b128 v[200:203], v161 offset:32768
	ds_read_b128 v[204:207], v161 offset:33792
	ds_read_b128 v[208:211], v161 offset:34816
	ds_read_b128 v[212:215], v161 offset:35840
	ds_read_b128 v[216:219], v161 offset:36864
	ds_read_b128 v[220:223], v161 offset:37888
	ds_read_b128 v[224:227], v161 offset:38912
	ds_read_b128 v[228:231], v161 offset:39936
	global_load_lds_dwordx4 v[236:237], off
	v_lshl_add_u64 v[236:237], s[34:35], 0, v[134:135]
	s_mov_b32 m0, s50
	s_nop 0
	global_load_lds_dwordx4 v[236:237], off
	s_waitcnt vmcnt(8)
	s_waitcnt lgkmcnt(0)
	s_barrier
	s_waitcnt lgkmcnt(0)
	v_mfma_f32_16x16x32_bf16 v[126:129], v[164:167], v[200:203], v[126:129]
	v_mfma_f32_16x16x32_bf16 v[122:125], v[172:175], v[200:203], v[122:125]
	v_mfma_f32_16x16x32_bf16 v[118:121], v[164:167], v[208:211], v[118:121]
	v_mfma_f32_16x16x32_bf16 v[110:113], v[172:175], v[208:211], v[110:113]
	v_mfma_f32_16x16x32_bf16 v[102:105], v[164:167], v[216:219], v[102:105]
	v_mfma_f32_16x16x32_bf16 v[94:97], v[172:175], v[216:219], v[94:97]
	v_mfma_f32_16x16x32_bf16 v[86:89], v[164:167], v[224:227], v[86:89]
	v_mfma_f32_16x16x32_bf16 v[78:81], v[172:175], v[224:227], v[78:81]
	v_mfma_f32_16x16x32_bf16 v[126:129], v[168:171], v[204:207], v[126:129]
	v_mfma_f32_16x16x32_bf16 v[122:125], v[176:179], v[204:207], v[122:125]
	v_mfma_f32_16x16x32_bf16 v[118:121], v[168:171], v[212:215], v[118:121]
	v_mfma_f32_16x16x32_bf16 v[110:113], v[176:179], v[212:215], v[110:113]
	v_mfma_f32_16x16x32_bf16 v[102:105], v[168:171], v[220:223], v[102:105]
	v_mfma_f32_16x16x32_bf16 v[94:97], v[176:179], v[220:223], v[94:97]
	v_mfma_f32_16x16x32_bf16 v[86:89], v[168:171], v[228:231], v[86:89]
	v_mfma_f32_16x16x32_bf16 v[78:81], v[176:179], v[228:231], v[78:81]
	v_mfma_f32_16x16x32_bf16 v[114:117], v[184:187], v[200:203], v[114:117]
	v_mfma_f32_16x16x32_bf16 v[106:109], v[192:195], v[200:203], v[106:109]
	v_mfma_f32_16x16x32_bf16 v[98:101], v[184:187], v[208:211], v[98:101]
	v_mfma_f32_16x16x32_bf16 v[90:93], v[192:195], v[208:211], v[90:93]
	v_mfma_f32_16x16x32_bf16 v[82:85], v[184:187], v[216:219], v[82:85]
	v_mfma_f32_16x16x32_bf16 v[74:77], v[192:195], v[216:219], v[74:77]
	v_mfma_f32_16x16x32_bf16 v[70:73], v[184:187], v[224:227], v[70:73]
	v_mfma_f32_16x16x32_bf16 v[66:69], v[192:195], v[224:227], v[66:69]
	v_mfma_f32_16x16x32_bf16 v[114:117], v[188:191], v[204:207], v[114:117]
	v_mfma_f32_16x16x32_bf16 v[106:109], v[196:199], v[204:207], v[106:109]
	v_mfma_f32_16x16x32_bf16 v[98:101], v[188:191], v[212:215], v[98:101]
	v_mfma_f32_16x16x32_bf16 v[90:93], v[196:199], v[212:215], v[90:93]
	v_mfma_f32_16x16x32_bf16 v[82:85], v[188:191], v[220:223], v[82:85]
	v_mfma_f32_16x16x32_bf16 v[74:77], v[196:199], v[220:223], v[74:77]
	v_mfma_f32_16x16x32_bf16 v[70:73], v[188:191], v[228:231], v[70:73]
	v_mfma_f32_16x16x32_bf16 v[66:69], v[196:199], v[228:231], v[66:69]
	s_barrier
	s_add_i32 s34, s84, s43
	v_lshl_add_u64 v[148:149], v[148:149], 0, s[14:15]
	s_mov_b32 m0, s34
	ds_read_b128 v[200:203], v161 offset:49152
	ds_read_b128 v[204:207], v161 offset:50176
	ds_read_b128 v[208:211], v161 offset:51200
	ds_read_b128 v[212:215], v161 offset:52224
	ds_read_b128 v[216:219], v161 offset:53248
	ds_read_b128 v[220:223], v161 offset:54272
	ds_read_b128 v[224:227], v161 offset:55296
	ds_read_b128 v[228:231], v161 offset:56320
	global_load_lds_dwordx4 v[148:149], off
	s_add_i32 m0, s34, 0x2000
	s_add_u32 s30, s30, 0x100080
	v_lshl_add_u64 v[148:149], v[180:181], 0, s[14:15]
	s_addc_u32 s31, s31, 0
	s_add_i32 s34, s85, s43
	global_load_lds_dwordx4 v[148:149], off
	v_lshl_add_u64 v[148:149], s[30:31], 0, v[132:133]
	s_mov_b32 m0, s34
	s_nop 0
	global_load_lds_dwordx4 v[148:149], off
	v_lshl_add_u64 v[148:149], s[30:31], 0, v[136:137]
	s_add_i32 m0, s34, 0x2000
	s_nop 0
	global_load_lds_dwordx4 v[148:149], off
	v_lshl_add_u64 v[148:149], v[232:233], 0, s[14:15]
	s_mov_b32 m0, s52
	s_nop 0
	global_load_lds_dwordx4 v[148:149], off
	v_lshl_add_u64 v[148:149], v[234:235], 0, s[14:15]
	s_mov_b32 m0, s53
	s_nop 0
	global_load_lds_dwordx4 v[148:149], off
	s_waitcnt vmcnt(8)
	s_waitcnt lgkmcnt(0)
	s_barrier
	s_waitcnt lgkmcnt(0)
	v_mfma_f32_16x16x32_bf16 v[62:65], v[164:167], v[200:203], v[62:65]
	v_mfma_f32_16x16x32_bf16 v[58:61], v[172:175], v[200:203], v[58:61]
	v_mfma_f32_16x16x32_bf16 v[54:57], v[164:167], v[208:211], v[54:57]
	v_mfma_f32_16x16x32_bf16 v[46:49], v[172:175], v[208:211], v[46:49]
	v_mfma_f32_16x16x32_bf16 v[38:41], v[164:167], v[216:219], v[38:41]
	v_mfma_f32_16x16x32_bf16 v[30:33], v[172:175], v[216:219], v[30:33]
	v_mfma_f32_16x16x32_bf16 v[22:25], v[164:167], v[224:227], v[22:25]
	v_mfma_f32_16x16x32_bf16 v[14:17], v[172:175], v[224:227], v[14:17]
	v_mfma_f32_16x16x32_bf16 v[62:65], v[168:171], v[204:207], v[62:65]
	v_mfma_f32_16x16x32_bf16 v[58:61], v[176:179], v[204:207], v[58:61]
	v_mfma_f32_16x16x32_bf16 v[54:57], v[168:171], v[212:215], v[54:57]
	v_mfma_f32_16x16x32_bf16 v[46:49], v[176:179], v[212:215], v[46:49]
	v_mfma_f32_16x16x32_bf16 v[38:41], v[168:171], v[220:223], v[38:41]
	v_mfma_f32_16x16x32_bf16 v[30:33], v[176:179], v[220:223], v[30:33]
	v_mfma_f32_16x16x32_bf16 v[22:25], v[168:171], v[228:231], v[22:25]
	v_mfma_f32_16x16x32_bf16 v[14:17], v[176:179], v[228:231], v[14:17]
	v_mfma_f32_16x16x32_bf16 v[50:53], v[184:187], v[200:203], v[50:53]
	v_mfma_f32_16x16x32_bf16 v[42:45], v[192:195], v[200:203], v[42:45]
	v_mfma_f32_16x16x32_bf16 v[34:37], v[184:187], v[208:211], v[34:37]
	v_mfma_f32_16x16x32_bf16 v[26:29], v[192:195], v[208:211], v[26:29]
	v_mfma_f32_16x16x32_bf16 v[18:21], v[184:187], v[216:219], v[18:21]
	v_mfma_f32_16x16x32_bf16 v[10:13], v[192:195], v[216:219], v[10:13]
	v_mfma_f32_16x16x32_bf16 v[6:9], v[184:187], v[224:227], v[6:9]
	v_mfma_f32_16x16x32_bf16 v[2:5], v[192:195], v[224:227], v[2:5]
	v_mfma_f32_16x16x32_bf16 v[50:53], v[188:191], v[204:207], v[50:53]
	v_mfma_f32_16x16x32_bf16 v[42:45], v[196:199], v[204:207], v[42:45]
	v_mfma_f32_16x16x32_bf16 v[34:37], v[188:191], v[212:215], v[34:37]
	v_mfma_f32_16x16x32_bf16 v[26:29], v[196:199], v[212:215], v[26:29]
	v_mfma_f32_16x16x32_bf16 v[18:21], v[188:191], v[220:223], v[18:21]
	v_mfma_f32_16x16x32_bf16 v[10:13], v[196:199], v[220:223], v[10:13]
	v_mfma_f32_16x16x32_bf16 v[6:9], v[188:191], v[228:231], v[6:9]
	v_mfma_f32_16x16x32_bf16 v[2:5], v[196:199], v[228:231], v[2:5]
	s_barrier
	s_add_i32 s83, s83, 2
	s_add_u32 s28, s28, 0x100
	s_addc_u32 s29, s29, 0
	s_add_u32 s81, s81, 0x100
	s_addc_u32 s82, s82, 0
	s_cmp_gt_u32 s83, 61
	s_cbranch_scc0 .LBB0_217
	s_and_b64 vcc, exec, s[16:17]
	s_cbranch_vccz .LBB0_220
	s_barrier

.LBB0_236:
	s_ashr_i32 s19, s18, 31
	s_lshl_b64 s[20:21], s[18:19], 21
	s_add_u32 s20, s54, s20
	s_addc_u32 s21, s55, s21
	s_and_b64 s[22:23], s[0:1], exec
	s_cselect_b32 s19, s21, s27
	s_cselect_b32 s53, s20, s26
	s_ashr_i32 s17, s16, 31
	s_lshl_b64 s[22:23], s[16:17], 21
	s_add_u32 s22, s35, s22
	s_addc_u32 s23, s43, s23
	s_and_b64 s[30:31], s[0:1], exec
	s_cselect_b32 s17, s23, s29
	s_cselect_b32 s58, s22, s28
	s_add_u32 s26, s26, 0x100080
	s_addc_u32 s27, s27, 0
	s_add_u32 s59, s28, 0x100
	v_mov_b32_e32 v2, 0
	s_addc_u32 s62, s29, 0
	s_mov_b32 s63, -2
	v_mov_b32_e32 v3, v2
	v_mov_b32_e32 v4, v2
	v_mov_b32_e32 v5, v2
	v_mov_b32_e32 v6, v2
	v_mov_b32_e32 v7, v2
	v_mov_b32_e32 v8, v2
	v_mov_b32_e32 v9, v2
	v_mov_b32_e32 v18, v2
	v_mov_b32_e32 v19, v2
	v_mov_b32_e32 v20, v2
	v_mov_b32_e32 v21, v2
	v_mov_b32_e32 v22, v2
	v_mov_b32_e32 v23, v2
	v_mov_b32_e32 v24, v2
	v_mov_b32_e32 v25, v2
	v_mov_b32_e32 v34, v2
	v_mov_b32_e32 v35, v2
	v_mov_b32_e32 v36, v2
	v_mov_b32_e32 v37, v2
	v_mov_b32_e32 v38, v2
	v_mov_b32_e32 v39, v2
	v_mov_b32_e32 v40, v2
	v_mov_b32_e32 v41, v2
	v_mov_b32_e32 v50, v2
	v_mov_b32_e32 v51, v2
	v_mov_b32_e32 v52, v2
	v_mov_b32_e32 v53, v2
	v_mov_b32_e32 v54, v2
	v_mov_b32_e32 v55, v2
	v_mov_b32_e32 v56, v2
	v_mov_b32_e32 v57, v2
	v_mov_b32_e32 v10, v2
	v_mov_b32_e32 v11, v2
	v_mov_b32_e32 v12, v2
	v_mov_b32_e32 v13, v2
	v_mov_b32_e32 v14, v2
	v_mov_b32_e32 v15, v2
	v_mov_b32_e32 v16, v2
	v_mov_b32_e32 v17, v2
	v_mov_b32_e32 v26, v2
	v_mov_b32_e32 v27, v2
	v_mov_b32_e32 v28, v2
	v_mov_b32_e32 v29, v2
	v_mov_b32_e32 v30, v2
	v_mov_b32_e32 v31, v2
	v_mov_b32_e32 v32, v2
	v_mov_b32_e32 v33, v2
	v_mov_b32_e32 v42, v2
	v_mov_b32_e32 v43, v2
	v_mov_b32_e32 v44, v2
	v_mov_b32_e32 v45, v2
	v_mov_b32_e32 v46, v2
	v_mov_b32_e32 v47, v2
	v_mov_b32_e32 v48, v2
	v_mov_b32_e32 v49, v2
	v_mov_b32_e32 v58, v2
	v_mov_b32_e32 v59, v2
	v_mov_b32_e32 v60, v2
	v_mov_b32_e32 v61, v2
	v_mov_b32_e32 v62, v2
	v_mov_b32_e32 v63, v2
	v_mov_b32_e32 v64, v2
	v_mov_b32_e32 v65, v2
	v_mov_b32_e32 v66, v2
	v_mov_b32_e32 v67, v2
	v_mov_b32_e32 v68, v2
	v_mov_b32_e32 v69, v2
	v_mov_b32_e32 v70, v2
	v_mov_b32_e32 v71, v2
	v_mov_b32_e32 v72, v2
	v_mov_b32_e32 v73, v2
	v_mov_b32_e32 v82, v2
	v_mov_b32_e32 v83, v2
	v_mov_b32_e32 v84, v2
	v_mov_b32_e32 v85, v2
	v_mov_b32_e32 v86, v2
	v_mov_b32_e32 v87, v2
	v_mov_b32_e32 v88, v2
	v_mov_b32_e32 v89, v2
	v_mov_b32_e32 v98, v2
	v_mov_b32_e32 v99, v2
	v_mov_b32_e32 v100, v2
	v_mov_b32_e32 v101, v2
	v_mov_b32_e32 v102, v2
	v_mov_b32_e32 v103, v2
	v_mov_b32_e32 v104, v2
	v_mov_b32_e32 v105, v2
	v_mov_b32_e32 v114, v2
	v_mov_b32_e32 v115, v2
	v_mov_b32_e32 v116, v2
	v_mov_b32_e32 v117, v2
	v_mov_b32_e32 v118, v2
	v_mov_b32_e32 v119, v2
	v_mov_b32_e32 v120, v2
	v_mov_b32_e32 v121, v2
	v_mov_b32_e32 v74, v2
	v_mov_b32_e32 v75, v2
	v_mov_b32_e32 v76, v2
	v_mov_b32_e32 v77, v2
	v_mov_b32_e32 v78, v2
	v_mov_b32_e32 v79, v2
	v_mov_b32_e32 v80, v2
	v_mov_b32_e32 v81, v2
	v_mov_b32_e32 v90, v2
	v_mov_b32_e32 v91, v2
	v_mov_b32_e32 v92, v2
	v_mov_b32_e32 v93, v2
	v_mov_b32_e32 v94, v2
	v_mov_b32_e32 v95, v2
	v_mov_b32_e32 v96, v2
	v_mov_b32_e32 v97, v2
	v_mov_b32_e32 v106, v2
	v_mov_b32_e32 v107, v2
	v_mov_b32_e32 v108, v2
	v_mov_b32_e32 v109, v2
	v_mov_b32_e32 v110, v2
	v_mov_b32_e32 v111, v2
	v_mov_b32_e32 v112, v2
	v_mov_b32_e32 v113, v2
	v_mov_b32_e32 v122, v2
	v_mov_b32_e32 v123, v2
	v_mov_b32_e32 v124, v2
	v_mov_b32_e32 v125, v2
	v_mov_b32_e32 v126, v2
	v_mov_b32_e32 v127, v2
	v_mov_b32_e32 v128, v2
	v_mov_b32_e32 v129, v2
	s_setprio 0
.LBB0_237:
	ds_read_b128 v[148:151], v164
	ds_read_b128 v[168:171], v164 offset:1024
	ds_read_b128 v[172:175], v164 offset:2048
	ds_read_b128 v[176:179], v164 offset:3072
	ds_read_b128 v[184:187], v165
	ds_read_b128 v[188:191], v165 offset:1024
	ds_read_b128 v[192:195], v165 offset:2048
	ds_read_b128 v[196:199], v165 offset:3072
	s_add_u32 s28, s26, 0xfff00080
	s_addc_u32 s29, s27, -1
	s_cmp_eq_u32 s63, 60
	s_cselect_b32 s31, s19, s29
	s_cselect_b32 s30, s53, s28
	s_cselect_b32 s29, s17, s62
	s_cselect_b32 s28, s58, s59
	v_lshl_add_u64 v[152:153], s[26:27], 0, v[140:141]
	s_add_i32 m0, s25, 0xc000
	ds_read_b128 v[200:203], v166
	ds_read_b128 v[204:207], v166 offset:1024
	ds_read_b128 v[208:211], v166 offset:2048
	ds_read_b128 v[212:215], v166 offset:3072
	ds_read_b128 v[216:219], v166 offset:4096
	ds_read_b128 v[220:223], v166 offset:5120
	ds_read_b128 v[224:227], v166 offset:6144
	ds_read_b128 v[228:231], v166 offset:7168
	global_load_lds_dwordx4 v[152:153], off
	v_lshl_add_u64 v[152:153], s[26:27], 0, v[142:143]
	s_add_i32 m0, s25, 0xe000
	s_nop 0
	global_load_lds_dwordx4 v[152:153], off
	s_waitcnt vmcnt(8)
	s_waitcnt lgkmcnt(0)
	s_barrier
	s_waitcnt lgkmcnt(0)
	v_mfma_f32_16x16x32_bf16 v[126:129], v[148:151], v[200:203], v[126:129]
	v_mfma_f32_16x16x32_bf16 v[122:125], v[172:175], v[200:203], v[122:125]
	v_mfma_f32_16x16x32_bf16 v[110:113], v[148:151], v[208:211], v[110:113]
	v_mfma_f32_16x16x32_bf16 v[106:109], v[172:175], v[208:211], v[106:109]
	v_mfma_f32_16x16x32_bf16 v[94:97], v[148:151], v[216:219], v[94:97]
	v_mfma_f32_16x16x32_bf16 v[90:93], v[172:175], v[216:219], v[90:93]
	v_mfma_f32_16x16x32_bf16 v[78:81], v[148:151], v[224:227], v[78:81]
	v_mfma_f32_16x16x32_bf16 v[74:77], v[172:175], v[224:227], v[74:77]
	v_mfma_f32_16x16x32_bf16 v[126:129], v[168:171], v[204:207], v[126:129]
	v_mfma_f32_16x16x32_bf16 v[122:125], v[176:179], v[204:207], v[122:125]
	v_mfma_f32_16x16x32_bf16 v[110:113], v[168:171], v[212:215], v[110:113]
	v_mfma_f32_16x16x32_bf16 v[106:109], v[176:179], v[212:215], v[106:109]
	v_mfma_f32_16x16x32_bf16 v[94:97], v[168:171], v[220:223], v[94:97]
	v_mfma_f32_16x16x32_bf16 v[90:93], v[176:179], v[220:223], v[90:93]
	v_mfma_f32_16x16x32_bf16 v[78:81], v[168:171], v[228:231], v[78:81]
	v_mfma_f32_16x16x32_bf16 v[74:77], v[176:179], v[228:231], v[74:77]
	v_mfma_f32_16x16x32_bf16 v[118:121], v[184:187], v[200:203], v[118:121]
	v_mfma_f32_16x16x32_bf16 v[114:117], v[192:195], v[200:203], v[114:117]
	v_mfma_f32_16x16x32_bf16 v[102:105], v[184:187], v[208:211], v[102:105]
	v_mfma_f32_16x16x32_bf16 v[98:101], v[192:195], v[208:211], v[98:101]
	v_mfma_f32_16x16x32_bf16 v[86:89], v[184:187], v[216:219], v[86:89]
	v_mfma_f32_16x16x32_bf16 v[82:85], v[192:195], v[216:219], v[82:85]
	v_mfma_f32_16x16x32_bf16 v[70:73], v[184:187], v[224:227], v[70:73]
	v_mfma_f32_16x16x32_bf16 v[66:69], v[192:195], v[224:227], v[66:69]
	v_mfma_f32_16x16x32_bf16 v[118:121], v[188:191], v[204:207], v[118:121]
	v_mfma_f32_16x16x32_bf16 v[114:117], v[196:199], v[204:207], v[114:117]
	v_mfma_f32_16x16x32_bf16 v[102:105], v[188:191], v[212:215], v[102:105]
	v_mfma_f32_16x16x32_bf16 v[98:101], v[196:199], v[212:215], v[98:101]
	v_mfma_f32_16x16x32_bf16 v[86:89], v[188:191], v[220:223], v[86:89]
	v_mfma_f32_16x16x32_bf16 v[82:85], v[196:199], v[220:223], v[82:85]
	v_mfma_f32_16x16x32_bf16 v[70:73], v[188:191], v[228:231], v[70:73]
	v_mfma_f32_16x16x32_bf16 v[66:69], v[196:199], v[228:231], v[66:69]
	s_barrier
	s_add_i32 s80, s50, s34
	v_lshl_add_u64 v[152:153], s[28:29], 0, v[132:133]
	s_mov_b32 m0, s80
	ds_read_b128 v[200:203], v166 offset:16384
	ds_read_b128 v[204:207], v166 offset:17408
	ds_read_b128 v[208:211], v166 offset:18432
	ds_read_b128 v[212:215], v166 offset:19456
	ds_read_b128 v[216:219], v166 offset:20480
	ds_read_b128 v[220:223], v166 offset:21504
	ds_read_b128 v[224:227], v166 offset:22528
	ds_read_b128 v[228:231], v166 offset:23552
	global_load_lds_dwordx4 v[152:153], off
	s_add_i32 m0, s80, 0x2000
	s_add_u32 s80, s28, 0x100000
	v_lshl_add_u64 v[180:181], s[28:29], 0, v[136:137]
	s_addc_u32 s81, s29, 0
	s_add_i32 s82, s51, s34
	global_load_lds_dwordx4 v[180:181], off
	v_lshl_add_u64 v[232:233], s[80:81], 0, v[132:133]
	s_mov_b32 m0, s82
	v_lshl_add_u64 v[234:235], s[30:31], 0, v[134:135]
	global_load_lds_dwordx4 v[232:233], off
	v_lshl_add_u64 v[232:233], s[80:81], 0, v[136:137]
	s_add_i32 m0, s82, 0x2000
	s_nop 0
	global_load_lds_dwordx4 v[232:233], off
	v_lshl_add_u64 v[232:233], s[30:31], 0, v[130:131]
	s_mov_b32 m0, s25
	s_nop 0
	global_load_lds_dwordx4 v[232:233], off
	s_mov_b32 m0, s41
	s_nop 0
	global_load_lds_dwordx4 v[234:235], off
	s_waitcnt vmcnt(8)
	s_waitcnt lgkmcnt(0)
	s_barrier
	s_waitcnt lgkmcnt(0)
	v_mfma_f32_16x16x32_bf16 v[62:65], v[148:151], v[200:203], v[62:65]
	v_mfma_f32_16x16x32_bf16 v[58:61], v[172:175], v[200:203], v[58:61]
	v_mfma_f32_16x16x32_bf16 v[46:49], v[148:151], v[208:211], v[46:49]
	v_mfma_f32_16x16x32_bf16 v[42:45], v[172:175], v[208:211], v[42:45]
	v_mfma_f32_16x16x32_bf16 v[30:33], v[148:151], v[216:219], v[30:33]
	v_mfma_f32_16x16x32_bf16 v[26:29], v[172:175], v[216:219], v[26:29]
	v_mfma_f32_16x16x32_bf16 v[14:17], v[148:151], v[224:227], v[14:17]
	v_mfma_f32_16x16x32_bf16 v[10:13], v[172:175], v[224:227], v[10:13]
	v_mfma_f32_16x16x32_bf16 v[62:65], v[168:171], v[204:207], v[62:65]
	v_mfma_f32_16x16x32_bf16 v[58:61], v[176:179], v[204:207], v[58:61]
	v_mfma_f32_16x16x32_bf16 v[46:49], v[168:171], v[212:215], v[46:49]
	v_mfma_f32_16x16x32_bf16 v[42:45], v[176:179], v[212:215], v[42:45]
	v_mfma_f32_16x16x32_bf16 v[30:33], v[168:171], v[220:223], v[30:33]
	v_mfma_f32_16x16x32_bf16 v[26:29], v[176:179], v[220:223], v[26:29]
	v_mfma_f32_16x16x32_bf16 v[14:17], v[168:171], v[228:231], v[14:17]
	v_mfma_f32_16x16x32_bf16 v[10:13], v[176:179], v[228:231], v[10:13]
	v_mfma_f32_16x16x32_bf16 v[54:57], v[184:187], v[200:203], v[54:57]
	v_mfma_f32_16x16x32_bf16 v[50:53], v[192:195], v[200:203], v[50:53]
	v_mfma_f32_16x16x32_bf16 v[38:41], v[184:187], v[208:211], v[38:41]
	v_mfma_f32_16x16x32_bf16 v[34:37], v[192:195], v[208:211], v[34:37]
	v_mfma_f32_16x16x32_bf16 v[22:25], v[184:187], v[216:219], v[22:25]
	v_mfma_f32_16x16x32_bf16 v[18:21], v[192:195], v[216:219], v[18:21]
	v_mfma_f32_16x16x32_bf16 v[6:9], v[184:187], v[224:227], v[6:9]
	v_mfma_f32_16x16x32_bf16 v[2:5], v[192:195], v[224:227], v[2:5]
	v_mfma_f32_16x16x32_bf16 v[54:57], v[188:191], v[204:207], v[54:57]
	v_mfma_f32_16x16x32_bf16 v[50:53], v[196:199], v[204:207], v[50:53]
	v_mfma_f32_16x16x32_bf16 v[38:41], v[188:191], v[212:215], v[38:41]
	v_mfma_f32_16x16x32_bf16 v[34:37], v[196:199], v[212:215], v[34:37]
	v_mfma_f32_16x16x32_bf16 v[22:25], v[188:191], v[220:223], v[22:25]
	v_mfma_f32_16x16x32_bf16 v[18:21], v[196:199], v[220:223], v[18:21]
	v_mfma_f32_16x16x32_bf16 v[6:9], v[188:191], v[228:231], v[6:9]
	v_mfma_f32_16x16x32_bf16 v[2:5], v[196:199], v[228:231], v[2:5]
	s_barrier
	s_add_i32 s80, 0, 0x18000
	v_add_u32_e32 v167, s80, v161
	s_add_i32 s81, 0, 0x1c000
	ds_read_b128 v[148:151], v167
	ds_read_b128 v[168:171], v167 offset:1024
	ds_read_b128 v[172:175], v167 offset:2048
	ds_read_b128 v[176:179], v167 offset:3072
	v_add_u32_e32 v167, s81, v161
	ds_read_b128 v[184:187], v167
	ds_read_b128 v[188:191], v167 offset:1024
	ds_read_b128 v[192:195], v167 offset:2048
	ds_read_b128 v[196:199], v167 offset:3072
	s_add_u32 s30, s30, 0x100000
	s_addc_u32 s31, s31, 0
	s_mov_b32 m0, s42
	v_lshl_add_u64 v[236:237], s[30:31], 0, v[130:131]
	ds_read_b128 v[200:203], v166 offset:32768
	ds_read_b128 v[204:207], v166 offset:33792
	ds_read_b128 v[208:211], v166 offset:34816
	ds_read_b128 v[212:215], v166 offset:35840
	ds_read_b128 v[216:219], v166 offset:36864
	ds_read_b128 v[220:223], v166 offset:37888
	ds_read_b128 v[224:227], v166 offset:38912
	ds_read_b128 v[228:231], v166 offset:39936
	global_load_lds_dwordx4 v[236:237], off
	v_lshl_add_u64 v[236:237], s[30:31], 0, v[134:135]
	s_mov_b32 m0, s44
	s_nop 0
	global_load_lds_dwordx4 v[236:237], off
	s_waitcnt vmcnt(8)
	s_waitcnt lgkmcnt(0)
	s_barrier
	s_waitcnt lgkmcnt(0)
	v_mfma_f32_16x16x32_bf16 v[126:129], v[148:151], v[200:203], v[126:129]
	v_mfma_f32_16x16x32_bf16 v[122:125], v[172:175], v[200:203], v[122:125]
	v_mfma_f32_16x16x32_bf16 v[110:113], v[148:151], v[208:211], v[110:113]
	v_mfma_f32_16x16x32_bf16 v[106:109], v[172:175], v[208:211], v[106:109]
	v_mfma_f32_16x16x32_bf16 v[94:97], v[148:151], v[216:219], v[94:97]
	v_mfma_f32_16x16x32_bf16 v[90:93], v[172:175], v[216:219], v[90:93]
	v_mfma_f32_16x16x32_bf16 v[78:81], v[148:151], v[224:227], v[78:81]
	v_mfma_f32_16x16x32_bf16 v[74:77], v[172:175], v[224:227], v[74:77]
	v_mfma_f32_16x16x32_bf16 v[126:129], v[168:171], v[204:207], v[126:129]
	v_mfma_f32_16x16x32_bf16 v[122:125], v[176:179], v[204:207], v[122:125]
	v_mfma_f32_16x16x32_bf16 v[110:113], v[168:171], v[212:215], v[110:113]
	v_mfma_f32_16x16x32_bf16 v[106:109], v[176:179], v[212:215], v[106:109]
	v_mfma_f32_16x16x32_bf16 v[94:97], v[168:171], v[220:223], v[94:97]
	v_mfma_f32_16x16x32_bf16 v[90:93], v[176:179], v[220:223], v[90:93]
	v_mfma_f32_16x16x32_bf16 v[78:81], v[168:171], v[228:231], v[78:81]
	v_mfma_f32_16x16x32_bf16 v[74:77], v[176:179], v[228:231], v[74:77]
	v_mfma_f32_16x16x32_bf16 v[118:121], v[184:187], v[200:203], v[118:121]
	v_mfma_f32_16x16x32_bf16 v[114:117], v[192:195], v[200:203], v[114:117]
	v_mfma_f32_16x16x32_bf16 v[102:105], v[184:187], v[208:211], v[102:105]
	v_mfma_f32_16x16x32_bf16 v[98:101], v[192:195], v[208:211], v[98:101]
	v_mfma_f32_16x16x32_bf16 v[86:89], v[184:187], v[216:219], v[86:89]
	v_mfma_f32_16x16x32_bf16 v[82:85], v[192:195], v[216:219], v[82:85]
	v_mfma_f32_16x16x32_bf16 v[70:73], v[184:187], v[224:227], v[70:73]
	v_mfma_f32_16x16x32_bf16 v[66:69], v[192:195], v[224:227], v[66:69]
	v_mfma_f32_16x16x32_bf16 v[118:121], v[188:191], v[204:207], v[118:121]
	v_mfma_f32_16x16x32_bf16 v[114:117], v[196:199], v[204:207], v[114:117]
	v_mfma_f32_16x16x32_bf16 v[102:105], v[188:191], v[212:215], v[102:105]
	v_mfma_f32_16x16x32_bf16 v[98:101], v[196:199], v[212:215], v[98:101]
	v_mfma_f32_16x16x32_bf16 v[86:89], v[188:191], v[220:223], v[86:89]
	v_mfma_f32_16x16x32_bf16 v[82:85], v[196:199], v[220:223], v[82:85]
	v_mfma_f32_16x16x32_bf16 v[70:73], v[188:191], v[228:231], v[70:73]
	v_mfma_f32_16x16x32_bf16 v[66:69], v[196:199], v[228:231], v[66:69]
	s_barrier
	s_add_i32 s30, s80, s34
	v_lshl_add_u64 v[152:153], v[152:153], 0, s[12:13]
	s_mov_b32 m0, s30
	ds_read_b128 v[200:203], v166 offset:49152
	ds_read_b128 v[204:207], v166 offset:50176
	ds_read_b128 v[208:211], v166 offset:51200
	ds_read_b128 v[212:215], v166 offset:52224
	ds_read_b128 v[216:219], v166 offset:53248
	ds_read_b128 v[220:223], v166 offset:54272
	ds_read_b128 v[224:227], v166 offset:55296
	ds_read_b128 v[228:231], v166 offset:56320
	global_load_lds_dwordx4 v[152:153], off
	s_add_i32 m0, s30, 0x2000
	s_add_u32 s28, s28, 0x100080
	v_lshl_add_u64 v[152:153], v[180:181], 0, s[12:13]
	s_addc_u32 s29, s29, 0
	s_add_i32 s30, s81, s34
	global_load_lds_dwordx4 v[152:153], off
	v_lshl_add_u64 v[152:153], s[28:29], 0, v[132:133]
	s_mov_b32 m0, s30
	s_nop 0
	global_load_lds_dwordx4 v[152:153], off
	v_lshl_add_u64 v[152:153], s[28:29], 0, v[136:137]
	s_add_i32 m0, s30, 0x2000
	s_nop 0
	global_load_lds_dwordx4 v[152:153], off
	v_lshl_add_u64 v[152:153], v[232:233], 0, s[12:13]
	s_mov_b32 m0, s46
	s_nop 0
	global_load_lds_dwordx4 v[152:153], off
	v_lshl_add_u64 v[152:153], v[234:235], 0, s[12:13]
	s_mov_b32 m0, s47
	s_nop 0
	global_load_lds_dwordx4 v[152:153], off
	s_waitcnt vmcnt(8)
	s_waitcnt lgkmcnt(0)
	s_barrier
	s_waitcnt lgkmcnt(0)
	v_mfma_f32_16x16x32_bf16 v[62:65], v[148:151], v[200:203], v[62:65]
	v_mfma_f32_16x16x32_bf16 v[58:61], v[172:175], v[200:203], v[58:61]
	v_mfma_f32_16x16x32_bf16 v[46:49], v[148:151], v[208:211], v[46:49]
	v_mfma_f32_16x16x32_bf16 v[42:45], v[172:175], v[208:211], v[42:45]
	v_mfma_f32_16x16x32_bf16 v[30:33], v[148:151], v[216:219], v[30:33]
	v_mfma_f32_16x16x32_bf16 v[26:29], v[172:175], v[216:219], v[26:29]
	v_mfma_f32_16x16x32_bf16 v[14:17], v[148:151], v[224:227], v[14:17]
	v_mfma_f32_16x16x32_bf16 v[10:13], v[172:175], v[224:227], v[10:13]
	v_mfma_f32_16x16x32_bf16 v[62:65], v[168:171], v[204:207], v[62:65]
	v_mfma_f32_16x16x32_bf16 v[58:61], v[176:179], v[204:207], v[58:61]
	v_mfma_f32_16x16x32_bf16 v[46:49], v[168:171], v[212:215], v[46:49]
	v_mfma_f32_16x16x32_bf16 v[42:45], v[176:179], v[212:215], v[42:45]
	v_mfma_f32_16x16x32_bf16 v[30:33], v[168:171], v[220:223], v[30:33]
	v_mfma_f32_16x16x32_bf16 v[26:29], v[176:179], v[220:223], v[26:29]
	v_mfma_f32_16x16x32_bf16 v[14:17], v[168:171], v[228:231], v[14:17]
	v_mfma_f32_16x16x32_bf16 v[10:13], v[176:179], v[228:231], v[10:13]
	v_mfma_f32_16x16x32_bf16 v[54:57], v[184:187], v[200:203], v[54:57]
	v_mfma_f32_16x16x32_bf16 v[50:53], v[192:195], v[200:203], v[50:53]
	v_mfma_f32_16x16x32_bf16 v[38:41], v[184:187], v[208:211], v[38:41]
	v_mfma_f32_16x16x32_bf16 v[34:37], v[192:195], v[208:211], v[34:37]
	v_mfma_f32_16x16x32_bf16 v[22:25], v[184:187], v[216:219], v[22:25]
	v_mfma_f32_16x16x32_bf16 v[18:21], v[192:195], v[216:219], v[18:21]
	v_mfma_f32_16x16x32_bf16 v[6:9], v[184:187], v[224:227], v[6:9]
	v_mfma_f32_16x16x32_bf16 v[2:5], v[192:195], v[224:227], v[2:5]
	v_mfma_f32_16x16x32_bf16 v[54:57], v[188:191], v[204:207], v[54:57]
	v_mfma_f32_16x16x32_bf16 v[50:53], v[196:199], v[204:207], v[50:53]
	v_mfma_f32_16x16x32_bf16 v[38:41], v[188:191], v[212:215], v[38:41]
	v_mfma_f32_16x16x32_bf16 v[34:37], v[196:199], v[212:215], v[34:37]
	v_mfma_f32_16x16x32_bf16 v[22:25], v[188:191], v[220:223], v[22:25]
	v_mfma_f32_16x16x32_bf16 v[18:21], v[196:199], v[220:223], v[18:21]
	v_mfma_f32_16x16x32_bf16 v[6:9], v[188:191], v[228:231], v[6:9]
	v_mfma_f32_16x16x32_bf16 v[2:5], v[196:199], v[228:231], v[2:5]
	s_barrier
	s_add_i32 s63, s63, 2
	s_add_u32 s26, s26, 0x100
	s_addc_u32 s27, s27, 0
	s_add_u32 s59, s59, 0x100
	s_addc_u32 s62, s62, 0
	s_cmp_gt_u32 s63, 61
	s_cbranch_scc0 .LBB0_237
	s_and_b64 vcc, exec, s[14:15]
	s_cbranch_vccz .LBB0_240
	s_barrier

.LBB0_268:
	s_or_b64 exec, exec, s[30:31]
	v_ashrrev_i32_e32 v147, 31, v146
	v_lshlrev_b64 v[6:7], 21, v[146:147]
	v_ashrrev_i32_e32 v145, 31, v144
	v_lshl_add_u64 v[148:149], s[0:1], 0, v[6:7]
	v_lshlrev_b64 v[6:7], 21, v[144:145]
	v_lshl_add_u64 v[150:151], s[54:55], 0, v[6:7]
	v_cndmask_b32_e64 v154, v2, v150, s[28:29]
	v_lshl_add_u64 v[158:159], v[2:3], 0, s[22:23]
	v_mov_b32_e32 v2, 0
	v_cndmask_b32_e64 v1, v5, v149, s[28:29]
	v_cndmask_b32_e64 v152, v4, v148, s[28:29]
	v_cndmask_b32_e64 v145, v3, v151, s[28:29]
	v_lshl_add_u64 v[156:157], v[4:5], 0, s[16:17]
	s_mov_b32 s30, -2
	v_mov_b32_e32 v3, v2
	v_mov_b32_e32 v4, v2
	v_mov_b32_e32 v5, v2
	v_mov_b32_e32 v6, v2
	v_mov_b32_e32 v7, v2
	v_mov_b32_e32 v8, v2
	v_mov_b32_e32 v9, v2
	v_mov_b32_e32 v10, v2
	v_mov_b32_e32 v11, v2
	v_mov_b32_e32 v12, v2
	v_mov_b32_e32 v13, v2
	v_mov_b32_e32 v18, v2
	v_mov_b32_e32 v19, v2
	v_mov_b32_e32 v20, v2
	v_mov_b32_e32 v21, v2
	s_waitcnt vmcnt(0)
	v_mov_b32_e32 v26, v2
	v_mov_b32_e32 v27, v2
	v_mov_b32_e32 v28, v2
	v_mov_b32_e32 v29, v2
	v_mov_b32_e32 v34, v2
	v_mov_b32_e32 v35, v2
	v_mov_b32_e32 v36, v2
	v_mov_b32_e32 v37, v2
	v_mov_b32_e32 v42, v2
	v_mov_b32_e32 v43, v2
	v_mov_b32_e32 v44, v2
	v_mov_b32_e32 v45, v2
	v_mov_b32_e32 v50, v2
	v_mov_b32_e32 v51, v2
	v_mov_b32_e32 v52, v2
	v_mov_b32_e32 v53, v2
	v_mov_b32_e32 v14, v2
	v_mov_b32_e32 v15, v2
	v_mov_b32_e32 v16, v2
	v_mov_b32_e32 v17, v2
	v_mov_b32_e32 v22, v2
	v_mov_b32_e32 v23, v2
	v_mov_b32_e32 v24, v2
	v_mov_b32_e32 v25, v2
	v_mov_b32_e32 v30, v2
	v_mov_b32_e32 v31, v2
	v_mov_b32_e32 v32, v2
	v_mov_b32_e32 v33, v2
	v_mov_b32_e32 v38, v2
	v_mov_b32_e32 v39, v2
	v_mov_b32_e32 v40, v2
	v_mov_b32_e32 v41, v2
	v_mov_b32_e32 v46, v2
	v_mov_b32_e32 v47, v2
	v_mov_b32_e32 v48, v2
	v_mov_b32_e32 v49, v2
	v_mov_b32_e32 v54, v2
	v_mov_b32_e32 v55, v2
	v_mov_b32_e32 v56, v2
	v_mov_b32_e32 v57, v2
	v_mov_b32_e32 v58, v2
	v_mov_b32_e32 v59, v2
	v_mov_b32_e32 v60, v2
	v_mov_b32_e32 v61, v2
	v_mov_b32_e32 v62, v2
	v_mov_b32_e32 v63, v2
	v_mov_b32_e32 v64, v2
	v_mov_b32_e32 v65, v2
	v_mov_b32_e32 v66, v2
	v_mov_b32_e32 v67, v2
	v_mov_b32_e32 v68, v2
	v_mov_b32_e32 v69, v2
	v_mov_b32_e32 v70, v2
	v_mov_b32_e32 v71, v2
	v_mov_b32_e32 v72, v2
	v_mov_b32_e32 v73, v2
	v_mov_b32_e32 v74, v2
	v_mov_b32_e32 v75, v2
	v_mov_b32_e32 v76, v2
	v_mov_b32_e32 v77, v2
	v_mov_b32_e32 v82, v2
	v_mov_b32_e32 v83, v2
	v_mov_b32_e32 v84, v2
	v_mov_b32_e32 v85, v2
	v_mov_b32_e32 v90, v2
	v_mov_b32_e32 v91, v2
	v_mov_b32_e32 v92, v2
	v_mov_b32_e32 v93, v2
	v_mov_b32_e32 v98, v2
	v_mov_b32_e32 v99, v2
	v_mov_b32_e32 v100, v2
	v_mov_b32_e32 v101, v2
	v_mov_b32_e32 v106, v2
	v_mov_b32_e32 v107, v2
	v_mov_b32_e32 v108, v2
	v_mov_b32_e32 v109, v2
	v_mov_b32_e32 v114, v2
	v_mov_b32_e32 v115, v2
	v_mov_b32_e32 v116, v2
	v_mov_b32_e32 v117, v2
	v_mov_b32_e32 v78, v2
	v_mov_b32_e32 v79, v2
	v_mov_b32_e32 v80, v2
	v_mov_b32_e32 v81, v2
	v_mov_b32_e32 v86, v2
	v_mov_b32_e32 v87, v2
	v_mov_b32_e32 v88, v2
	v_mov_b32_e32 v89, v2
	v_mov_b32_e32 v94, v2
	v_mov_b32_e32 v95, v2
	v_mov_b32_e32 v96, v2
	v_mov_b32_e32 v97, v2
	v_mov_b32_e32 v102, v2
	v_mov_b32_e32 v103, v2
	v_mov_b32_e32 v104, v2
	v_mov_b32_e32 v105, v2
	v_mov_b32_e32 v110, v2
	v_mov_b32_e32 v111, v2
	v_mov_b32_e32 v112, v2
	v_mov_b32_e32 v113, v2
	v_mov_b32_e32 v118, v2
	v_mov_b32_e32 v119, v2
	v_mov_b32_e32 v120, v2
	v_mov_b32_e32 v121, v2
	v_mov_b32_e32 v122, v2
	v_mov_b32_e32 v123, v2
	v_mov_b32_e32 v124, v2
	v_mov_b32_e32 v125, v2
	v_mov_b32_e32 v126, v2
	v_mov_b32_e32 v127, v2
	v_mov_b32_e32 v128, v2
	v_mov_b32_e32 v129, v2
	s_setprio 0
.LBB0_269:
	v_add_u32_e32 v147, s46, v161
	ds_read_b128 v[166:169], v147
	ds_read_b128 v[170:173], v147 offset:1024
	ds_read_b128 v[174:177], v147 offset:2048
	ds_read_b128 v[178:181], v147 offset:3072
	v_add_u32_e32 v147, s47, v161
	ds_read_b128 v[184:187], v147
	ds_read_b128 v[188:191], v147 offset:1024
	ds_read_b128 v[192:195], v147 offset:2048
	ds_read_b128 v[196:199], v147 offset:3072
	s_mov_b32 s34, 0xfff00080
	s_cmp_eq_u32 s30, 60
	s_mov_b32 s35, -1
	v_lshl_add_u64 v[200:201], v[156:157], 0, s[34:35]
	s_cselect_b64 vcc, -1, 0
	v_cndmask_b32_e32 v233, v201, v1, vcc
	v_cndmask_b32_e32 v232, v200, v152, vcc
	v_cndmask_b32_e32 v235, v159, v145, vcc
	v_cndmask_b32_e32 v234, v158, v154, vcc
	v_lshl_add_u64 v[236:237], v[156:157], 0, v[138:139]
	s_add_i32 m0, s39, 0xc000
	ds_read_b128 v[200:203], v155
	ds_read_b128 v[204:207], v155 offset:1024
	ds_read_b128 v[208:211], v155 offset:2048
	ds_read_b128 v[212:215], v155 offset:3072
	ds_read_b128 v[216:219], v155 offset:4096
	ds_read_b128 v[220:223], v155 offset:5120
	ds_read_b128 v[224:227], v155 offset:6144
	ds_read_b128 v[228:231], v155 offset:7168
	global_load_lds_dwordx4 v[236:237], off
	v_lshl_add_u64 v[236:237], v[156:157], 0, v[140:141]
	s_add_i32 m0, s39, 0xe000
	s_nop 0
	global_load_lds_dwordx4 v[236:237], off
	s_waitcnt vmcnt(8)
	s_waitcnt lgkmcnt(0)
	s_barrier
	s_waitcnt lgkmcnt(0)
	v_mfma_f32_16x16x32_bf16 v[126:129], v[166:169], v[200:203], v[126:129]
	v_mfma_f32_16x16x32_bf16 v[122:125], v[174:177], v[200:203], v[122:125]
	v_mfma_f32_16x16x32_bf16 v[118:121], v[166:169], v[208:211], v[118:121]
	v_mfma_f32_16x16x32_bf16 v[110:113], v[174:177], v[208:211], v[110:113]
	v_mfma_f32_16x16x32_bf16 v[102:105], v[166:169], v[216:219], v[102:105]
	v_mfma_f32_16x16x32_bf16 v[94:97], v[174:177], v[216:219], v[94:97]
	v_mfma_f32_16x16x32_bf16 v[86:89], v[166:169], v[224:227], v[86:89]
	v_mfma_f32_16x16x32_bf16 v[78:81], v[174:177], v[224:227], v[78:81]
	v_mfma_f32_16x16x32_bf16 v[126:129], v[170:173], v[204:207], v[126:129]
	v_mfma_f32_16x16x32_bf16 v[122:125], v[178:181], v[204:207], v[122:125]
	v_mfma_f32_16x16x32_bf16 v[118:121], v[170:173], v[212:215], v[118:121]
	v_mfma_f32_16x16x32_bf16 v[110:113], v[178:181], v[212:215], v[110:113]
	v_mfma_f32_16x16x32_bf16 v[102:105], v[170:173], v[220:223], v[102:105]
	v_mfma_f32_16x16x32_bf16 v[94:97], v[178:181], v[220:223], v[94:97]
	v_mfma_f32_16x16x32_bf16 v[86:89], v[170:173], v[228:231], v[86:89]
	v_mfma_f32_16x16x32_bf16 v[78:81], v[178:181], v[228:231], v[78:81]
	v_mfma_f32_16x16x32_bf16 v[114:117], v[184:187], v[200:203], v[114:117]
	v_mfma_f32_16x16x32_bf16 v[106:109], v[192:195], v[200:203], v[106:109]
	v_mfma_f32_16x16x32_bf16 v[98:101], v[184:187], v[208:211], v[98:101]
	v_mfma_f32_16x16x32_bf16 v[90:93], v[192:195], v[208:211], v[90:93]
	v_mfma_f32_16x16x32_bf16 v[82:85], v[184:187], v[216:219], v[82:85]
	v_mfma_f32_16x16x32_bf16 v[74:77], v[192:195], v[216:219], v[74:77]
	v_mfma_f32_16x16x32_bf16 v[70:73], v[184:187], v[224:227], v[70:73]
	v_mfma_f32_16x16x32_bf16 v[66:69], v[192:195], v[224:227], v[66:69]
	v_mfma_f32_16x16x32_bf16 v[114:117], v[188:191], v[204:207], v[114:117]
	v_mfma_f32_16x16x32_bf16 v[106:109], v[196:199], v[204:207], v[106:109]
	v_mfma_f32_16x16x32_bf16 v[98:101], v[188:191], v[212:215], v[98:101]
	v_mfma_f32_16x16x32_bf16 v[90:93], v[196:199], v[212:215], v[90:93]
	v_mfma_f32_16x16x32_bf16 v[82:85], v[188:191], v[220:223], v[82:85]
	v_mfma_f32_16x16x32_bf16 v[74:77], v[196:199], v[220:223], v[74:77]
	v_mfma_f32_16x16x32_bf16 v[70:73], v[188:191], v[228:231], v[70:73]
	v_mfma_f32_16x16x32_bf16 v[66:69], v[196:199], v[228:231], v[66:69]
	s_barrier
	s_add_i32 s31, s46, s38
	v_lshl_add_u64 v[236:237], v[234:235], 0, v[132:133]
	s_mov_b32 m0, s31
	ds_read_b128 v[200:203], v155 offset:16384
	ds_read_b128 v[204:207], v155 offset:17408
	ds_read_b128 v[208:211], v155 offset:18432
	ds_read_b128 v[212:215], v155 offset:19456
	ds_read_b128 v[216:219], v155 offset:20480
	ds_read_b128 v[220:223], v155 offset:21504
	ds_read_b128 v[224:227], v155 offset:22528
	ds_read_b128 v[228:231], v155 offset:23552
	global_load_lds_dwordx4 v[236:237], off
	v_lshl_add_u64 v[238:239], v[234:235], 0, v[136:137]
	s_add_i32 m0, s31, 0x2000
	v_lshl_add_u64 v[240:241], v[234:235], 0, s[6:7]
	s_add_i32 s31, s47, s38
	global_load_lds_dwordx4 v[238:239], off
	v_lshl_add_u64 v[242:243], v[240:241], 0, v[132:133]
	s_mov_b32 m0, s31
	v_lshl_add_u64 v[240:241], v[240:241], 0, v[136:137]
	global_load_lds_dwordx4 v[242:243], off
	s_add_i32 m0, s31, 0x2000
	v_lshl_add_u64 v[242:243], v[232:233], 0, v[134:135]
	global_load_lds_dwordx4 v[240:241], off
	v_lshl_add_u64 v[240:241], v[232:233], 0, v[130:131]
	s_mov_b32 m0, s39
	s_nop 0
	global_load_lds_dwordx4 v[240:241], off
	s_mov_b32 m0, s40
	s_nop 0
	global_load_lds_dwordx4 v[242:243], off
	s_waitcnt vmcnt(8)
	s_waitcnt lgkmcnt(0)
	s_barrier
	s_waitcnt lgkmcnt(0)
	v_mfma_f32_16x16x32_bf16 v[62:65], v[166:169], v[200:203], v[62:65]
	v_mfma_f32_16x16x32_bf16 v[58:61], v[174:177], v[200:203], v[58:61]
	v_mfma_f32_16x16x32_bf16 v[54:57], v[166:169], v[208:211], v[54:57]
	v_mfma_f32_16x16x32_bf16 v[46:49], v[174:177], v[208:211], v[46:49]
	v_mfma_f32_16x16x32_bf16 v[38:41], v[166:169], v[216:219], v[38:41]
	v_mfma_f32_16x16x32_bf16 v[30:33], v[174:177], v[216:219], v[30:33]
	v_mfma_f32_16x16x32_bf16 v[22:25], v[166:169], v[224:227], v[22:25]
	v_mfma_f32_16x16x32_bf16 v[14:17], v[174:177], v[224:227], v[14:17]
	v_mfma_f32_16x16x32_bf16 v[62:65], v[170:173], v[204:207], v[62:65]
	v_mfma_f32_16x16x32_bf16 v[58:61], v[178:181], v[204:207], v[58:61]
	v_mfma_f32_16x16x32_bf16 v[54:57], v[170:173], v[212:215], v[54:57]
	v_mfma_f32_16x16x32_bf16 v[46:49], v[178:181], v[212:215], v[46:49]
	v_mfma_f32_16x16x32_bf16 v[38:41], v[170:173], v[220:223], v[38:41]
	v_mfma_f32_16x16x32_bf16 v[30:33], v[178:181], v[220:223], v[30:33]
	v_mfma_f32_16x16x32_bf16 v[22:25], v[170:173], v[228:231], v[22:25]
	v_mfma_f32_16x16x32_bf16 v[14:17], v[178:181], v[228:231], v[14:17]
	v_mfma_f32_16x16x32_bf16 v[50:53], v[184:187], v[200:203], v[50:53]
	v_mfma_f32_16x16x32_bf16 v[42:45], v[192:195], v[200:203], v[42:45]
	v_mfma_f32_16x16x32_bf16 v[34:37], v[184:187], v[208:211], v[34:37]
	v_mfma_f32_16x16x32_bf16 v[26:29], v[192:195], v[208:211], v[26:29]
	v_mfma_f32_16x16x32_bf16 v[18:21], v[184:187], v[216:219], v[18:21]
	v_mfma_f32_16x16x32_bf16 v[10:13], v[192:195], v[216:219], v[10:13]
	v_mfma_f32_16x16x32_bf16 v[6:9], v[184:187], v[224:227], v[6:9]
	v_mfma_f32_16x16x32_bf16 v[2:5], v[192:195], v[224:227], v[2:5]
	v_mfma_f32_16x16x32_bf16 v[50:53], v[188:191], v[204:207], v[50:53]
	v_mfma_f32_16x16x32_bf16 v[42:45], v[196:199], v[204:207], v[42:45]
	v_mfma_f32_16x16x32_bf16 v[34:37], v[188:191], v[212:215], v[34:37]
	v_mfma_f32_16x16x32_bf16 v[26:29], v[196:199], v[212:215], v[26:29]
	v_mfma_f32_16x16x32_bf16 v[18:21], v[188:191], v[220:223], v[18:21]
	v_mfma_f32_16x16x32_bf16 v[10:13], v[196:199], v[220:223], v[10:13]
	v_mfma_f32_16x16x32_bf16 v[6:9], v[188:191], v[228:231], v[6:9]
	v_mfma_f32_16x16x32_bf16 v[2:5], v[196:199], v[228:231], v[2:5]
	s_barrier
	s_add_i32 s31, 0, 0x18000
	v_add_u32_e32 v147, s31, v161
	s_add_i32 s34, 0, 0x1c000
	ds_read_b128 v[166:169], v147
	ds_read_b128 v[170:173], v147 offset:1024
	ds_read_b128 v[174:177], v147 offset:2048
	ds_read_b128 v[178:181], v147 offset:3072
	v_add_u32_e32 v147, s34, v161
	ds_read_b128 v[184:187], v147
	ds_read_b128 v[188:191], v147 offset:1024
	ds_read_b128 v[192:195], v147 offset:2048
	ds_read_b128 v[196:199], v147 offset:3072
	v_lshl_add_u64 v[232:233], v[232:233], 0, s[6:7]
	s_mov_b32 m0, s41
	v_lshl_add_u64 v[244:245], v[232:233], 0, v[130:131]
	ds_read_b128 v[200:203], v155 offset:32768
	ds_read_b128 v[204:207], v155 offset:33792
	ds_read_b128 v[208:211], v155 offset:34816
	ds_read_b128 v[212:215], v155 offset:35840
	ds_read_b128 v[216:219], v155 offset:36864
	ds_read_b128 v[220:223], v155 offset:37888
	ds_read_b128 v[224:227], v155 offset:38912
	ds_read_b128 v[228:231], v155 offset:39936
	global_load_lds_dwordx4 v[244:245], off
	v_lshl_add_u64 v[232:233], v[232:233], 0, v[134:135]
	s_mov_b32 m0, s42
	s_nop 0
	global_load_lds_dwordx4 v[232:233], off
	s_waitcnt vmcnt(8)
	s_waitcnt lgkmcnt(0)
	s_barrier
	s_waitcnt lgkmcnt(0)
	v_mfma_f32_16x16x32_bf16 v[126:129], v[166:169], v[200:203], v[126:129]
	v_mfma_f32_16x16x32_bf16 v[122:125], v[174:177], v[200:203], v[122:125]
	v_mfma_f32_16x16x32_bf16 v[118:121], v[166:169], v[208:211], v[118:121]
	v_mfma_f32_16x16x32_bf16 v[110:113], v[174:177], v[208:211], v[110:113]
	v_mfma_f32_16x16x32_bf16 v[102:105], v[166:169], v[216:219], v[102:105]
	v_mfma_f32_16x16x32_bf16 v[94:97], v[174:177], v[216:219], v[94:97]
	v_mfma_f32_16x16x32_bf16 v[86:89], v[166:169], v[224:227], v[86:89]
	v_mfma_f32_16x16x32_bf16 v[78:81], v[174:177], v[224:227], v[78:81]
	v_mfma_f32_16x16x32_bf16 v[126:129], v[170:173], v[204:207], v[126:129]
	v_mfma_f32_16x16x32_bf16 v[122:125], v[178:181], v[204:207], v[122:125]
	v_mfma_f32_16x16x32_bf16 v[118:121], v[170:173], v[212:215], v[118:121]
	v_mfma_f32_16x16x32_bf16 v[110:113], v[178:181], v[212:215], v[110:113]
	v_mfma_f32_16x16x32_bf16 v[102:105], v[170:173], v[220:223], v[102:105]
	v_mfma_f32_16x16x32_bf16 v[94:97], v[178:181], v[220:223], v[94:97]
	v_mfma_f32_16x16x32_bf16 v[86:89], v[170:173], v[228:231], v[86:89]
	v_mfma_f32_16x16x32_bf16 v[78:81], v[178:181], v[228:231], v[78:81]
	v_mfma_f32_16x16x32_bf16 v[114:117], v[184:187], v[200:203], v[114:117]
	v_mfma_f32_16x16x32_bf16 v[106:109], v[192:195], v[200:203], v[106:109]
	v_mfma_f32_16x16x32_bf16 v[98:101], v[184:187], v[208:211], v[98:101]
	v_mfma_f32_16x16x32_bf16 v[90:93], v[192:195], v[208:211], v[90:93]
	v_mfma_f32_16x16x32_bf16 v[82:85], v[184:187], v[216:219], v[82:85]
	v_mfma_f32_16x16x32_bf16 v[74:77], v[192:195], v[216:219], v[74:77]
	v_mfma_f32_16x16x32_bf16 v[70:73], v[184:187], v[224:227], v[70:73]
	v_mfma_f32_16x16x32_bf16 v[66:69], v[192:195], v[224:227], v[66:69]
	v_mfma_f32_16x16x32_bf16 v[114:117], v[188:191], v[204:207], v[114:117]
	v_mfma_f32_16x16x32_bf16 v[106:109], v[196:199], v[204:207], v[106:109]
	v_mfma_f32_16x16x32_bf16 v[98:101], v[188:191], v[212:215], v[98:101]
	v_mfma_f32_16x16x32_bf16 v[90:93], v[196:199], v[212:215], v[90:93]
	v_mfma_f32_16x16x32_bf16 v[82:85], v[188:191], v[220:223], v[82:85]
	v_mfma_f32_16x16x32_bf16 v[74:77], v[196:199], v[220:223], v[74:77]
	v_mfma_f32_16x16x32_bf16 v[70:73], v[188:191], v[228:231], v[70:73]
	v_mfma_f32_16x16x32_bf16 v[66:69], v[196:199], v[228:231], v[66:69]
	s_barrier
	s_add_i32 s31, s31, s38
	v_lshl_add_u64 v[232:233], v[236:237], 0, s[12:13]
	s_mov_b32 m0, s31
	ds_read_b128 v[200:203], v155 offset:49152
	ds_read_b128 v[204:207], v155 offset:50176
	ds_read_b128 v[208:211], v155 offset:51200
	ds_read_b128 v[212:215], v155 offset:52224
	ds_read_b128 v[216:219], v155 offset:53248
	ds_read_b128 v[220:223], v155 offset:54272
	ds_read_b128 v[224:227], v155 offset:55296
	ds_read_b128 v[228:231], v155 offset:56320
	global_load_lds_dwordx4 v[232:233], off
	v_lshl_add_u64 v[232:233], v[238:239], 0, s[12:13]
	s_add_i32 m0, s31, 0x2000
	s_add_i32 s31, s34, s38
	global_load_lds_dwordx4 v[232:233], off
	v_lshl_add_u64 v[232:233], v[234:235], 0, s[16:17]
	v_lshl_add_u64 v[234:235], v[232:233], 0, v[132:133]
	s_mov_b32 m0, s31
	v_lshl_add_u64 v[232:233], v[232:233], 0, v[136:137]
	global_load_lds_dwordx4 v[234:235], off
	s_add_i32 m0, s31, 0x2000
	s_nop 0
	global_load_lds_dwordx4 v[232:233], off
	v_lshl_add_u64 v[232:233], v[240:241], 0, s[12:13]
	s_mov_b32 m0, s44
	s_nop 0
	global_load_lds_dwordx4 v[232:233], off
	v_lshl_add_u64 v[232:233], v[242:243], 0, s[12:13]
	s_mov_b32 m0, s45
	s_nop 0
	global_load_lds_dwordx4 v[232:233], off
	s_waitcnt vmcnt(8)
	s_waitcnt lgkmcnt(0)
	s_barrier
	s_waitcnt lgkmcnt(0)
	v_mfma_f32_16x16x32_bf16 v[62:65], v[166:169], v[200:203], v[62:65]
	v_mfma_f32_16x16x32_bf16 v[58:61], v[174:177], v[200:203], v[58:61]
	v_mfma_f32_16x16x32_bf16 v[54:57], v[166:169], v[208:211], v[54:57]
	v_mfma_f32_16x16x32_bf16 v[46:49], v[174:177], v[208:211], v[46:49]
	v_mfma_f32_16x16x32_bf16 v[38:41], v[166:169], v[216:219], v[38:41]
	v_mfma_f32_16x16x32_bf16 v[30:33], v[174:177], v[216:219], v[30:33]
	v_mfma_f32_16x16x32_bf16 v[22:25], v[166:169], v[224:227], v[22:25]
	v_mfma_f32_16x16x32_bf16 v[14:17], v[174:177], v[224:227], v[14:17]
	v_mfma_f32_16x16x32_bf16 v[62:65], v[170:173], v[204:207], v[62:65]
	v_mfma_f32_16x16x32_bf16 v[58:61], v[178:181], v[204:207], v[58:61]
	v_mfma_f32_16x16x32_bf16 v[54:57], v[170:173], v[212:215], v[54:57]
	v_mfma_f32_16x16x32_bf16 v[46:49], v[178:181], v[212:215], v[46:49]
	v_mfma_f32_16x16x32_bf16 v[38:41], v[170:173], v[220:223], v[38:41]
	v_mfma_f32_16x16x32_bf16 v[30:33], v[178:181], v[220:223], v[30:33]
	v_mfma_f32_16x16x32_bf16 v[22:25], v[170:173], v[228:231], v[22:25]
	v_mfma_f32_16x16x32_bf16 v[14:17], v[178:181], v[228:231], v[14:17]
	v_mfma_f32_16x16x32_bf16 v[50:53], v[184:187], v[200:203], v[50:53]
	v_mfma_f32_16x16x32_bf16 v[42:45], v[192:195], v[200:203], v[42:45]
	v_mfma_f32_16x16x32_bf16 v[34:37], v[184:187], v[208:211], v[34:37]
	v_mfma_f32_16x16x32_bf16 v[26:29], v[192:195], v[208:211], v[26:29]
	v_mfma_f32_16x16x32_bf16 v[18:21], v[184:187], v[216:219], v[18:21]
	v_mfma_f32_16x16x32_bf16 v[10:13], v[192:195], v[216:219], v[10:13]
	v_mfma_f32_16x16x32_bf16 v[6:9], v[184:187], v[224:227], v[6:9]
	v_mfma_f32_16x16x32_bf16 v[2:5], v[192:195], v[224:227], v[2:5]
	v_mfma_f32_16x16x32_bf16 v[50:53], v[188:191], v[204:207], v[50:53]
	v_mfma_f32_16x16x32_bf16 v[42:45], v[196:199], v[204:207], v[42:45]
	v_mfma_f32_16x16x32_bf16 v[34:37], v[188:191], v[212:215], v[34:37]
	v_mfma_f32_16x16x32_bf16 v[26:29], v[196:199], v[212:215], v[26:29]
	v_mfma_f32_16x16x32_bf16 v[18:21], v[188:191], v[220:223], v[18:21]
	v_mfma_f32_16x16x32_bf16 v[10:13], v[196:199], v[220:223], v[10:13]
	v_mfma_f32_16x16x32_bf16 v[6:9], v[188:191], v[228:231], v[6:9]
	v_mfma_f32_16x16x32_bf16 v[2:5], v[196:199], v[228:231], v[2:5]
	s_barrier
	s_add_i32 s30, s30, 2
	v_lshl_add_u64 v[156:157], v[156:157], 0, s[22:23]
	s_cmp_gt_u32 s30, 61
	v_lshl_add_u64 v[158:159], v[158:159], 0, s[22:23]
	s_cbranch_scc0 .LBB0_269
	s_and_b64 vcc, exec, s[18:19]
	s_cbranch_vccz .LBB0_272
	s_barrier

.LBB0_762:
	s_ashr_i32 s19, s18, 31
	s_lshl_b64 s[20:21], s[18:19], 22
	s_add_u32 s20, s34, s20
	s_addc_u32 s21, s35, s21
	s_and_b64 s[22:23], s[0:1], exec
	s_cselect_b32 s19, s21, s27
	s_cselect_b32 s53, s20, s26
	s_ashr_i32 s17, s16, 31
	s_lshl_b64 s[22:23], s[16:17], 22
	s_add_u32 s22, s36, s22
	s_addc_u32 s23, s37, s23
	s_and_b64 s[30:31], s[0:1], exec
	s_cselect_b32 s17, s23, s29
	s_cselect_b32 s56, s22, s28
	s_add_u32 s26, s26, 0x200080
	s_addc_u32 s27, s27, 0
	s_add_u32 s57, s28, 0x100
	v_mov_b32_e32 v2, 0
	s_addc_u32 s58, s29, 0
	s_mov_b32 s59, -2
	v_mov_b32_e32 v3, v2
	v_mov_b32_e32 v4, v2
	v_mov_b32_e32 v5, v2
	v_mov_b32_e32 v6, v2
	v_mov_b32_e32 v7, v2
	v_mov_b32_e32 v8, v2
	v_mov_b32_e32 v9, v2
	v_mov_b32_e32 v14, v2
	v_mov_b32_e32 v15, v2
	v_mov_b32_e32 v16, v2
	v_mov_b32_e32 v17, v2
	v_mov_b32_e32 v22, v2
	v_mov_b32_e32 v23, v2
	v_mov_b32_e32 v24, v2
	v_mov_b32_e32 v25, v2
	v_mov_b32_e32 v30, v2
	v_mov_b32_e32 v31, v2
	v_mov_b32_e32 v32, v2
	v_mov_b32_e32 v33, v2
	v_mov_b32_e32 v38, v2
	v_mov_b32_e32 v39, v2
	v_mov_b32_e32 v40, v2
	v_mov_b32_e32 v41, v2
	v_mov_b32_e32 v46, v2
	v_mov_b32_e32 v47, v2
	v_mov_b32_e32 v48, v2
	v_mov_b32_e32 v49, v2
	v_mov_b32_e32 v54, v2
	v_mov_b32_e32 v55, v2
	v_mov_b32_e32 v56, v2
	v_mov_b32_e32 v57, v2
	v_mov_b32_e32 v10, v2
	v_mov_b32_e32 v11, v2
	v_mov_b32_e32 v12, v2
	v_mov_b32_e32 v13, v2
	v_mov_b32_e32 v18, v2
	v_mov_b32_e32 v19, v2
	v_mov_b32_e32 v20, v2
	v_mov_b32_e32 v21, v2
	v_mov_b32_e32 v26, v2
	v_mov_b32_e32 v27, v2
	v_mov_b32_e32 v28, v2
	v_mov_b32_e32 v29, v2
	v_mov_b32_e32 v34, v2
	v_mov_b32_e32 v35, v2
	v_mov_b32_e32 v36, v2
	v_mov_b32_e32 v37, v2
	v_mov_b32_e32 v42, v2
	v_mov_b32_e32 v43, v2
	v_mov_b32_e32 v44, v2
	v_mov_b32_e32 v45, v2
	v_mov_b32_e32 v50, v2
	v_mov_b32_e32 v51, v2
	v_mov_b32_e32 v52, v2
	v_mov_b32_e32 v53, v2
	v_mov_b32_e32 v58, v2
	v_mov_b32_e32 v59, v2
	v_mov_b32_e32 v60, v2
	v_mov_b32_e32 v61, v2
	v_mov_b32_e32 v62, v2
	v_mov_b32_e32 v63, v2
	v_mov_b32_e32 v64, v2
	v_mov_b32_e32 v65, v2
	v_mov_b32_e32 v66, v2
	v_mov_b32_e32 v67, v2
	v_mov_b32_e32 v68, v2
	v_mov_b32_e32 v69, v2
	v_mov_b32_e32 v70, v2
	v_mov_b32_e32 v71, v2
	v_mov_b32_e32 v72, v2
	v_mov_b32_e32 v73, v2
	v_mov_b32_e32 v78, v2
	v_mov_b32_e32 v79, v2
	v_mov_b32_e32 v80, v2
	v_mov_b32_e32 v81, v2
	v_mov_b32_e32 v86, v2
	v_mov_b32_e32 v87, v2
	v_mov_b32_e32 v88, v2
	v_mov_b32_e32 v89, v2
	v_mov_b32_e32 v94, v2
	v_mov_b32_e32 v95, v2
	v_mov_b32_e32 v96, v2
	v_mov_b32_e32 v97, v2
	v_mov_b32_e32 v102, v2
	v_mov_b32_e32 v103, v2
	v_mov_b32_e32 v104, v2
	v_mov_b32_e32 v105, v2
	v_mov_b32_e32 v110, v2
	v_mov_b32_e32 v111, v2
	v_mov_b32_e32 v112, v2
	v_mov_b32_e32 v113, v2
	v_mov_b32_e32 v118, v2
	v_mov_b32_e32 v119, v2
	v_mov_b32_e32 v120, v2
	v_mov_b32_e32 v121, v2
	v_mov_b32_e32 v74, v2
	v_mov_b32_e32 v75, v2
	v_mov_b32_e32 v76, v2
	v_mov_b32_e32 v77, v2
	v_mov_b32_e32 v82, v2
	v_mov_b32_e32 v83, v2
	v_mov_b32_e32 v84, v2
	v_mov_b32_e32 v85, v2
	v_mov_b32_e32 v90, v2
	v_mov_b32_e32 v91, v2
	v_mov_b32_e32 v92, v2
	v_mov_b32_e32 v93, v2
	v_mov_b32_e32 v98, v2
	v_mov_b32_e32 v99, v2
	v_mov_b32_e32 v100, v2
	v_mov_b32_e32 v101, v2
	v_mov_b32_e32 v106, v2
	v_mov_b32_e32 v107, v2
	v_mov_b32_e32 v108, v2
	v_mov_b32_e32 v109, v2
	v_mov_b32_e32 v114, v2
	v_mov_b32_e32 v115, v2
	v_mov_b32_e32 v116, v2
	v_mov_b32_e32 v117, v2
	v_mov_b32_e32 v122, v2
	v_mov_b32_e32 v123, v2
	v_mov_b32_e32 v124, v2
	v_mov_b32_e32 v125, v2
	v_mov_b32_e32 v126, v2
	v_mov_b32_e32 v127, v2
	v_mov_b32_e32 v128, v2
	v_mov_b32_e32 v129, v2
	s_setprio 0
.LBB0_763:
	ds_read_b128 v[142:145], v165
	ds_read_b128 v[146:149], v165 offset:1024
	ds_read_b128 v[150:153], v165 offset:2048
	ds_read_b128 v[154:157], v165 offset:3072
	ds_read_b128 v[158:161], v166
	ds_read_b128 v[168:171], v166 offset:1024
	ds_read_b128 v[172:175], v166 offset:2048
	ds_read_b128 v[176:179], v166 offset:3072
	s_add_u32 s28, s26, 0xffe00080
	s_addc_u32 s29, s27, -1
	s_cmpk_eq_i32 s59, 0x7c
	s_cselect_b32 s31, s19, s29
	s_cselect_b32 s30, s53, s28
	s_cselect_b32 s29, s17, s58
	s_cselect_b32 s28, s56, s57
	v_lshl_add_u64 v[180:181], s[26:27], 0, v[134:135]
	s_add_i32 m0, s25, 0xc000
	ds_read_b128 v[184:187], v167
	ds_read_b128 v[188:191], v167 offset:1024
	ds_read_b128 v[192:195], v167 offset:2048
	ds_read_b128 v[196:199], v167 offset:3072
	ds_read_b128 v[200:203], v167 offset:4096
	ds_read_b128 v[204:207], v167 offset:5120
	ds_read_b128 v[208:211], v167 offset:6144
	ds_read_b128 v[212:215], v167 offset:7168
	global_load_lds_dwordx4 v[180:181], off
	v_lshl_add_u64 v[180:181], s[26:27], 0, v[136:137]
	s_add_i32 m0, s25, 0xe000
	s_nop 0
	global_load_lds_dwordx4 v[180:181], off
	s_waitcnt vmcnt(8)
	s_waitcnt lgkmcnt(0)
	s_barrier
	s_waitcnt lgkmcnt(0)
	v_mfma_f32_16x16x32_bf16 v[126:129], v[142:145], v[184:187], v[126:129]
	v_mfma_f32_16x16x32_bf16 v[122:125], v[150:153], v[184:187], v[122:125]
	v_mfma_f32_16x16x32_bf16 v[114:117], v[142:145], v[192:195], v[114:117]
	v_mfma_f32_16x16x32_bf16 v[106:109], v[150:153], v[192:195], v[106:109]
	v_mfma_f32_16x16x32_bf16 v[98:101], v[142:145], v[200:203], v[98:101]
	v_mfma_f32_16x16x32_bf16 v[90:93], v[150:153], v[200:203], v[90:93]
	v_mfma_f32_16x16x32_bf16 v[82:85], v[142:145], v[208:211], v[82:85]
	v_mfma_f32_16x16x32_bf16 v[74:77], v[150:153], v[208:211], v[74:77]
	v_mfma_f32_16x16x32_bf16 v[126:129], v[146:149], v[188:191], v[126:129]
	v_mfma_f32_16x16x32_bf16 v[122:125], v[154:157], v[188:191], v[122:125]
	v_mfma_f32_16x16x32_bf16 v[114:117], v[146:149], v[196:199], v[114:117]
	v_mfma_f32_16x16x32_bf16 v[106:109], v[154:157], v[196:199], v[106:109]
	v_mfma_f32_16x16x32_bf16 v[98:101], v[146:149], v[204:207], v[98:101]
	v_mfma_f32_16x16x32_bf16 v[90:93], v[154:157], v[204:207], v[90:93]
	v_mfma_f32_16x16x32_bf16 v[82:85], v[146:149], v[212:215], v[82:85]
	v_mfma_f32_16x16x32_bf16 v[74:77], v[154:157], v[212:215], v[74:77]
	v_mfma_f32_16x16x32_bf16 v[118:121], v[158:161], v[184:187], v[118:121]
	v_mfma_f32_16x16x32_bf16 v[110:113], v[172:175], v[184:187], v[110:113]
	v_mfma_f32_16x16x32_bf16 v[102:105], v[158:161], v[192:195], v[102:105]
	v_mfma_f32_16x16x32_bf16 v[94:97], v[172:175], v[192:195], v[94:97]
	v_mfma_f32_16x16x32_bf16 v[86:89], v[158:161], v[200:203], v[86:89]
	v_mfma_f32_16x16x32_bf16 v[78:81], v[172:175], v[200:203], v[78:81]
	v_mfma_f32_16x16x32_bf16 v[70:73], v[158:161], v[208:211], v[70:73]
	v_mfma_f32_16x16x32_bf16 v[66:69], v[172:175], v[208:211], v[66:69]
	v_mfma_f32_16x16x32_bf16 v[118:121], v[168:171], v[188:191], v[118:121]
	v_mfma_f32_16x16x32_bf16 v[110:113], v[176:179], v[188:191], v[110:113]
	v_mfma_f32_16x16x32_bf16 v[102:105], v[168:171], v[196:199], v[102:105]
	v_mfma_f32_16x16x32_bf16 v[94:97], v[176:179], v[196:199], v[94:97]
	v_mfma_f32_16x16x32_bf16 v[86:89], v[168:171], v[204:207], v[86:89]
	v_mfma_f32_16x16x32_bf16 v[78:81], v[176:179], v[204:207], v[78:81]
	v_mfma_f32_16x16x32_bf16 v[70:73], v[168:171], v[212:215], v[70:73]
	v_mfma_f32_16x16x32_bf16 v[66:69], v[176:179], v[212:215], v[66:69]
	s_barrier
	s_add_i32 s60, s50, s38
	v_lshl_add_u64 v[180:181], s[28:29], 0, v[130:131]
	s_mov_b32 m0, s60
	ds_read_b128 v[184:187], v167 offset:16384
	ds_read_b128 v[188:191], v167 offset:17408
	ds_read_b128 v[192:195], v167 offset:18432
	ds_read_b128 v[196:199], v167 offset:19456
	ds_read_b128 v[200:203], v167 offset:20480
	ds_read_b128 v[204:207], v167 offset:21504
	ds_read_b128 v[208:211], v167 offset:22528
	ds_read_b128 v[212:215], v167 offset:23552
	global_load_lds_dwordx4 v[180:181], off
	s_add_i32 m0, s60, 0x2000
	s_add_u32 s60, s28, 0x200000
	v_lshl_add_u64 v[216:217], s[28:29], 0, v[132:133]
	s_addc_u32 s61, s29, 0
	s_add_i32 s62, s51, s38
	global_load_lds_dwordx4 v[216:217], off
	v_lshl_add_u64 v[218:219], s[60:61], 0, v[130:131]
	s_mov_b32 m0, s62
	v_lshl_add_u64 v[220:221], s[30:31], 0, v[132:133]
	global_load_lds_dwordx4 v[218:219], off
	v_lshl_add_u64 v[218:219], s[60:61], 0, v[132:133]
	s_add_i32 m0, s62, 0x2000
	s_nop 0
	global_load_lds_dwordx4 v[218:219], off
	v_lshl_add_u64 v[218:219], s[30:31], 0, v[130:131]
	s_mov_b32 m0, s25
	s_nop 0
	global_load_lds_dwordx4 v[218:219], off
	s_mov_b32 m0, s40
	s_nop 0
	global_load_lds_dwordx4 v[220:221], off
	s_waitcnt vmcnt(8)
	s_waitcnt lgkmcnt(0)
	s_barrier
	s_waitcnt lgkmcnt(0)
	v_mfma_f32_16x16x32_bf16 v[62:65], v[142:145], v[184:187], v[62:65]
	v_mfma_f32_16x16x32_bf16 v[58:61], v[150:153], v[184:187], v[58:61]
	v_mfma_f32_16x16x32_bf16 v[50:53], v[142:145], v[192:195], v[50:53]
	v_mfma_f32_16x16x32_bf16 v[42:45], v[150:153], v[192:195], v[42:45]
	v_mfma_f32_16x16x32_bf16 v[34:37], v[142:145], v[200:203], v[34:37]
	v_mfma_f32_16x16x32_bf16 v[26:29], v[150:153], v[200:203], v[26:29]
	v_mfma_f32_16x16x32_bf16 v[18:21], v[142:145], v[208:211], v[18:21]
	v_mfma_f32_16x16x32_bf16 v[10:13], v[150:153], v[208:211], v[10:13]
	v_mfma_f32_16x16x32_bf16 v[62:65], v[146:149], v[188:191], v[62:65]
	v_mfma_f32_16x16x32_bf16 v[58:61], v[154:157], v[188:191], v[58:61]
	v_mfma_f32_16x16x32_bf16 v[50:53], v[146:149], v[196:199], v[50:53]
	v_mfma_f32_16x16x32_bf16 v[42:45], v[154:157], v[196:199], v[42:45]
	v_mfma_f32_16x16x32_bf16 v[34:37], v[146:149], v[204:207], v[34:37]
	v_mfma_f32_16x16x32_bf16 v[26:29], v[154:157], v[204:207], v[26:29]
	v_mfma_f32_16x16x32_bf16 v[18:21], v[146:149], v[212:215], v[18:21]
	v_mfma_f32_16x16x32_bf16 v[10:13], v[154:157], v[212:215], v[10:13]
	v_mfma_f32_16x16x32_bf16 v[54:57], v[158:161], v[184:187], v[54:57]
	v_mfma_f32_16x16x32_bf16 v[46:49], v[172:175], v[184:187], v[46:49]
	v_mfma_f32_16x16x32_bf16 v[38:41], v[158:161], v[192:195], v[38:41]
	v_mfma_f32_16x16x32_bf16 v[30:33], v[172:175], v[192:195], v[30:33]
	v_mfma_f32_16x16x32_bf16 v[22:25], v[158:161], v[200:203], v[22:25]
	v_mfma_f32_16x16x32_bf16 v[14:17], v[172:175], v[200:203], v[14:17]
	v_mfma_f32_16x16x32_bf16 v[6:9], v[158:161], v[208:211], v[6:9]
	v_mfma_f32_16x16x32_bf16 v[2:5], v[172:175], v[208:211], v[2:5]
	v_mfma_f32_16x16x32_bf16 v[54:57], v[168:171], v[188:191], v[54:57]
	v_mfma_f32_16x16x32_bf16 v[46:49], v[176:179], v[188:191], v[46:49]
	v_mfma_f32_16x16x32_bf16 v[38:41], v[168:171], v[196:199], v[38:41]
	v_mfma_f32_16x16x32_bf16 v[30:33], v[176:179], v[196:199], v[30:33]
	v_mfma_f32_16x16x32_bf16 v[22:25], v[168:171], v[204:207], v[22:25]
	v_mfma_f32_16x16x32_bf16 v[14:17], v[176:179], v[204:207], v[14:17]
	v_mfma_f32_16x16x32_bf16 v[6:9], v[168:171], v[212:215], v[6:9]
	v_mfma_f32_16x16x32_bf16 v[2:5], v[176:179], v[212:215], v[2:5]
	s_barrier
	s_add_i32 s60, 0, 0x18000
	s_add_i32 s61, 0, 0x1c000
	v_add_u32_e32 v154, s60, v162
	v_add_u32_e32 v176, s61, v162
	ds_read_b128 v[142:145], v154
	ds_read_b128 v[146:149], v154 offset:1024
	ds_read_b128 v[150:153], v154 offset:2048
	ds_read_b128 v[154:157], v154 offset:3072
	ds_read_b128 v[158:161], v176
	ds_read_b128 v[168:171], v176 offset:1024
	ds_read_b128 v[172:175], v176 offset:2048
	ds_read_b128 v[176:179], v176 offset:3072
	s_add_u32 s30, s30, 0x200000
	s_addc_u32 s31, s31, 0
	s_mov_b32 m0, s41
	v_lshl_add_u64 v[222:223], s[30:31], 0, v[130:131]
	ds_read_b128 v[184:187], v167 offset:32768
	ds_read_b128 v[188:191], v167 offset:33792
	ds_read_b128 v[192:195], v167 offset:34816
	ds_read_b128 v[196:199], v167 offset:35840
	ds_read_b128 v[200:203], v167 offset:36864
	ds_read_b128 v[204:207], v167 offset:37888
	ds_read_b128 v[208:211], v167 offset:38912
	ds_read_b128 v[212:215], v167 offset:39936
	global_load_lds_dwordx4 v[222:223], off
	v_lshl_add_u64 v[222:223], s[30:31], 0, v[132:133]
	s_mov_b32 m0, s42
	s_nop 0
	global_load_lds_dwordx4 v[222:223], off
	s_waitcnt vmcnt(8)
	s_waitcnt lgkmcnt(0)
	s_barrier
	s_waitcnt lgkmcnt(0)
	v_mfma_f32_16x16x32_bf16 v[126:129], v[142:145], v[184:187], v[126:129]
	v_mfma_f32_16x16x32_bf16 v[122:125], v[150:153], v[184:187], v[122:125]
	v_mfma_f32_16x16x32_bf16 v[114:117], v[142:145], v[192:195], v[114:117]
	v_mfma_f32_16x16x32_bf16 v[106:109], v[150:153], v[192:195], v[106:109]
	v_mfma_f32_16x16x32_bf16 v[98:101], v[142:145], v[200:203], v[98:101]
	v_mfma_f32_16x16x32_bf16 v[90:93], v[150:153], v[200:203], v[90:93]
	v_mfma_f32_16x16x32_bf16 v[82:85], v[142:145], v[208:211], v[82:85]
	v_mfma_f32_16x16x32_bf16 v[74:77], v[150:153], v[208:211], v[74:77]
	v_mfma_f32_16x16x32_bf16 v[126:129], v[146:149], v[188:191], v[126:129]
	v_mfma_f32_16x16x32_bf16 v[122:125], v[154:157], v[188:191], v[122:125]
	v_mfma_f32_16x16x32_bf16 v[114:117], v[146:149], v[196:199], v[114:117]
	v_mfma_f32_16x16x32_bf16 v[106:109], v[154:157], v[196:199], v[106:109]
	v_mfma_f32_16x16x32_bf16 v[98:101], v[146:149], v[204:207], v[98:101]
	v_mfma_f32_16x16x32_bf16 v[90:93], v[154:157], v[204:207], v[90:93]
	v_mfma_f32_16x16x32_bf16 v[82:85], v[146:149], v[212:215], v[82:85]
	v_mfma_f32_16x16x32_bf16 v[74:77], v[154:157], v[212:215], v[74:77]
	v_mfma_f32_16x16x32_bf16 v[118:121], v[158:161], v[184:187], v[118:121]
	v_mfma_f32_16x16x32_bf16 v[110:113], v[172:175], v[184:187], v[110:113]
	v_mfma_f32_16x16x32_bf16 v[102:105], v[158:161], v[192:195], v[102:105]
	v_mfma_f32_16x16x32_bf16 v[94:97], v[172:175], v[192:195], v[94:97]
	v_mfma_f32_16x16x32_bf16 v[86:89], v[158:161], v[200:203], v[86:89]
	v_mfma_f32_16x16x32_bf16 v[78:81], v[172:175], v[200:203], v[78:81]
	v_mfma_f32_16x16x32_bf16 v[70:73], v[158:161], v[208:211], v[70:73]
	v_mfma_f32_16x16x32_bf16 v[66:69], v[172:175], v[208:211], v[66:69]
	v_mfma_f32_16x16x32_bf16 v[118:121], v[168:171], v[188:191], v[118:121]
	v_mfma_f32_16x16x32_bf16 v[110:113], v[176:179], v[188:191], v[110:113]
	v_mfma_f32_16x16x32_bf16 v[102:105], v[168:171], v[196:199], v[102:105]
	v_mfma_f32_16x16x32_bf16 v[94:97], v[176:179], v[196:199], v[94:97]
	v_mfma_f32_16x16x32_bf16 v[86:89], v[168:171], v[204:207], v[86:89]
	v_mfma_f32_16x16x32_bf16 v[78:81], v[176:179], v[204:207], v[78:81]
	v_mfma_f32_16x16x32_bf16 v[70:73], v[168:171], v[212:215], v[70:73]
	v_mfma_f32_16x16x32_bf16 v[66:69], v[176:179], v[212:215], v[66:69]
	s_barrier
	s_add_i32 s30, s60, s38
	v_lshl_add_u64 v[180:181], v[180:181], 0, s[10:11]
	s_mov_b32 m0, s30
	ds_read_b128 v[184:187], v167 offset:49152
	ds_read_b128 v[188:191], v167 offset:50176
	ds_read_b128 v[192:195], v167 offset:51200
	ds_read_b128 v[196:199], v167 offset:52224
	ds_read_b128 v[200:203], v167 offset:53248
	ds_read_b128 v[204:207], v167 offset:54272
	ds_read_b128 v[208:211], v167 offset:55296
	ds_read_b128 v[212:215], v167 offset:56320
	global_load_lds_dwordx4 v[180:181], off
	s_add_i32 m0, s30, 0x2000
	s_add_u32 s28, s28, 0x200080
	v_lshl_add_u64 v[180:181], v[216:217], 0, s[10:11]
	s_addc_u32 s29, s29, 0
	s_add_i32 s30, s61, s38
	global_load_lds_dwordx4 v[180:181], off
	v_lshl_add_u64 v[180:181], s[28:29], 0, v[130:131]
	s_mov_b32 m0, s30
	s_nop 0
	global_load_lds_dwordx4 v[180:181], off
	v_lshl_add_u64 v[180:181], s[28:29], 0, v[132:133]
	s_add_i32 m0, s30, 0x2000
	s_nop 0
	global_load_lds_dwordx4 v[180:181], off
	v_lshl_add_u64 v[180:181], v[218:219], 0, s[10:11]
	s_mov_b32 m0, s45
	s_nop 0
	global_load_lds_dwordx4 v[180:181], off
	v_lshl_add_u64 v[180:181], v[220:221], 0, s[10:11]
	s_mov_b32 m0, s46
	s_nop 0
	global_load_lds_dwordx4 v[180:181], off
	s_waitcnt vmcnt(8)
	s_waitcnt lgkmcnt(0)
	s_barrier
	s_waitcnt lgkmcnt(0)
	v_mfma_f32_16x16x32_bf16 v[62:65], v[142:145], v[184:187], v[62:65]
	v_mfma_f32_16x16x32_bf16 v[58:61], v[150:153], v[184:187], v[58:61]
	v_mfma_f32_16x16x32_bf16 v[50:53], v[142:145], v[192:195], v[50:53]
	v_mfma_f32_16x16x32_bf16 v[42:45], v[150:153], v[192:195], v[42:45]
	v_mfma_f32_16x16x32_bf16 v[34:37], v[142:145], v[200:203], v[34:37]
	v_mfma_f32_16x16x32_bf16 v[26:29], v[150:153], v[200:203], v[26:29]
	v_mfma_f32_16x16x32_bf16 v[18:21], v[142:145], v[208:211], v[18:21]
	v_mfma_f32_16x16x32_bf16 v[10:13], v[150:153], v[208:211], v[10:13]
	v_mfma_f32_16x16x32_bf16 v[62:65], v[146:149], v[188:191], v[62:65]
	v_mfma_f32_16x16x32_bf16 v[58:61], v[154:157], v[188:191], v[58:61]
	v_mfma_f32_16x16x32_bf16 v[50:53], v[146:149], v[196:199], v[50:53]
	v_mfma_f32_16x16x32_bf16 v[42:45], v[154:157], v[196:199], v[42:45]
	v_mfma_f32_16x16x32_bf16 v[34:37], v[146:149], v[204:207], v[34:37]
	v_mfma_f32_16x16x32_bf16 v[26:29], v[154:157], v[204:207], v[26:29]
	v_mfma_f32_16x16x32_bf16 v[18:21], v[146:149], v[212:215], v[18:21]
	v_mfma_f32_16x16x32_bf16 v[10:13], v[154:157], v[212:215], v[10:13]
	v_mfma_f32_16x16x32_bf16 v[54:57], v[158:161], v[184:187], v[54:57]
	v_mfma_f32_16x16x32_bf16 v[46:49], v[172:175], v[184:187], v[46:49]
	v_mfma_f32_16x16x32_bf16 v[38:41], v[158:161], v[192:195], v[38:41]
	v_mfma_f32_16x16x32_bf16 v[30:33], v[172:175], v[192:195], v[30:33]
	v_mfma_f32_16x16x32_bf16 v[22:25], v[158:161], v[200:203], v[22:25]
	v_mfma_f32_16x16x32_bf16 v[14:17], v[172:175], v[200:203], v[14:17]
	v_mfma_f32_16x16x32_bf16 v[6:9], v[158:161], v[208:211], v[6:9]
	v_mfma_f32_16x16x32_bf16 v[2:5], v[172:175], v[208:211], v[2:5]
	v_mfma_f32_16x16x32_bf16 v[54:57], v[168:171], v[188:191], v[54:57]
	v_mfma_f32_16x16x32_bf16 v[46:49], v[176:179], v[188:191], v[46:49]
	v_mfma_f32_16x16x32_bf16 v[38:41], v[168:171], v[196:199], v[38:41]
	v_mfma_f32_16x16x32_bf16 v[30:33], v[176:179], v[196:199], v[30:33]
	v_mfma_f32_16x16x32_bf16 v[22:25], v[168:171], v[204:207], v[22:25]
	v_mfma_f32_16x16x32_bf16 v[14:17], v[176:179], v[204:207], v[14:17]
	v_mfma_f32_16x16x32_bf16 v[6:9], v[168:171], v[212:215], v[6:9]
	v_mfma_f32_16x16x32_bf16 v[2:5], v[176:179], v[212:215], v[2:5]
	s_barrier
	s_add_i32 s59, s59, 2
	s_add_u32 s26, s26, 0x100
	s_addc_u32 s27, s27, 0
	s_add_u32 s57, s57, 0x100
	s_addc_u32 s58, s58, 0
	s_cmpk_gt_u32 s59, 0x7d
	s_cbranch_scc0 .LBB0_763
	s_and_b64 vcc, exec, s[14:15]
	s_cbranch_vccz .LBB0_766
	s_barrier

.LBB0_915:
	s_ashr_i32 s19, s18, 31
	s_lshl_b64 s[20:21], s[18:19], 21
	s_add_u32 s20, s54, s20
	s_addc_u32 s21, s55, s21
	s_and_b64 s[22:23], s[0:1], exec
	s_cselect_b32 s19, s21, s27
	s_cselect_b32 s53, s20, s26
	s_ashr_i32 s17, s16, 31
	s_lshl_b64 s[22:23], s[16:17], 21
	s_add_u32 s22, s36, s22
	s_addc_u32 s23, s37, s23
	s_and_b64 s[30:31], s[0:1], exec
	s_cselect_b32 s17, s23, s29
	s_cselect_b32 s56, s22, s28
	s_add_u32 s26, s26, 0x100080
	s_addc_u32 s27, s27, 0
	s_add_u32 s57, s28, 0x100
	v_mov_b32_e32 v2, 0
	s_addc_u32 s58, s29, 0
	s_mov_b32 s59, -2
	v_mov_b32_e32 v3, v2
	v_mov_b32_e32 v4, v2
	v_mov_b32_e32 v5, v2
	v_mov_b32_e32 v6, v2
	v_mov_b32_e32 v7, v2
	v_mov_b32_e32 v8, v2
	v_mov_b32_e32 v9, v2
	v_mov_b32_e32 v18, v2
	v_mov_b32_e32 v19, v2
	v_mov_b32_e32 v20, v2
	v_mov_b32_e32 v21, v2
	v_mov_b32_e32 v22, v2
	v_mov_b32_e32 v23, v2
	v_mov_b32_e32 v24, v2
	v_mov_b32_e32 v25, v2
	v_mov_b32_e32 v34, v2
	v_mov_b32_e32 v35, v2
	v_mov_b32_e32 v36, v2
	v_mov_b32_e32 v37, v2
	v_mov_b32_e32 v38, v2
	v_mov_b32_e32 v39, v2
	v_mov_b32_e32 v40, v2
	v_mov_b32_e32 v41, v2
	v_mov_b32_e32 v50, v2
	v_mov_b32_e32 v51, v2
	v_mov_b32_e32 v52, v2
	v_mov_b32_e32 v53, v2
	v_mov_b32_e32 v54, v2
	v_mov_b32_e32 v55, v2
	v_mov_b32_e32 v56, v2
	v_mov_b32_e32 v57, v2
	v_mov_b32_e32 v10, v2
	v_mov_b32_e32 v11, v2
	v_mov_b32_e32 v12, v2
	v_mov_b32_e32 v13, v2
	v_mov_b32_e32 v14, v2
	v_mov_b32_e32 v15, v2
	v_mov_b32_e32 v16, v2
	v_mov_b32_e32 v17, v2
	v_mov_b32_e32 v26, v2
	v_mov_b32_e32 v27, v2
	v_mov_b32_e32 v28, v2
	v_mov_b32_e32 v29, v2
	v_mov_b32_e32 v30, v2
	v_mov_b32_e32 v31, v2
	v_mov_b32_e32 v32, v2
	v_mov_b32_e32 v33, v2
	v_mov_b32_e32 v42, v2
	v_mov_b32_e32 v43, v2
	v_mov_b32_e32 v44, v2
	v_mov_b32_e32 v45, v2
	v_mov_b32_e32 v46, v2
	v_mov_b32_e32 v47, v2
	v_mov_b32_e32 v48, v2
	v_mov_b32_e32 v49, v2
	v_mov_b32_e32 v58, v2
	v_mov_b32_e32 v59, v2
	v_mov_b32_e32 v60, v2
	v_mov_b32_e32 v61, v2
	v_mov_b32_e32 v62, v2
	v_mov_b32_e32 v63, v2
	v_mov_b32_e32 v64, v2
	v_mov_b32_e32 v65, v2
	v_mov_b32_e32 v66, v2
	v_mov_b32_e32 v67, v2
	v_mov_b32_e32 v68, v2
	v_mov_b32_e32 v69, v2
	v_mov_b32_e32 v70, v2
	v_mov_b32_e32 v71, v2
	v_mov_b32_e32 v72, v2
	v_mov_b32_e32 v73, v2
	v_mov_b32_e32 v82, v2
	v_mov_b32_e32 v83, v2
	v_mov_b32_e32 v84, v2
	v_mov_b32_e32 v85, v2
	v_mov_b32_e32 v86, v2
	v_mov_b32_e32 v87, v2
	v_mov_b32_e32 v88, v2
	v_mov_b32_e32 v89, v2
	v_mov_b32_e32 v98, v2
	v_mov_b32_e32 v99, v2
	v_mov_b32_e32 v100, v2
	v_mov_b32_e32 v101, v2
	v_mov_b32_e32 v102, v2
	v_mov_b32_e32 v103, v2
	v_mov_b32_e32 v104, v2
	v_mov_b32_e32 v105, v2
	v_mov_b32_e32 v114, v2
	v_mov_b32_e32 v115, v2
	v_mov_b32_e32 v116, v2
	v_mov_b32_e32 v117, v2
	v_mov_b32_e32 v118, v2
	v_mov_b32_e32 v119, v2
	v_mov_b32_e32 v120, v2
	v_mov_b32_e32 v121, v2
	v_mov_b32_e32 v74, v2
	v_mov_b32_e32 v75, v2
	v_mov_b32_e32 v76, v2
	v_mov_b32_e32 v77, v2
	v_mov_b32_e32 v78, v2
	v_mov_b32_e32 v79, v2
	v_mov_b32_e32 v80, v2
	v_mov_b32_e32 v81, v2
	v_mov_b32_e32 v90, v2
	v_mov_b32_e32 v91, v2
	v_mov_b32_e32 v92, v2
	v_mov_b32_e32 v93, v2
	v_mov_b32_e32 v94, v2
	v_mov_b32_e32 v95, v2
	v_mov_b32_e32 v96, v2
	v_mov_b32_e32 v97, v2
	v_mov_b32_e32 v106, v2
	v_mov_b32_e32 v107, v2
	v_mov_b32_e32 v108, v2
	v_mov_b32_e32 v109, v2
	v_mov_b32_e32 v110, v2
	v_mov_b32_e32 v111, v2
	v_mov_b32_e32 v112, v2
	v_mov_b32_e32 v113, v2
	v_mov_b32_e32 v122, v2
	v_mov_b32_e32 v123, v2
	v_mov_b32_e32 v124, v2
	v_mov_b32_e32 v125, v2
	v_mov_b32_e32 v126, v2
	v_mov_b32_e32 v127, v2
	v_mov_b32_e32 v128, v2
	v_mov_b32_e32 v129, v2
	s_setprio 0
.LBB0_916:
	ds_read_b128 v[164:167], v158
	ds_read_b128 v[168:171], v158 offset:1024
	ds_read_b128 v[172:175], v158 offset:2048
	ds_read_b128 v[176:179], v158 offset:3072
	ds_read_b128 v[180:183], v159
	ds_read_b128 v[184:187], v159 offset:1024
	ds_read_b128 v[188:191], v159 offset:2048
	ds_read_b128 v[192:195], v159 offset:3072
	s_add_u32 s28, s26, 0xfff00080
	s_addc_u32 s29, s27, -1
	s_cmp_eq_u32 s59, 60
	s_cselect_b32 s31, s19, s29
	s_cselect_b32 s30, s53, s28
	s_cselect_b32 s29, s17, s58
	s_cselect_b32 s28, s56, s57
	v_lshl_add_u64 v[146:147], s[26:27], 0, v[138:139]
	s_add_i32 m0, s25, 0xc000
	ds_read_b128 v[196:199], v160
	ds_read_b128 v[200:203], v160 offset:1024
	ds_read_b128 v[204:207], v160 offset:2048
	ds_read_b128 v[208:211], v160 offset:3072
	ds_read_b128 v[212:215], v160 offset:4096
	ds_read_b128 v[216:219], v160 offset:5120
	ds_read_b128 v[220:223], v160 offset:6144
	ds_read_b128 v[224:227], v160 offset:7168
	global_load_lds_dwordx4 v[146:147], off
	v_lshl_add_u64 v[146:147], s[26:27], 0, v[140:141]
	s_add_i32 m0, s25, 0xe000
	s_nop 0
	global_load_lds_dwordx4 v[146:147], off
	s_waitcnt vmcnt(8)
	s_waitcnt lgkmcnt(0)
	s_barrier
	s_waitcnt lgkmcnt(0)
	v_mfma_f32_16x16x32_bf16 v[126:129], v[164:167], v[196:199], v[126:129]
	v_mfma_f32_16x16x32_bf16 v[122:125], v[172:175], v[196:199], v[122:125]
	v_mfma_f32_16x16x32_bf16 v[110:113], v[164:167], v[204:207], v[110:113]
	v_mfma_f32_16x16x32_bf16 v[106:109], v[172:175], v[204:207], v[106:109]
	v_mfma_f32_16x16x32_bf16 v[94:97], v[164:167], v[212:215], v[94:97]
	v_mfma_f32_16x16x32_bf16 v[90:93], v[172:175], v[212:215], v[90:93]
	v_mfma_f32_16x16x32_bf16 v[78:81], v[164:167], v[220:223], v[78:81]
	v_mfma_f32_16x16x32_bf16 v[74:77], v[172:175], v[220:223], v[74:77]
	v_mfma_f32_16x16x32_bf16 v[126:129], v[168:171], v[200:203], v[126:129]
	v_mfma_f32_16x16x32_bf16 v[122:125], v[176:179], v[200:203], v[122:125]
	v_mfma_f32_16x16x32_bf16 v[110:113], v[168:171], v[208:211], v[110:113]
	v_mfma_f32_16x16x32_bf16 v[106:109], v[176:179], v[208:211], v[106:109]
	v_mfma_f32_16x16x32_bf16 v[94:97], v[168:171], v[216:219], v[94:97]
	v_mfma_f32_16x16x32_bf16 v[90:93], v[176:179], v[216:219], v[90:93]
	v_mfma_f32_16x16x32_bf16 v[78:81], v[168:171], v[224:227], v[78:81]
	v_mfma_f32_16x16x32_bf16 v[74:77], v[176:179], v[224:227], v[74:77]
	v_mfma_f32_16x16x32_bf16 v[118:121], v[180:183], v[196:199], v[118:121]
	v_mfma_f32_16x16x32_bf16 v[114:117], v[188:191], v[196:199], v[114:117]
	v_mfma_f32_16x16x32_bf16 v[102:105], v[180:183], v[204:207], v[102:105]
	v_mfma_f32_16x16x32_bf16 v[98:101], v[188:191], v[204:207], v[98:101]
	v_mfma_f32_16x16x32_bf16 v[86:89], v[180:183], v[212:215], v[86:89]
	v_mfma_f32_16x16x32_bf16 v[82:85], v[188:191], v[212:215], v[82:85]
	v_mfma_f32_16x16x32_bf16 v[70:73], v[180:183], v[220:223], v[70:73]
	v_mfma_f32_16x16x32_bf16 v[66:69], v[188:191], v[220:223], v[66:69]
	v_mfma_f32_16x16x32_bf16 v[118:121], v[184:187], v[200:203], v[118:121]
	v_mfma_f32_16x16x32_bf16 v[114:117], v[192:195], v[200:203], v[114:117]
	v_mfma_f32_16x16x32_bf16 v[102:105], v[184:187], v[208:211], v[102:105]
	v_mfma_f32_16x16x32_bf16 v[98:101], v[192:195], v[208:211], v[98:101]
	v_mfma_f32_16x16x32_bf16 v[86:89], v[184:187], v[216:219], v[86:89]
	v_mfma_f32_16x16x32_bf16 v[82:85], v[192:195], v[216:219], v[82:85]
	v_mfma_f32_16x16x32_bf16 v[70:73], v[184:187], v[224:227], v[70:73]
	v_mfma_f32_16x16x32_bf16 v[66:69], v[192:195], v[224:227], v[66:69]
	s_barrier
	s_add_i32 s60, s45, s38
	v_lshl_add_u64 v[146:147], s[28:29], 0, v[132:133]
	s_mov_b32 m0, s60
	ds_read_b128 v[196:199], v160 offset:16384
	ds_read_b128 v[200:203], v160 offset:17408
	ds_read_b128 v[204:207], v160 offset:18432
	ds_read_b128 v[208:211], v160 offset:19456
	ds_read_b128 v[212:215], v160 offset:20480
	ds_read_b128 v[216:219], v160 offset:21504
	ds_read_b128 v[220:223], v160 offset:22528
	ds_read_b128 v[224:227], v160 offset:23552
	global_load_lds_dwordx4 v[146:147], off
	s_add_i32 m0, s60, 0x2000
	s_add_u32 s60, s28, 0x100000
	v_lshl_add_u64 v[228:229], s[28:29], 0, v[136:137]
	s_addc_u32 s61, s29, 0
	s_add_i32 s62, s46, s38
	global_load_lds_dwordx4 v[228:229], off
	v_lshl_add_u64 v[230:231], s[60:61], 0, v[132:133]
	s_mov_b32 m0, s62
	v_lshl_add_u64 v[232:233], s[30:31], 0, v[134:135]
	global_load_lds_dwordx4 v[230:231], off
	v_lshl_add_u64 v[230:231], s[60:61], 0, v[136:137]
	s_add_i32 m0, s62, 0x2000
	s_nop 0
	global_load_lds_dwordx4 v[230:231], off
	v_lshl_add_u64 v[230:231], s[30:31], 0, v[130:131]
	s_mov_b32 m0, s25
	s_nop 0
	global_load_lds_dwordx4 v[230:231], off
	s_mov_b32 m0, s39
	s_nop 0
	global_load_lds_dwordx4 v[232:233], off
	s_waitcnt vmcnt(8)
	s_waitcnt lgkmcnt(0)
	s_barrier
	s_waitcnt lgkmcnt(0)
	v_mfma_f32_16x16x32_bf16 v[62:65], v[164:167], v[196:199], v[62:65]
	v_mfma_f32_16x16x32_bf16 v[58:61], v[172:175], v[196:199], v[58:61]
	v_mfma_f32_16x16x32_bf16 v[46:49], v[164:167], v[204:207], v[46:49]
	v_mfma_f32_16x16x32_bf16 v[42:45], v[172:175], v[204:207], v[42:45]
	v_mfma_f32_16x16x32_bf16 v[30:33], v[164:167], v[212:215], v[30:33]
	v_mfma_f32_16x16x32_bf16 v[26:29], v[172:175], v[212:215], v[26:29]
	v_mfma_f32_16x16x32_bf16 v[14:17], v[164:167], v[220:223], v[14:17]
	v_mfma_f32_16x16x32_bf16 v[10:13], v[172:175], v[220:223], v[10:13]
	v_mfma_f32_16x16x32_bf16 v[62:65], v[168:171], v[200:203], v[62:65]
	v_mfma_f32_16x16x32_bf16 v[58:61], v[176:179], v[200:203], v[58:61]
	v_mfma_f32_16x16x32_bf16 v[46:49], v[168:171], v[208:211], v[46:49]
	v_mfma_f32_16x16x32_bf16 v[42:45], v[176:179], v[208:211], v[42:45]
	v_mfma_f32_16x16x32_bf16 v[30:33], v[168:171], v[216:219], v[30:33]
	v_mfma_f32_16x16x32_bf16 v[26:29], v[176:179], v[216:219], v[26:29]
	v_mfma_f32_16x16x32_bf16 v[14:17], v[168:171], v[224:227], v[14:17]
	v_mfma_f32_16x16x32_bf16 v[10:13], v[176:179], v[224:227], v[10:13]
	v_mfma_f32_16x16x32_bf16 v[54:57], v[180:183], v[196:199], v[54:57]
	v_mfma_f32_16x16x32_bf16 v[50:53], v[188:191], v[196:199], v[50:53]
	v_mfma_f32_16x16x32_bf16 v[38:41], v[180:183], v[204:207], v[38:41]
	v_mfma_f32_16x16x32_bf16 v[34:37], v[188:191], v[204:207], v[34:37]
	v_mfma_f32_16x16x32_bf16 v[22:25], v[180:183], v[212:215], v[22:25]
	v_mfma_f32_16x16x32_bf16 v[18:21], v[188:191], v[212:215], v[18:21]
	v_mfma_f32_16x16x32_bf16 v[6:9], v[180:183], v[220:223], v[6:9]
	v_mfma_f32_16x16x32_bf16 v[2:5], v[188:191], v[220:223], v[2:5]
	v_mfma_f32_16x16x32_bf16 v[54:57], v[184:187], v[200:203], v[54:57]
	v_mfma_f32_16x16x32_bf16 v[50:53], v[192:195], v[200:203], v[50:53]
	v_mfma_f32_16x16x32_bf16 v[38:41], v[184:187], v[208:211], v[38:41]
	v_mfma_f32_16x16x32_bf16 v[34:37], v[192:195], v[208:211], v[34:37]
	v_mfma_f32_16x16x32_bf16 v[22:25], v[184:187], v[216:219], v[22:25]
	v_mfma_f32_16x16x32_bf16 v[18:21], v[192:195], v[216:219], v[18:21]
	v_mfma_f32_16x16x32_bf16 v[6:9], v[184:187], v[224:227], v[6:9]
	v_mfma_f32_16x16x32_bf16 v[2:5], v[192:195], v[224:227], v[2:5]
	s_barrier
	s_add_i32 s60, 0, 0x18000
	v_add_u32_e32 v161, s60, v156
	s_add_i32 s61, 0, 0x1c000
	ds_read_b128 v[164:167], v161
	ds_read_b128 v[168:171], v161 offset:1024
	ds_read_b128 v[172:175], v161 offset:2048
	ds_read_b128 v[176:179], v161 offset:3072
	v_add_u32_e32 v161, s61, v156
	ds_read_b128 v[180:183], v161
	ds_read_b128 v[184:187], v161 offset:1024
	ds_read_b128 v[188:191], v161 offset:2048
	ds_read_b128 v[192:195], v161 offset:3072
	s_add_u32 s30, s30, 0x100000
	s_addc_u32 s31, s31, 0
	s_mov_b32 m0, s40
	v_lshl_add_u64 v[234:235], s[30:31], 0, v[130:131]
	ds_read_b128 v[196:199], v160 offset:32768
	ds_read_b128 v[200:203], v160 offset:33792
	ds_read_b128 v[204:207], v160 offset:34816
	ds_read_b128 v[208:211], v160 offset:35840
	ds_read_b128 v[212:215], v160 offset:36864
	ds_read_b128 v[216:219], v160 offset:37888
	ds_read_b128 v[220:223], v160 offset:38912
	ds_read_b128 v[224:227], v160 offset:39936
	global_load_lds_dwordx4 v[234:235], off
	v_lshl_add_u64 v[234:235], s[30:31], 0, v[134:135]
	s_mov_b32 m0, s41
	s_nop 0
	global_load_lds_dwordx4 v[234:235], off
	s_waitcnt vmcnt(8)
	s_waitcnt lgkmcnt(0)
	s_barrier
	s_waitcnt lgkmcnt(0)
	v_mfma_f32_16x16x32_bf16 v[126:129], v[164:167], v[196:199], v[126:129]
	v_mfma_f32_16x16x32_bf16 v[122:125], v[172:175], v[196:199], v[122:125]
	v_mfma_f32_16x16x32_bf16 v[110:113], v[164:167], v[204:207], v[110:113]
	v_mfma_f32_16x16x32_bf16 v[106:109], v[172:175], v[204:207], v[106:109]
	v_mfma_f32_16x16x32_bf16 v[94:97], v[164:167], v[212:215], v[94:97]
	v_mfma_f32_16x16x32_bf16 v[90:93], v[172:175], v[212:215], v[90:93]
	v_mfma_f32_16x16x32_bf16 v[78:81], v[164:167], v[220:223], v[78:81]
	v_mfma_f32_16x16x32_bf16 v[74:77], v[172:175], v[220:223], v[74:77]
	v_mfma_f32_16x16x32_bf16 v[126:129], v[168:171], v[200:203], v[126:129]
	v_mfma_f32_16x16x32_bf16 v[122:125], v[176:179], v[200:203], v[122:125]
	v_mfma_f32_16x16x32_bf16 v[110:113], v[168:171], v[208:211], v[110:113]
	v_mfma_f32_16x16x32_bf16 v[106:109], v[176:179], v[208:211], v[106:109]
	v_mfma_f32_16x16x32_bf16 v[94:97], v[168:171], v[216:219], v[94:97]
	v_mfma_f32_16x16x32_bf16 v[90:93], v[176:179], v[216:219], v[90:93]
	v_mfma_f32_16x16x32_bf16 v[78:81], v[168:171], v[224:227], v[78:81]
	v_mfma_f32_16x16x32_bf16 v[74:77], v[176:179], v[224:227], v[74:77]
	v_mfma_f32_16x16x32_bf16 v[118:121], v[180:183], v[196:199], v[118:121]
	v_mfma_f32_16x16x32_bf16 v[114:117], v[188:191], v[196:199], v[114:117]
	v_mfma_f32_16x16x32_bf16 v[102:105], v[180:183], v[204:207], v[102:105]
	v_mfma_f32_16x16x32_bf16 v[98:101], v[188:191], v[204:207], v[98:101]
	v_mfma_f32_16x16x32_bf16 v[86:89], v[180:183], v[212:215], v[86:89]
	v_mfma_f32_16x16x32_bf16 v[82:85], v[188:191], v[212:215], v[82:85]
	v_mfma_f32_16x16x32_bf16 v[70:73], v[180:183], v[220:223], v[70:73]
	v_mfma_f32_16x16x32_bf16 v[66:69], v[188:191], v[220:223], v[66:69]
	v_mfma_f32_16x16x32_bf16 v[118:121], v[184:187], v[200:203], v[118:121]
	v_mfma_f32_16x16x32_bf16 v[114:117], v[192:195], v[200:203], v[114:117]
	v_mfma_f32_16x16x32_bf16 v[102:105], v[184:187], v[208:211], v[102:105]
	v_mfma_f32_16x16x32_bf16 v[98:101], v[192:195], v[208:211], v[98:101]
	v_mfma_f32_16x16x32_bf16 v[86:89], v[184:187], v[216:219], v[86:89]
	v_mfma_f32_16x16x32_bf16 v[82:85], v[192:195], v[216:219], v[82:85]
	v_mfma_f32_16x16x32_bf16 v[70:73], v[184:187], v[224:227], v[70:73]
	v_mfma_f32_16x16x32_bf16 v[66:69], v[192:195], v[224:227], v[66:69]
	s_barrier
	s_add_i32 s30, s60, s38
	v_lshl_add_u64 v[146:147], v[146:147], 0, s[12:13]
	s_mov_b32 m0, s30
	ds_read_b128 v[196:199], v160 offset:49152
	ds_read_b128 v[200:203], v160 offset:50176
	ds_read_b128 v[204:207], v160 offset:51200
	ds_read_b128 v[208:211], v160 offset:52224
	ds_read_b128 v[212:215], v160 offset:53248
	ds_read_b128 v[216:219], v160 offset:54272
	ds_read_b128 v[220:223], v160 offset:55296
	ds_read_b128 v[224:227], v160 offset:56320
	global_load_lds_dwordx4 v[146:147], off
	s_add_i32 m0, s30, 0x2000
	s_add_u32 s28, s28, 0x100080
	v_lshl_add_u64 v[146:147], v[228:229], 0, s[12:13]
	s_addc_u32 s29, s29, 0
	s_add_i32 s30, s61, s38
	global_load_lds_dwordx4 v[146:147], off
	v_lshl_add_u64 v[146:147], s[28:29], 0, v[132:133]
	s_mov_b32 m0, s30
	s_nop 0
	global_load_lds_dwordx4 v[146:147], off
	v_lshl_add_u64 v[146:147], s[28:29], 0, v[136:137]
	s_add_i32 m0, s30, 0x2000
	s_nop 0
	global_load_lds_dwordx4 v[146:147], off
	v_lshl_add_u64 v[146:147], v[230:231], 0, s[12:13]
	s_mov_b32 m0, s42
	s_nop 0
	global_load_lds_dwordx4 v[146:147], off
	v_lshl_add_u64 v[146:147], v[232:233], 0, s[12:13]
	s_mov_b32 m0, s43
	s_nop 0
	global_load_lds_dwordx4 v[146:147], off
	s_waitcnt vmcnt(8)
	s_waitcnt lgkmcnt(0)
	s_barrier
	s_waitcnt lgkmcnt(0)
	v_mfma_f32_16x16x32_bf16 v[62:65], v[164:167], v[196:199], v[62:65]
	v_mfma_f32_16x16x32_bf16 v[58:61], v[172:175], v[196:199], v[58:61]
	v_mfma_f32_16x16x32_bf16 v[46:49], v[164:167], v[204:207], v[46:49]
	v_mfma_f32_16x16x32_bf16 v[42:45], v[172:175], v[204:207], v[42:45]
	v_mfma_f32_16x16x32_bf16 v[30:33], v[164:167], v[212:215], v[30:33]
	v_mfma_f32_16x16x32_bf16 v[26:29], v[172:175], v[212:215], v[26:29]
	v_mfma_f32_16x16x32_bf16 v[14:17], v[164:167], v[220:223], v[14:17]
	v_mfma_f32_16x16x32_bf16 v[10:13], v[172:175], v[220:223], v[10:13]
	v_mfma_f32_16x16x32_bf16 v[62:65], v[168:171], v[200:203], v[62:65]
	v_mfma_f32_16x16x32_bf16 v[58:61], v[176:179], v[200:203], v[58:61]
	v_mfma_f32_16x16x32_bf16 v[46:49], v[168:171], v[208:211], v[46:49]
	v_mfma_f32_16x16x32_bf16 v[42:45], v[176:179], v[208:211], v[42:45]
	v_mfma_f32_16x16x32_bf16 v[30:33], v[168:171], v[216:219], v[30:33]
	v_mfma_f32_16x16x32_bf16 v[26:29], v[176:179], v[216:219], v[26:29]
	v_mfma_f32_16x16x32_bf16 v[14:17], v[168:171], v[224:227], v[14:17]
	v_mfma_f32_16x16x32_bf16 v[10:13], v[176:179], v[224:227], v[10:13]
	v_mfma_f32_16x16x32_bf16 v[54:57], v[180:183], v[196:199], v[54:57]
	v_mfma_f32_16x16x32_bf16 v[50:53], v[188:191], v[196:199], v[50:53]
	v_mfma_f32_16x16x32_bf16 v[38:41], v[180:183], v[204:207], v[38:41]
	v_mfma_f32_16x16x32_bf16 v[34:37], v[188:191], v[204:207], v[34:37]
	v_mfma_f32_16x16x32_bf16 v[22:25], v[180:183], v[212:215], v[22:25]
	v_mfma_f32_16x16x32_bf16 v[18:21], v[188:191], v[212:215], v[18:21]
	v_mfma_f32_16x16x32_bf16 v[6:9], v[180:183], v[220:223], v[6:9]
	v_mfma_f32_16x16x32_bf16 v[2:5], v[188:191], v[220:223], v[2:5]
	v_mfma_f32_16x16x32_bf16 v[54:57], v[184:187], v[200:203], v[54:57]
	v_mfma_f32_16x16x32_bf16 v[50:53], v[192:195], v[200:203], v[50:53]
	v_mfma_f32_16x16x32_bf16 v[38:41], v[184:187], v[208:211], v[38:41]
	v_mfma_f32_16x16x32_bf16 v[34:37], v[192:195], v[208:211], v[34:37]
	v_mfma_f32_16x16x32_bf16 v[22:25], v[184:187], v[216:219], v[22:25]
	v_mfma_f32_16x16x32_bf16 v[18:21], v[192:195], v[216:219], v[18:21]
	v_mfma_f32_16x16x32_bf16 v[6:9], v[184:187], v[224:227], v[6:9]
	v_mfma_f32_16x16x32_bf16 v[2:5], v[192:195], v[224:227], v[2:5]
	s_barrier
	s_add_i32 s59, s59, 2
	s_add_u32 s26, s26, 0x100
	s_addc_u32 s27, s27, 0
	s_add_u32 s57, s57, 0x100
	s_addc_u32 s58, s58, 0
	s_cmp_gt_u32 s59, 61
	s_cbranch_scc0 .LBB0_916
	s_and_b64 vcc, exec, s[14:15]
	s_cbranch_vccz .LBB0_919
	s_barrier

.LBB0_947:
	s_or_b64 exec, exec, s[48:49]
	v_ashrrev_i32_e32 v147, 31, v146
	v_lshlrev_b64 v[6:7], 21, v[146:147]
	v_ashrrev_i32_e32 v145, 31, v144
	v_lshl_add_u64 v[148:149], s[6:7], 0, v[6:7]
	v_lshlrev_b64 v[6:7], 21, v[144:145]
	v_lshl_add_u64 v[150:151], s[54:55], 0, v[6:7]
	v_cndmask_b32_e64 v154, v2, v150, s[44:45]
	v_lshl_add_u64 v[158:159], v[2:3], 0, s[30:31]
	v_mov_b32_e32 v2, 0
	v_cndmask_b32_e64 v1, v5, v149, s[44:45]
	v_cndmask_b32_e64 v152, v4, v148, s[44:45]
	v_cndmask_b32_e64 v145, v3, v151, s[44:45]
	v_lshl_add_u64 v[156:157], v[4:5], 0, s[22:23]
	s_mov_b32 s46, -2
	v_mov_b32_e32 v3, v2
	v_mov_b32_e32 v4, v2
	v_mov_b32_e32 v5, v2
	v_mov_b32_e32 v6, v2
	v_mov_b32_e32 v7, v2
	v_mov_b32_e32 v8, v2
	v_mov_b32_e32 v9, v2
	v_mov_b32_e32 v18, v2
	v_mov_b32_e32 v19, v2
	v_mov_b32_e32 v20, v2
	v_mov_b32_e32 v21, v2
	v_mov_b32_e32 v22, v2
	v_mov_b32_e32 v23, v2
	v_mov_b32_e32 v24, v2
	v_mov_b32_e32 v25, v2
	v_mov_b32_e32 v34, v2
	v_mov_b32_e32 v35, v2
	v_mov_b32_e32 v36, v2
	v_mov_b32_e32 v37, v2
	v_mov_b32_e32 v38, v2
	v_mov_b32_e32 v39, v2
	v_mov_b32_e32 v40, v2
	v_mov_b32_e32 v41, v2
	v_mov_b32_e32 v50, v2
	v_mov_b32_e32 v51, v2
	v_mov_b32_e32 v52, v2
	v_mov_b32_e32 v53, v2
	v_mov_b32_e32 v54, v2
	v_mov_b32_e32 v55, v2
	v_mov_b32_e32 v56, v2
	v_mov_b32_e32 v57, v2
	v_mov_b32_e32 v10, v2
	v_mov_b32_e32 v11, v2
	v_mov_b32_e32 v12, v2
	v_mov_b32_e32 v13, v2
	v_mov_b32_e32 v14, v2
	v_mov_b32_e32 v15, v2
	v_mov_b32_e32 v16, v2
	v_mov_b32_e32 v17, v2
	v_mov_b32_e32 v26, v2
	v_mov_b32_e32 v27, v2
	v_mov_b32_e32 v28, v2
	v_mov_b32_e32 v29, v2
	v_mov_b32_e32 v30, v2
	v_mov_b32_e32 v31, v2
	v_mov_b32_e32 v32, v2
	v_mov_b32_e32 v33, v2
	v_mov_b32_e32 v42, v2
	v_mov_b32_e32 v43, v2
	v_mov_b32_e32 v44, v2
	v_mov_b32_e32 v45, v2
	v_mov_b32_e32 v46, v2
	v_mov_b32_e32 v47, v2
	v_mov_b32_e32 v48, v2
	v_mov_b32_e32 v49, v2
	v_mov_b32_e32 v58, v2
	v_mov_b32_e32 v59, v2
	v_mov_b32_e32 v60, v2
	v_mov_b32_e32 v61, v2
	v_mov_b32_e32 v62, v2
	v_mov_b32_e32 v63, v2
	v_mov_b32_e32 v64, v2
	v_mov_b32_e32 v65, v2
	v_mov_b32_e32 v66, v2
	v_mov_b32_e32 v67, v2
	v_mov_b32_e32 v68, v2
	v_mov_b32_e32 v69, v2
	v_mov_b32_e32 v70, v2
	v_mov_b32_e32 v71, v2
	v_mov_b32_e32 v72, v2
	v_mov_b32_e32 v73, v2
	v_mov_b32_e32 v82, v2
	v_mov_b32_e32 v83, v2
	v_mov_b32_e32 v84, v2
	v_mov_b32_e32 v85, v2
	v_mov_b32_e32 v86, v2
	v_mov_b32_e32 v87, v2
	v_mov_b32_e32 v88, v2
	v_mov_b32_e32 v89, v2
	v_mov_b32_e32 v98, v2
	v_mov_b32_e32 v99, v2
	v_mov_b32_e32 v100, v2
	v_mov_b32_e32 v101, v2
	v_mov_b32_e32 v102, v2
	v_mov_b32_e32 v103, v2
	v_mov_b32_e32 v104, v2
	v_mov_b32_e32 v105, v2
	v_mov_b32_e32 v114, v2
	v_mov_b32_e32 v115, v2
	v_mov_b32_e32 v116, v2
	v_mov_b32_e32 v117, v2
	v_mov_b32_e32 v118, v2
	v_mov_b32_e32 v119, v2
	v_mov_b32_e32 v120, v2
	v_mov_b32_e32 v121, v2
	v_mov_b32_e32 v74, v2
	v_mov_b32_e32 v75, v2
	v_mov_b32_e32 v76, v2
	v_mov_b32_e32 v77, v2
	v_mov_b32_e32 v78, v2
	v_mov_b32_e32 v79, v2
	v_mov_b32_e32 v80, v2
	v_mov_b32_e32 v81, v2
	v_mov_b32_e32 v90, v2
	v_mov_b32_e32 v91, v2
	v_mov_b32_e32 v92, v2
	v_mov_b32_e32 v93, v2
	v_mov_b32_e32 v94, v2
	v_mov_b32_e32 v95, v2
	v_mov_b32_e32 v96, v2
	v_mov_b32_e32 v97, v2
	v_mov_b32_e32 v106, v2
	v_mov_b32_e32 v107, v2
	v_mov_b32_e32 v108, v2
	v_mov_b32_e32 v109, v2
	v_mov_b32_e32 v110, v2
	v_mov_b32_e32 v111, v2
	v_mov_b32_e32 v112, v2
	v_mov_b32_e32 v113, v2
	v_mov_b32_e32 v122, v2
	v_mov_b32_e32 v123, v2
	v_mov_b32_e32 v124, v2
	v_mov_b32_e32 v125, v2
	v_mov_b32_e32 v126, v2
	v_mov_b32_e32 v127, v2
	v_mov_b32_e32 v128, v2
	v_mov_b32_e32 v129, v2
	s_setprio 0
.LBB0_948:
	v_add_u32_e32 v147, s63, v161
	ds_read_b128 v[168:171], v147
	ds_read_b128 v[172:175], v147 offset:1024
	ds_read_b128 v[176:179], v147 offset:2048
	ds_read_b128 v[180:183], v147 offset:3072
	v_add_u32_e32 v147, s64, v161
	ds_read_b128 v[184:187], v147
	ds_read_b128 v[188:191], v147 offset:1024
	ds_read_b128 v[192:195], v147 offset:2048
	ds_read_b128 v[196:199], v147 offset:3072
	s_cmp_eq_u32 s46, 60
	v_lshl_add_u64 v[200:201], v[156:157], 0, s[34:35]
	s_cselect_b64 vcc, -1, 0
	v_cndmask_b32_e32 v233, v201, v1, vcc
	v_cndmask_b32_e32 v232, v200, v152, vcc
	v_cndmask_b32_e32 v235, v159, v145, vcc
	v_cndmask_b32_e32 v234, v158, v154, vcc
	v_lshl_add_u64 v[236:237], v[156:157], 0, v[138:139]
	s_add_i32 m0, s56, 0xc000
	ds_read_b128 v[200:203], v164
	ds_read_b128 v[204:207], v164 offset:1024
	ds_read_b128 v[208:211], v164 offset:2048
	ds_read_b128 v[212:215], v164 offset:3072
	ds_read_b128 v[216:219], v164 offset:4096
	ds_read_b128 v[220:223], v164 offset:5120
	ds_read_b128 v[224:227], v164 offset:6144
	ds_read_b128 v[228:231], v164 offset:7168
	global_load_lds_dwordx4 v[236:237], off
	v_lshl_add_u64 v[236:237], v[156:157], 0, v[140:141]
	s_add_i32 m0, s56, 0xe000
	s_nop 0
	global_load_lds_dwordx4 v[236:237], off
	s_waitcnt vmcnt(8)
	s_waitcnt lgkmcnt(0)
	s_barrier
	s_waitcnt lgkmcnt(0)
	v_mfma_f32_16x16x32_bf16 v[126:129], v[168:171], v[200:203], v[126:129]
	v_mfma_f32_16x16x32_bf16 v[122:125], v[176:179], v[200:203], v[122:125]
	v_mfma_f32_16x16x32_bf16 v[110:113], v[168:171], v[208:211], v[110:113]
	v_mfma_f32_16x16x32_bf16 v[106:109], v[176:179], v[208:211], v[106:109]
	v_mfma_f32_16x16x32_bf16 v[94:97], v[168:171], v[216:219], v[94:97]
	v_mfma_f32_16x16x32_bf16 v[90:93], v[176:179], v[216:219], v[90:93]
	v_mfma_f32_16x16x32_bf16 v[78:81], v[168:171], v[224:227], v[78:81]
	v_mfma_f32_16x16x32_bf16 v[74:77], v[176:179], v[224:227], v[74:77]
	v_mfma_f32_16x16x32_bf16 v[126:129], v[172:175], v[204:207], v[126:129]
	v_mfma_f32_16x16x32_bf16 v[122:125], v[180:183], v[204:207], v[122:125]
	v_mfma_f32_16x16x32_bf16 v[110:113], v[172:175], v[212:215], v[110:113]
	v_mfma_f32_16x16x32_bf16 v[106:109], v[180:183], v[212:215], v[106:109]
	v_mfma_f32_16x16x32_bf16 v[94:97], v[172:175], v[220:223], v[94:97]
	v_mfma_f32_16x16x32_bf16 v[90:93], v[180:183], v[220:223], v[90:93]
	v_mfma_f32_16x16x32_bf16 v[78:81], v[172:175], v[228:231], v[78:81]
	v_mfma_f32_16x16x32_bf16 v[74:77], v[180:183], v[228:231], v[74:77]
	v_mfma_f32_16x16x32_bf16 v[118:121], v[184:187], v[200:203], v[118:121]
	v_mfma_f32_16x16x32_bf16 v[114:117], v[192:195], v[200:203], v[114:117]
	v_mfma_f32_16x16x32_bf16 v[102:105], v[184:187], v[208:211], v[102:105]
	v_mfma_f32_16x16x32_bf16 v[98:101], v[192:195], v[208:211], v[98:101]
	v_mfma_f32_16x16x32_bf16 v[86:89], v[184:187], v[216:219], v[86:89]
	v_mfma_f32_16x16x32_bf16 v[82:85], v[192:195], v[216:219], v[82:85]
	v_mfma_f32_16x16x32_bf16 v[70:73], v[184:187], v[224:227], v[70:73]
	v_mfma_f32_16x16x32_bf16 v[66:69], v[192:195], v[224:227], v[66:69]
	v_mfma_f32_16x16x32_bf16 v[118:121], v[188:191], v[204:207], v[118:121]
	v_mfma_f32_16x16x32_bf16 v[114:117], v[196:199], v[204:207], v[114:117]
	v_mfma_f32_16x16x32_bf16 v[102:105], v[188:191], v[212:215], v[102:105]
	v_mfma_f32_16x16x32_bf16 v[98:101], v[196:199], v[212:215], v[98:101]
	v_mfma_f32_16x16x32_bf16 v[86:89], v[188:191], v[220:223], v[86:89]
	v_mfma_f32_16x16x32_bf16 v[82:85], v[196:199], v[220:223], v[82:85]
	v_mfma_f32_16x16x32_bf16 v[70:73], v[188:191], v[228:231], v[70:73]
	v_mfma_f32_16x16x32_bf16 v[66:69], v[196:199], v[228:231], v[66:69]
	s_barrier
	s_add_i32 s47, s63, s53
	v_lshl_add_u64 v[236:237], v[234:235], 0, v[132:133]
	s_mov_b32 m0, s47
	ds_read_b128 v[200:203], v164 offset:16384
	ds_read_b128 v[204:207], v164 offset:17408
	ds_read_b128 v[208:211], v164 offset:18432
	ds_read_b128 v[212:215], v164 offset:19456
	ds_read_b128 v[216:219], v164 offset:20480
	ds_read_b128 v[220:223], v164 offset:21504
	ds_read_b128 v[224:227], v164 offset:22528
	ds_read_b128 v[228:231], v164 offset:23552
	global_load_lds_dwordx4 v[236:237], off
	v_lshl_add_u64 v[238:239], v[234:235], 0, v[136:137]
	s_add_i32 m0, s47, 0x2000
	v_lshl_add_u64 v[240:241], v[234:235], 0, s[10:11]
	s_add_i32 s47, s64, s53
	global_load_lds_dwordx4 v[238:239], off
	v_lshl_add_u64 v[242:243], v[240:241], 0, v[132:133]
	s_mov_b32 m0, s47
	v_lshl_add_u64 v[240:241], v[240:241], 0, v[136:137]
	global_load_lds_dwordx4 v[242:243], off
	s_add_i32 m0, s47, 0x2000
	v_lshl_add_u64 v[242:243], v[232:233], 0, v[134:135]
	global_load_lds_dwordx4 v[240:241], off
	v_lshl_add_u64 v[240:241], v[232:233], 0, v[130:131]
	s_mov_b32 m0, s56
	s_nop 0
	global_load_lds_dwordx4 v[240:241], off
	s_mov_b32 m0, s57
	s_nop 0
	global_load_lds_dwordx4 v[242:243], off
	s_waitcnt vmcnt(8)
	s_waitcnt lgkmcnt(0)
	s_barrier
	s_waitcnt lgkmcnt(0)
	v_mfma_f32_16x16x32_bf16 v[62:65], v[168:171], v[200:203], v[62:65]
	v_mfma_f32_16x16x32_bf16 v[58:61], v[176:179], v[200:203], v[58:61]
	v_mfma_f32_16x16x32_bf16 v[46:49], v[168:171], v[208:211], v[46:49]
	v_mfma_f32_16x16x32_bf16 v[42:45], v[176:179], v[208:211], v[42:45]
	v_mfma_f32_16x16x32_bf16 v[30:33], v[168:171], v[216:219], v[30:33]
	v_mfma_f32_16x16x32_bf16 v[26:29], v[176:179], v[216:219], v[26:29]
	v_mfma_f32_16x16x32_bf16 v[14:17], v[168:171], v[224:227], v[14:17]
	v_mfma_f32_16x16x32_bf16 v[10:13], v[176:179], v[224:227], v[10:13]
	v_mfma_f32_16x16x32_bf16 v[62:65], v[172:175], v[204:207], v[62:65]
	v_mfma_f32_16x16x32_bf16 v[58:61], v[180:183], v[204:207], v[58:61]
	v_mfma_f32_16x16x32_bf16 v[46:49], v[172:175], v[212:215], v[46:49]
	v_mfma_f32_16x16x32_bf16 v[42:45], v[180:183], v[212:215], v[42:45]
	v_mfma_f32_16x16x32_bf16 v[30:33], v[172:175], v[220:223], v[30:33]
	v_mfma_f32_16x16x32_bf16 v[26:29], v[180:183], v[220:223], v[26:29]
	v_mfma_f32_16x16x32_bf16 v[14:17], v[172:175], v[228:231], v[14:17]
	v_mfma_f32_16x16x32_bf16 v[10:13], v[180:183], v[228:231], v[10:13]
	v_mfma_f32_16x16x32_bf16 v[54:57], v[184:187], v[200:203], v[54:57]
	v_mfma_f32_16x16x32_bf16 v[50:53], v[192:195], v[200:203], v[50:53]
	v_mfma_f32_16x16x32_bf16 v[38:41], v[184:187], v[208:211], v[38:41]
	v_mfma_f32_16x16x32_bf16 v[34:37], v[192:195], v[208:211], v[34:37]
	v_mfma_f32_16x16x32_bf16 v[22:25], v[184:187], v[216:219], v[22:25]
	v_mfma_f32_16x16x32_bf16 v[18:21], v[192:195], v[216:219], v[18:21]
	v_mfma_f32_16x16x32_bf16 v[6:9], v[184:187], v[224:227], v[6:9]
	v_mfma_f32_16x16x32_bf16 v[2:5], v[192:195], v[224:227], v[2:5]
	v_mfma_f32_16x16x32_bf16 v[54:57], v[188:191], v[204:207], v[54:57]
	v_mfma_f32_16x16x32_bf16 v[50:53], v[196:199], v[204:207], v[50:53]
	v_mfma_f32_16x16x32_bf16 v[38:41], v[188:191], v[212:215], v[38:41]
	v_mfma_f32_16x16x32_bf16 v[34:37], v[196:199], v[212:215], v[34:37]
	v_mfma_f32_16x16x32_bf16 v[22:25], v[188:191], v[220:223], v[22:25]
	v_mfma_f32_16x16x32_bf16 v[18:21], v[196:199], v[220:223], v[18:21]
	v_mfma_f32_16x16x32_bf16 v[6:9], v[188:191], v[228:231], v[6:9]
	v_mfma_f32_16x16x32_bf16 v[2:5], v[196:199], v[228:231], v[2:5]
	s_barrier
	s_add_i32 s47, 0, 0x18000
	v_add_u32_e32 v147, s47, v161
	s_add_i32 s48, 0, 0x1c000
	ds_read_b128 v[168:171], v147
	ds_read_b128 v[172:175], v147 offset:1024
	ds_read_b128 v[176:179], v147 offset:2048
	ds_read_b128 v[180:183], v147 offset:3072
	v_add_u32_e32 v147, s48, v161
	ds_read_b128 v[184:187], v147
	ds_read_b128 v[188:191], v147 offset:1024
	ds_read_b128 v[192:195], v147 offset:2048
	ds_read_b128 v[196:199], v147 offset:3072
	v_lshl_add_u64 v[232:233], v[232:233], 0, s[10:11]
	s_mov_b32 m0, s58
	v_lshl_add_u64 v[244:245], v[232:233], 0, v[130:131]
	ds_read_b128 v[200:203], v164 offset:32768
	ds_read_b128 v[204:207], v164 offset:33792
	ds_read_b128 v[208:211], v164 offset:34816
	ds_read_b128 v[212:215], v164 offset:35840
	ds_read_b128 v[216:219], v164 offset:36864
	ds_read_b128 v[220:223], v164 offset:37888
	ds_read_b128 v[224:227], v164 offset:38912
	ds_read_b128 v[228:231], v164 offset:39936
	global_load_lds_dwordx4 v[244:245], off
	v_lshl_add_u64 v[232:233], v[232:233], 0, v[134:135]
	s_mov_b32 m0, s59
	s_nop 0
	global_load_lds_dwordx4 v[232:233], off
	s_waitcnt vmcnt(8)
	s_waitcnt lgkmcnt(0)
	s_barrier
	s_waitcnt lgkmcnt(0)
	v_mfma_f32_16x16x32_bf16 v[126:129], v[168:171], v[200:203], v[126:129]
	v_mfma_f32_16x16x32_bf16 v[122:125], v[176:179], v[200:203], v[122:125]
	v_mfma_f32_16x16x32_bf16 v[110:113], v[168:171], v[208:211], v[110:113]
	v_mfma_f32_16x16x32_bf16 v[106:109], v[176:179], v[208:211], v[106:109]
	v_mfma_f32_16x16x32_bf16 v[94:97], v[168:171], v[216:219], v[94:97]
	v_mfma_f32_16x16x32_bf16 v[90:93], v[176:179], v[216:219], v[90:93]
	v_mfma_f32_16x16x32_bf16 v[78:81], v[168:171], v[224:227], v[78:81]
	v_mfma_f32_16x16x32_bf16 v[74:77], v[176:179], v[224:227], v[74:77]
	v_mfma_f32_16x16x32_bf16 v[126:129], v[172:175], v[204:207], v[126:129]
	v_mfma_f32_16x16x32_bf16 v[122:125], v[180:183], v[204:207], v[122:125]
	v_mfma_f32_16x16x32_bf16 v[110:113], v[172:175], v[212:215], v[110:113]
	v_mfma_f32_16x16x32_bf16 v[106:109], v[180:183], v[212:215], v[106:109]
	v_mfma_f32_16x16x32_bf16 v[94:97], v[172:175], v[220:223], v[94:97]
	v_mfma_f32_16x16x32_bf16 v[90:93], v[180:183], v[220:223], v[90:93]
	v_mfma_f32_16x16x32_bf16 v[78:81], v[172:175], v[228:231], v[78:81]
	v_mfma_f32_16x16x32_bf16 v[74:77], v[180:183], v[228:231], v[74:77]
	v_mfma_f32_16x16x32_bf16 v[118:121], v[184:187], v[200:203], v[118:121]
	v_mfma_f32_16x16x32_bf16 v[114:117], v[192:195], v[200:203], v[114:117]
	v_mfma_f32_16x16x32_bf16 v[102:105], v[184:187], v[208:211], v[102:105]
	v_mfma_f32_16x16x32_bf16 v[98:101], v[192:195], v[208:211], v[98:101]
	v_mfma_f32_16x16x32_bf16 v[86:89], v[184:187], v[216:219], v[86:89]
	v_mfma_f32_16x16x32_bf16 v[82:85], v[192:195], v[216:219], v[82:85]
	v_mfma_f32_16x16x32_bf16 v[70:73], v[184:187], v[224:227], v[70:73]
	v_mfma_f32_16x16x32_bf16 v[66:69], v[192:195], v[224:227], v[66:69]
	v_mfma_f32_16x16x32_bf16 v[118:121], v[188:191], v[204:207], v[118:121]
	v_mfma_f32_16x16x32_bf16 v[114:117], v[196:199], v[204:207], v[114:117]
	v_mfma_f32_16x16x32_bf16 v[102:105], v[188:191], v[212:215], v[102:105]
	v_mfma_f32_16x16x32_bf16 v[98:101], v[196:199], v[212:215], v[98:101]
	v_mfma_f32_16x16x32_bf16 v[86:89], v[188:191], v[220:223], v[86:89]
	v_mfma_f32_16x16x32_bf16 v[82:85], v[196:199], v[220:223], v[82:85]
	v_mfma_f32_16x16x32_bf16 v[70:73], v[188:191], v[228:231], v[70:73]
	v_mfma_f32_16x16x32_bf16 v[66:69], v[196:199], v[228:231], v[66:69]
	s_barrier
	s_add_i32 s47, s47, s53
	v_lshl_add_u64 v[232:233], v[236:237], 0, s[18:19]
	s_mov_b32 m0, s47
	ds_read_b128 v[200:203], v164 offset:49152
	ds_read_b128 v[204:207], v164 offset:50176
	ds_read_b128 v[208:211], v164 offset:51200
	ds_read_b128 v[212:215], v164 offset:52224
	ds_read_b128 v[216:219], v164 offset:53248
	ds_read_b128 v[220:223], v164 offset:54272
	ds_read_b128 v[224:227], v164 offset:55296
	ds_read_b128 v[228:231], v164 offset:56320
	global_load_lds_dwordx4 v[232:233], off
	v_lshl_add_u64 v[232:233], v[238:239], 0, s[18:19]
	s_add_i32 m0, s47, 0x2000
	s_add_i32 s47, s48, s53
	global_load_lds_dwordx4 v[232:233], off
	v_lshl_add_u64 v[232:233], v[234:235], 0, s[22:23]
	v_lshl_add_u64 v[234:235], v[232:233], 0, v[132:133]
	s_mov_b32 m0, s47
	v_lshl_add_u64 v[232:233], v[232:233], 0, v[136:137]
	global_load_lds_dwordx4 v[234:235], off
	s_add_i32 m0, s47, 0x2000
	s_nop 0
	global_load_lds_dwordx4 v[232:233], off
	v_lshl_add_u64 v[232:233], v[240:241], 0, s[18:19]
	s_mov_b32 m0, s61
	s_nop 0
	global_load_lds_dwordx4 v[232:233], off
	v_lshl_add_u64 v[232:233], v[242:243], 0, s[18:19]
	s_mov_b32 m0, s62
	s_nop 0
	global_load_lds_dwordx4 v[232:233], off
	s_waitcnt vmcnt(8)
	s_waitcnt lgkmcnt(0)
	s_barrier
	s_waitcnt lgkmcnt(0)
	v_mfma_f32_16x16x32_bf16 v[62:65], v[168:171], v[200:203], v[62:65]
	v_mfma_f32_16x16x32_bf16 v[58:61], v[176:179], v[200:203], v[58:61]
	v_mfma_f32_16x16x32_bf16 v[46:49], v[168:171], v[208:211], v[46:49]
	v_mfma_f32_16x16x32_bf16 v[42:45], v[176:179], v[208:211], v[42:45]
	v_mfma_f32_16x16x32_bf16 v[30:33], v[168:171], v[216:219], v[30:33]
	v_mfma_f32_16x16x32_bf16 v[26:29], v[176:179], v[216:219], v[26:29]
	v_mfma_f32_16x16x32_bf16 v[14:17], v[168:171], v[224:227], v[14:17]
	v_mfma_f32_16x16x32_bf16 v[10:13], v[176:179], v[224:227], v[10:13]
	v_mfma_f32_16x16x32_bf16 v[62:65], v[172:175], v[204:207], v[62:65]
	v_mfma_f32_16x16x32_bf16 v[58:61], v[180:183], v[204:207], v[58:61]
	v_mfma_f32_16x16x32_bf16 v[46:49], v[172:175], v[212:215], v[46:49]
	v_mfma_f32_16x16x32_bf16 v[42:45], v[180:183], v[212:215], v[42:45]
	v_mfma_f32_16x16x32_bf16 v[30:33], v[172:175], v[220:223], v[30:33]
	v_mfma_f32_16x16x32_bf16 v[26:29], v[180:183], v[220:223], v[26:29]
	v_mfma_f32_16x16x32_bf16 v[14:17], v[172:175], v[228:231], v[14:17]
	v_mfma_f32_16x16x32_bf16 v[10:13], v[180:183], v[228:231], v[10:13]
	v_mfma_f32_16x16x32_bf16 v[54:57], v[184:187], v[200:203], v[54:57]
	v_mfma_f32_16x16x32_bf16 v[50:53], v[192:195], v[200:203], v[50:53]
	v_mfma_f32_16x16x32_bf16 v[38:41], v[184:187], v[208:211], v[38:41]
	v_mfma_f32_16x16x32_bf16 v[34:37], v[192:195], v[208:211], v[34:37]
	v_mfma_f32_16x16x32_bf16 v[22:25], v[184:187], v[216:219], v[22:25]
	v_mfma_f32_16x16x32_bf16 v[18:21], v[192:195], v[216:219], v[18:21]
	v_mfma_f32_16x16x32_bf16 v[6:9], v[184:187], v[224:227], v[6:9]
	v_mfma_f32_16x16x32_bf16 v[2:5], v[192:195], v[224:227], v[2:5]
	v_mfma_f32_16x16x32_bf16 v[54:57], v[188:191], v[204:207], v[54:57]
	v_mfma_f32_16x16x32_bf16 v[50:53], v[196:199], v[204:207], v[50:53]
	v_mfma_f32_16x16x32_bf16 v[38:41], v[188:191], v[212:215], v[38:41]
	v_mfma_f32_16x16x32_bf16 v[34:37], v[196:199], v[212:215], v[34:37]
	v_mfma_f32_16x16x32_bf16 v[22:25], v[188:191], v[220:223], v[22:25]
	v_mfma_f32_16x16x32_bf16 v[18:21], v[196:199], v[220:223], v[18:21]
	v_mfma_f32_16x16x32_bf16 v[6:9], v[188:191], v[228:231], v[6:9]
	v_mfma_f32_16x16x32_bf16 v[2:5], v[196:199], v[228:231], v[2:5]
	s_barrier
	s_add_i32 s46, s46, 2
	v_lshl_add_u64 v[156:157], v[156:157], 0, s[30:31]
	s_cmp_gt_u32 s46, 61
	v_lshl_add_u64 v[158:159], v[158:159], 0, s[30:31]
	s_cbranch_scc0 .LBB0_948
	s_and_b64 vcc, exec, s[24:25]
	s_cbranch_vccz .LBB0_951
	s_barrier

.LBB0_1097:
	s_ashr_i32 s19, s18, 31
	s_lshl_b64 s[20:21], s[18:19], 22
	s_add_u32 s20, s34, s20
	s_addc_u32 s21, s35, s21
	s_and_b64 s[22:23], s[0:1], exec
	s_cselect_b32 s19, s21, s27
	s_cselect_b32 s51, s20, s26
	s_ashr_i32 s17, s16, 31
	s_lshl_b64 s[22:23], s[16:17], 22
	s_add_u32 s22, s36, s22
	s_addc_u32 s23, s37, s23
	s_and_b64 s[30:31], s[0:1], exec
	s_cselect_b32 s17, s23, s29
	s_cselect_b32 s52, s22, s28
	s_add_u32 s26, s26, 0x200080
	s_addc_u32 s27, s27, 0
	s_add_u32 s53, s28, 0x100
	v_mov_b32_e32 v0, 0
	s_addc_u32 s54, s29, 0
	s_mov_b32 s55, -2
	v_mov_b32_e32 v1, v0
	v_mov_b32_e32 v2, v0
	v_mov_b32_e32 v3, v0
	v_mov_b32_e32 v4, v0
	v_mov_b32_e32 v5, v0
	v_mov_b32_e32 v6, v0
	v_mov_b32_e32 v7, v0
	v_mov_b32_e32 v12, v0
	v_mov_b32_e32 v13, v0
	v_mov_b32_e32 v14, v0
	v_mov_b32_e32 v15, v0
	v_mov_b32_e32 v20, v0
	v_mov_b32_e32 v21, v0
	v_mov_b32_e32 v22, v0
	v_mov_b32_e32 v23, v0
	v_mov_b32_e32 v32, v0
	v_mov_b32_e32 v33, v0
	v_mov_b32_e32 v34, v0
	v_mov_b32_e32 v35, v0
	v_mov_b32_e32 v36, v0
	v_mov_b32_e32 v37, v0
	v_mov_b32_e32 v38, v0
	v_mov_b32_e32 v39, v0
	v_mov_b32_e32 v48, v0
	v_mov_b32_e32 v49, v0
	v_mov_b32_e32 v50, v0
	v_mov_b32_e32 v51, v0
	v_mov_b32_e32 v52, v0
	v_mov_b32_e32 v53, v0
	v_mov_b32_e32 v54, v0
	v_mov_b32_e32 v55, v0
	v_mov_b32_e32 v8, v0
	v_mov_b32_e32 v9, v0
	v_mov_b32_e32 v10, v0
	v_mov_b32_e32 v11, v0
	v_mov_b32_e32 v16, v0
	v_mov_b32_e32 v17, v0
	v_mov_b32_e32 v18, v0
	v_mov_b32_e32 v19, v0
	v_mov_b32_e32 v24, v0
	v_mov_b32_e32 v25, v0
	v_mov_b32_e32 v26, v0
	v_mov_b32_e32 v27, v0
	v_mov_b32_e32 v28, v0
	v_mov_b32_e32 v29, v0
	v_mov_b32_e32 v30, v0
	v_mov_b32_e32 v31, v0
	v_mov_b32_e32 v40, v0
	v_mov_b32_e32 v41, v0
	v_mov_b32_e32 v42, v0
	v_mov_b32_e32 v43, v0
	v_mov_b32_e32 v44, v0
	v_mov_b32_e32 v45, v0
	v_mov_b32_e32 v46, v0
	v_mov_b32_e32 v47, v0
	v_mov_b32_e32 v56, v0
	v_mov_b32_e32 v57, v0
	v_mov_b32_e32 v58, v0
	v_mov_b32_e32 v59, v0
	v_mov_b32_e32 v60, v0
	v_mov_b32_e32 v61, v0
	v_mov_b32_e32 v62, v0
	v_mov_b32_e32 v63, v0
	v_mov_b32_e32 v64, v0
	v_mov_b32_e32 v65, v0
	v_mov_b32_e32 v66, v0
	v_mov_b32_e32 v67, v0
	v_mov_b32_e32 v68, v0
	v_mov_b32_e32 v69, v0
	v_mov_b32_e32 v70, v0
	v_mov_b32_e32 v71, v0
	v_mov_b32_e32 v80, v0
	v_mov_b32_e32 v81, v0
	v_mov_b32_e32 v82, v0
	v_mov_b32_e32 v83, v0
	v_mov_b32_e32 v84, v0
	v_mov_b32_e32 v85, v0
	v_mov_b32_e32 v86, v0
	v_mov_b32_e32 v87, v0
	v_mov_b32_e32 v96, v0
	v_mov_b32_e32 v97, v0
	v_mov_b32_e32 v98, v0
	v_mov_b32_e32 v99, v0
	v_mov_b32_e32 v100, v0
	v_mov_b32_e32 v101, v0
	v_mov_b32_e32 v102, v0
	v_mov_b32_e32 v103, v0
	v_mov_b32_e32 v112, v0
	v_mov_b32_e32 v113, v0
	v_mov_b32_e32 v114, v0
	v_mov_b32_e32 v115, v0
	v_mov_b32_e32 v116, v0
	v_mov_b32_e32 v117, v0
	v_mov_b32_e32 v118, v0
	v_mov_b32_e32 v119, v0
	v_mov_b32_e32 v72, v0
	v_mov_b32_e32 v73, v0
	v_mov_b32_e32 v74, v0
	v_mov_b32_e32 v75, v0
	v_mov_b32_e32 v76, v0
	v_mov_b32_e32 v77, v0
	v_mov_b32_e32 v78, v0
	v_mov_b32_e32 v79, v0
	v_mov_b32_e32 v88, v0
	v_mov_b32_e32 v89, v0
	v_mov_b32_e32 v90, v0
	v_mov_b32_e32 v91, v0
	v_mov_b32_e32 v92, v0
	v_mov_b32_e32 v93, v0
	v_mov_b32_e32 v94, v0
	v_mov_b32_e32 v95, v0
	v_mov_b32_e32 v104, v0
	v_mov_b32_e32 v105, v0
	v_mov_b32_e32 v106, v0
	v_mov_b32_e32 v107, v0
	v_mov_b32_e32 v108, v0
	v_mov_b32_e32 v109, v0
	v_mov_b32_e32 v110, v0
	v_mov_b32_e32 v111, v0
	v_mov_b32_e32 v120, v0
	v_mov_b32_e32 v121, v0
	v_mov_b32_e32 v122, v0
	v_mov_b32_e32 v123, v0
	v_mov_b32_e32 v124, v0
	v_mov_b32_e32 v125, v0
	v_mov_b32_e32 v126, v0
	v_mov_b32_e32 v127, v0
	s_setprio 0
.LBB0_1098:
	ds_read_b128 v[140:143], v165
	ds_read_b128 v[144:147], v165 offset:1024
	ds_read_b128 v[148:151], v165 offset:2048
	ds_read_b128 v[152:155], v165 offset:3072
	ds_read_b128 v[156:159], v166
	ds_read_b128 v[168:171], v166 offset:1024
	ds_read_b128 v[172:175], v166 offset:2048
	ds_read_b128 v[176:179], v166 offset:3072
	s_add_u32 s28, s26, 0xffe00080
	s_addc_u32 s29, s27, -1
	s_cmpk_eq_i32 s55, 0x7c
	s_cselect_b32 s31, s19, s29
	s_cselect_b32 s30, s51, s28
	s_cselect_b32 s29, s17, s54
	s_cselect_b32 s28, s52, s53
	v_lshl_add_u64 v[160:161], s[26:27], 0, v[132:133]
	s_add_i32 m0, s25, 0xc000
	ds_read_b128 v[180:183], v167
	ds_read_b128 v[184:187], v167 offset:1024
	ds_read_b128 v[188:191], v167 offset:2048
	ds_read_b128 v[192:195], v167 offset:3072
	ds_read_b128 v[196:199], v167 offset:4096
	ds_read_b128 v[200:203], v167 offset:5120
	ds_read_b128 v[204:207], v167 offset:6144
	ds_read_b128 v[208:211], v167 offset:7168
	global_load_lds_dwordx4 v[160:161], off
	v_lshl_add_u64 v[160:161], s[26:27], 0, v[134:135]
	s_add_i32 m0, s25, 0xe000
	s_nop 0
	global_load_lds_dwordx4 v[160:161], off
	s_waitcnt vmcnt(8)
	s_waitcnt lgkmcnt(0)
	s_barrier
	s_waitcnt lgkmcnt(0)
	v_mfma_f32_16x16x32_bf16 v[124:127], v[140:143], v[180:183], v[124:127]
	v_mfma_f32_16x16x32_bf16 v[120:123], v[148:151], v[180:183], v[120:123]
	v_mfma_f32_16x16x32_bf16 v[108:111], v[140:143], v[188:191], v[108:111]
	v_mfma_f32_16x16x32_bf16 v[104:107], v[148:151], v[188:191], v[104:107]
	v_mfma_f32_16x16x32_bf16 v[92:95], v[140:143], v[196:199], v[92:95]
	v_mfma_f32_16x16x32_bf16 v[88:91], v[148:151], v[196:199], v[88:91]
	v_mfma_f32_16x16x32_bf16 v[76:79], v[140:143], v[204:207], v[76:79]
	v_mfma_f32_16x16x32_bf16 v[72:75], v[148:151], v[204:207], v[72:75]
	v_mfma_f32_16x16x32_bf16 v[124:127], v[144:147], v[184:187], v[124:127]
	v_mfma_f32_16x16x32_bf16 v[120:123], v[152:155], v[184:187], v[120:123]
	v_mfma_f32_16x16x32_bf16 v[108:111], v[144:147], v[192:195], v[108:111]
	v_mfma_f32_16x16x32_bf16 v[104:107], v[152:155], v[192:195], v[104:107]
	v_mfma_f32_16x16x32_bf16 v[92:95], v[144:147], v[200:203], v[92:95]
	v_mfma_f32_16x16x32_bf16 v[88:91], v[152:155], v[200:203], v[88:91]
	v_mfma_f32_16x16x32_bf16 v[76:79], v[144:147], v[208:211], v[76:79]
	v_mfma_f32_16x16x32_bf16 v[72:75], v[152:155], v[208:211], v[72:75]
	v_mfma_f32_16x16x32_bf16 v[116:119], v[156:159], v[180:183], v[116:119]
	v_mfma_f32_16x16x32_bf16 v[112:115], v[172:175], v[180:183], v[112:115]
	v_mfma_f32_16x16x32_bf16 v[100:103], v[156:159], v[188:191], v[100:103]
	v_mfma_f32_16x16x32_bf16 v[96:99], v[172:175], v[188:191], v[96:99]
	v_mfma_f32_16x16x32_bf16 v[84:87], v[156:159], v[196:199], v[84:87]
	v_mfma_f32_16x16x32_bf16 v[80:83], v[172:175], v[196:199], v[80:83]
	v_mfma_f32_16x16x32_bf16 v[68:71], v[156:159], v[204:207], v[68:71]
	v_mfma_f32_16x16x32_bf16 v[64:67], v[172:175], v[204:207], v[64:67]
	v_mfma_f32_16x16x32_bf16 v[116:119], v[168:171], v[184:187], v[116:119]
	v_mfma_f32_16x16x32_bf16 v[112:115], v[176:179], v[184:187], v[112:115]
	v_mfma_f32_16x16x32_bf16 v[100:103], v[168:171], v[192:195], v[100:103]
	v_mfma_f32_16x16x32_bf16 v[96:99], v[176:179], v[192:195], v[96:99]
	v_mfma_f32_16x16x32_bf16 v[84:87], v[168:171], v[200:203], v[84:87]
	v_mfma_f32_16x16x32_bf16 v[80:83], v[176:179], v[200:203], v[80:83]
	v_mfma_f32_16x16x32_bf16 v[68:71], v[168:171], v[208:211], v[68:71]
	v_mfma_f32_16x16x32_bf16 v[64:67], v[176:179], v[208:211], v[64:67]
	s_barrier
	s_add_i32 s56, s48, s38
	v_lshl_add_u64 v[160:161], s[28:29], 0, v[128:129]
	s_mov_b32 m0, s56
	ds_read_b128 v[180:183], v167 offset:16384
	ds_read_b128 v[184:187], v167 offset:17408
	ds_read_b128 v[188:191], v167 offset:18432
	ds_read_b128 v[192:195], v167 offset:19456
	ds_read_b128 v[196:199], v167 offset:20480
	ds_read_b128 v[200:203], v167 offset:21504
	ds_read_b128 v[204:207], v167 offset:22528
	ds_read_b128 v[208:211], v167 offset:23552
	global_load_lds_dwordx4 v[160:161], off
	s_add_i32 m0, s56, 0x2000
	s_add_u32 s56, s28, 0x200000
	v_lshl_add_u64 v[212:213], s[28:29], 0, v[130:131]
	s_addc_u32 s57, s29, 0
	s_add_i32 s58, s49, s38
	global_load_lds_dwordx4 v[212:213], off
	v_lshl_add_u64 v[214:215], s[56:57], 0, v[128:129]
	s_mov_b32 m0, s58
	v_lshl_add_u64 v[216:217], s[30:31], 0, v[130:131]
	global_load_lds_dwordx4 v[214:215], off
	v_lshl_add_u64 v[214:215], s[56:57], 0, v[130:131]
	s_add_i32 m0, s58, 0x2000
	s_nop 0
	global_load_lds_dwordx4 v[214:215], off
	v_lshl_add_u64 v[214:215], s[30:31], 0, v[128:129]
	s_mov_b32 m0, s25
	s_nop 0
	global_load_lds_dwordx4 v[214:215], off
	s_mov_b32 m0, s40
	s_nop 0
	global_load_lds_dwordx4 v[216:217], off
	s_waitcnt vmcnt(8)
	s_waitcnt lgkmcnt(0)
	s_barrier
	s_waitcnt lgkmcnt(0)
	v_mfma_f32_16x16x32_bf16 v[60:63], v[140:143], v[180:183], v[60:63]
	v_mfma_f32_16x16x32_bf16 v[56:59], v[148:151], v[180:183], v[56:59]
	v_mfma_f32_16x16x32_bf16 v[44:47], v[140:143], v[188:191], v[44:47]
	v_mfma_f32_16x16x32_bf16 v[40:43], v[148:151], v[188:191], v[40:43]
	v_mfma_f32_16x16x32_bf16 v[28:31], v[140:143], v[196:199], v[28:31]
	v_mfma_f32_16x16x32_bf16 v[24:27], v[148:151], v[196:199], v[24:27]
	v_mfma_f32_16x16x32_bf16 v[16:19], v[140:143], v[204:207], v[16:19]
	v_mfma_f32_16x16x32_bf16 v[8:11], v[148:151], v[204:207], v[8:11]
	v_mfma_f32_16x16x32_bf16 v[60:63], v[144:147], v[184:187], v[60:63]
	v_mfma_f32_16x16x32_bf16 v[56:59], v[152:155], v[184:187], v[56:59]
	v_mfma_f32_16x16x32_bf16 v[44:47], v[144:147], v[192:195], v[44:47]
	v_mfma_f32_16x16x32_bf16 v[40:43], v[152:155], v[192:195], v[40:43]
	v_mfma_f32_16x16x32_bf16 v[28:31], v[144:147], v[200:203], v[28:31]
	v_mfma_f32_16x16x32_bf16 v[24:27], v[152:155], v[200:203], v[24:27]
	v_mfma_f32_16x16x32_bf16 v[16:19], v[144:147], v[208:211], v[16:19]
	v_mfma_f32_16x16x32_bf16 v[8:11], v[152:155], v[208:211], v[8:11]
	v_mfma_f32_16x16x32_bf16 v[52:55], v[156:159], v[180:183], v[52:55]
	v_mfma_f32_16x16x32_bf16 v[48:51], v[172:175], v[180:183], v[48:51]
	v_mfma_f32_16x16x32_bf16 v[36:39], v[156:159], v[188:191], v[36:39]
	v_mfma_f32_16x16x32_bf16 v[32:35], v[172:175], v[188:191], v[32:35]
	v_mfma_f32_16x16x32_bf16 v[20:23], v[156:159], v[196:199], v[20:23]
	v_mfma_f32_16x16x32_bf16 v[12:15], v[172:175], v[196:199], v[12:15]
	v_mfma_f32_16x16x32_bf16 v[4:7], v[156:159], v[204:207], v[4:7]
	v_mfma_f32_16x16x32_bf16 v[0:3], v[172:175], v[204:207], v[0:3]
	v_mfma_f32_16x16x32_bf16 v[52:55], v[168:171], v[184:187], v[52:55]
	v_mfma_f32_16x16x32_bf16 v[48:51], v[176:179], v[184:187], v[48:51]
	v_mfma_f32_16x16x32_bf16 v[36:39], v[168:171], v[192:195], v[36:39]
	v_mfma_f32_16x16x32_bf16 v[32:35], v[176:179], v[192:195], v[32:35]
	v_mfma_f32_16x16x32_bf16 v[20:23], v[168:171], v[200:203], v[20:23]
	v_mfma_f32_16x16x32_bf16 v[12:15], v[176:179], v[200:203], v[12:15]
	v_mfma_f32_16x16x32_bf16 v[4:7], v[168:171], v[208:211], v[4:7]
	v_mfma_f32_16x16x32_bf16 v[0:3], v[176:179], v[208:211], v[0:3]
	s_barrier
	s_add_i32 s56, 0, 0x18000
	s_add_i32 s57, 0, 0x1c000
	v_add_u32_e32 v152, s56, v163
	v_add_u32_e32 v176, s57, v163
	ds_read_b128 v[140:143], v152
	ds_read_b128 v[144:147], v152 offset:1024
	ds_read_b128 v[148:151], v152 offset:2048
	ds_read_b128 v[152:155], v152 offset:3072
	ds_read_b128 v[156:159], v176
	ds_read_b128 v[168:171], v176 offset:1024
	ds_read_b128 v[172:175], v176 offset:2048
	ds_read_b128 v[176:179], v176 offset:3072
	s_add_u32 s30, s30, 0x200000
	s_addc_u32 s31, s31, 0
	s_mov_b32 m0, s41
	v_lshl_add_u64 v[218:219], s[30:31], 0, v[128:129]
	ds_read_b128 v[180:183], v167 offset:32768
	ds_read_b128 v[184:187], v167 offset:33792
	ds_read_b128 v[188:191], v167 offset:34816
	ds_read_b128 v[192:195], v167 offset:35840
	ds_read_b128 v[196:199], v167 offset:36864
	ds_read_b128 v[200:203], v167 offset:37888
	ds_read_b128 v[204:207], v167 offset:38912
	ds_read_b128 v[208:211], v167 offset:39936
	global_load_lds_dwordx4 v[218:219], off
	v_lshl_add_u64 v[218:219], s[30:31], 0, v[130:131]
	s_mov_b32 m0, s42
	s_nop 0
	global_load_lds_dwordx4 v[218:219], off
	s_waitcnt vmcnt(8)
	s_waitcnt lgkmcnt(0)
	s_barrier
	s_waitcnt lgkmcnt(0)
	v_mfma_f32_16x16x32_bf16 v[124:127], v[140:143], v[180:183], v[124:127]
	v_mfma_f32_16x16x32_bf16 v[120:123], v[148:151], v[180:183], v[120:123]
	v_mfma_f32_16x16x32_bf16 v[108:111], v[140:143], v[188:191], v[108:111]
	v_mfma_f32_16x16x32_bf16 v[104:107], v[148:151], v[188:191], v[104:107]
	v_mfma_f32_16x16x32_bf16 v[92:95], v[140:143], v[196:199], v[92:95]
	v_mfma_f32_16x16x32_bf16 v[88:91], v[148:151], v[196:199], v[88:91]
	v_mfma_f32_16x16x32_bf16 v[76:79], v[140:143], v[204:207], v[76:79]
	v_mfma_f32_16x16x32_bf16 v[72:75], v[148:151], v[204:207], v[72:75]
	v_mfma_f32_16x16x32_bf16 v[124:127], v[144:147], v[184:187], v[124:127]
	v_mfma_f32_16x16x32_bf16 v[120:123], v[152:155], v[184:187], v[120:123]
	v_mfma_f32_16x16x32_bf16 v[108:111], v[144:147], v[192:195], v[108:111]
	v_mfma_f32_16x16x32_bf16 v[104:107], v[152:155], v[192:195], v[104:107]
	v_mfma_f32_16x16x32_bf16 v[92:95], v[144:147], v[200:203], v[92:95]
	v_mfma_f32_16x16x32_bf16 v[88:91], v[152:155], v[200:203], v[88:91]
	v_mfma_f32_16x16x32_bf16 v[76:79], v[144:147], v[208:211], v[76:79]
	v_mfma_f32_16x16x32_bf16 v[72:75], v[152:155], v[208:211], v[72:75]
	v_mfma_f32_16x16x32_bf16 v[116:119], v[156:159], v[180:183], v[116:119]
	v_mfma_f32_16x16x32_bf16 v[112:115], v[172:175], v[180:183], v[112:115]
	v_mfma_f32_16x16x32_bf16 v[100:103], v[156:159], v[188:191], v[100:103]
	v_mfma_f32_16x16x32_bf16 v[96:99], v[172:175], v[188:191], v[96:99]
	v_mfma_f32_16x16x32_bf16 v[84:87], v[156:159], v[196:199], v[84:87]
	v_mfma_f32_16x16x32_bf16 v[80:83], v[172:175], v[196:199], v[80:83]
	v_mfma_f32_16x16x32_bf16 v[68:71], v[156:159], v[204:207], v[68:71]
	v_mfma_f32_16x16x32_bf16 v[64:67], v[172:175], v[204:207], v[64:67]
	v_mfma_f32_16x16x32_bf16 v[116:119], v[168:171], v[184:187], v[116:119]
	v_mfma_f32_16x16x32_bf16 v[112:115], v[176:179], v[184:187], v[112:115]
	v_mfma_f32_16x16x32_bf16 v[100:103], v[168:171], v[192:195], v[100:103]
	v_mfma_f32_16x16x32_bf16 v[96:99], v[176:179], v[192:195], v[96:99]
	v_mfma_f32_16x16x32_bf16 v[84:87], v[168:171], v[200:203], v[84:87]
	v_mfma_f32_16x16x32_bf16 v[80:83], v[176:179], v[200:203], v[80:83]
	v_mfma_f32_16x16x32_bf16 v[68:71], v[168:171], v[208:211], v[68:71]
	v_mfma_f32_16x16x32_bf16 v[64:67], v[176:179], v[208:211], v[64:67]
	s_barrier
	s_add_i32 s30, s56, s38
	v_lshl_add_u64 v[160:161], v[160:161], 0, s[10:11]
	s_mov_b32 m0, s30
	ds_read_b128 v[180:183], v167 offset:49152
	ds_read_b128 v[184:187], v167 offset:50176
	ds_read_b128 v[188:191], v167 offset:51200
	ds_read_b128 v[192:195], v167 offset:52224
	ds_read_b128 v[196:199], v167 offset:53248
	ds_read_b128 v[200:203], v167 offset:54272
	ds_read_b128 v[204:207], v167 offset:55296
	ds_read_b128 v[208:211], v167 offset:56320
	global_load_lds_dwordx4 v[160:161], off
	s_add_i32 m0, s30, 0x2000
	s_add_u32 s28, s28, 0x200080
	v_lshl_add_u64 v[160:161], v[212:213], 0, s[10:11]
	s_addc_u32 s29, s29, 0
	s_add_i32 s30, s57, s38
	global_load_lds_dwordx4 v[160:161], off
	v_lshl_add_u64 v[160:161], s[28:29], 0, v[128:129]
	s_mov_b32 m0, s30
	s_nop 0
	global_load_lds_dwordx4 v[160:161], off
	v_lshl_add_u64 v[160:161], s[28:29], 0, v[130:131]
	s_add_i32 m0, s30, 0x2000
	s_nop 0
	global_load_lds_dwordx4 v[160:161], off
	v_lshl_add_u64 v[160:161], v[214:215], 0, s[10:11]
	s_mov_b32 m0, s45
	s_nop 0
	global_load_lds_dwordx4 v[160:161], off
	v_lshl_add_u64 v[160:161], v[216:217], 0, s[10:11]
	s_mov_b32 m0, s46
	s_nop 0
	global_load_lds_dwordx4 v[160:161], off
	s_waitcnt vmcnt(8)
	s_waitcnt lgkmcnt(0)
	s_barrier
	s_waitcnt lgkmcnt(0)
	v_mfma_f32_16x16x32_bf16 v[60:63], v[140:143], v[180:183], v[60:63]
	v_mfma_f32_16x16x32_bf16 v[56:59], v[148:151], v[180:183], v[56:59]
	v_mfma_f32_16x16x32_bf16 v[44:47], v[140:143], v[188:191], v[44:47]
	v_mfma_f32_16x16x32_bf16 v[40:43], v[148:151], v[188:191], v[40:43]
	v_mfma_f32_16x16x32_bf16 v[28:31], v[140:143], v[196:199], v[28:31]
	v_mfma_f32_16x16x32_bf16 v[24:27], v[148:151], v[196:199], v[24:27]
	v_mfma_f32_16x16x32_bf16 v[16:19], v[140:143], v[204:207], v[16:19]
	v_mfma_f32_16x16x32_bf16 v[8:11], v[148:151], v[204:207], v[8:11]
	v_mfma_f32_16x16x32_bf16 v[60:63], v[144:147], v[184:187], v[60:63]
	v_mfma_f32_16x16x32_bf16 v[56:59], v[152:155], v[184:187], v[56:59]
	v_mfma_f32_16x16x32_bf16 v[44:47], v[144:147], v[192:195], v[44:47]
	v_mfma_f32_16x16x32_bf16 v[40:43], v[152:155], v[192:195], v[40:43]
	v_mfma_f32_16x16x32_bf16 v[28:31], v[144:147], v[200:203], v[28:31]
	v_mfma_f32_16x16x32_bf16 v[24:27], v[152:155], v[200:203], v[24:27]
	v_mfma_f32_16x16x32_bf16 v[16:19], v[144:147], v[208:211], v[16:19]
	v_mfma_f32_16x16x32_bf16 v[8:11], v[152:155], v[208:211], v[8:11]
	v_mfma_f32_16x16x32_bf16 v[52:55], v[156:159], v[180:183], v[52:55]
	v_mfma_f32_16x16x32_bf16 v[48:51], v[172:175], v[180:183], v[48:51]
	v_mfma_f32_16x16x32_bf16 v[36:39], v[156:159], v[188:191], v[36:39]
	v_mfma_f32_16x16x32_bf16 v[32:35], v[172:175], v[188:191], v[32:35]
	v_mfma_f32_16x16x32_bf16 v[20:23], v[156:159], v[196:199], v[20:23]
	v_mfma_f32_16x16x32_bf16 v[12:15], v[172:175], v[196:199], v[12:15]
	v_mfma_f32_16x16x32_bf16 v[4:7], v[156:159], v[204:207], v[4:7]
	v_mfma_f32_16x16x32_bf16 v[0:3], v[172:175], v[204:207], v[0:3]
	v_mfma_f32_16x16x32_bf16 v[52:55], v[168:171], v[184:187], v[52:55]
	v_mfma_f32_16x16x32_bf16 v[48:51], v[176:179], v[184:187], v[48:51]
	v_mfma_f32_16x16x32_bf16 v[36:39], v[168:171], v[192:195], v[36:39]
	v_mfma_f32_16x16x32_bf16 v[32:35], v[176:179], v[192:195], v[32:35]
	v_mfma_f32_16x16x32_bf16 v[20:23], v[168:171], v[200:203], v[20:23]
	v_mfma_f32_16x16x32_bf16 v[12:15], v[176:179], v[200:203], v[12:15]
	v_mfma_f32_16x16x32_bf16 v[4:7], v[168:171], v[208:211], v[4:7]
	v_mfma_f32_16x16x32_bf16 v[0:3], v[176:179], v[208:211], v[0:3]
	s_barrier
	s_add_i32 s55, s55, 2
	s_add_u32 s26, s26, 0x100
	s_addc_u32 s27, s27, 0
	s_add_u32 s53, s53, 0x100
	s_addc_u32 s54, s54, 0
	s_cmpk_gt_u32 s55, 0x7d
	s_cbranch_scc0 .LBB0_1098
	s_and_b64 vcc, exec, s[14:15]
	s_cbranch_vccz .LBB0_1101
	s_barrier
